# remaining four pool MFMA chains read W fragments into a spare register ring with counted waits
# baseline (speedup 1.0000x reference)
.LBB0_208:
	s_or_b64 exec, exec, s[44:45]
	v_add_u32_e32 v58, s95, v83
	v_min_i32_e32 v58, 3, v58
	v_add_u32_e32 v58, 1, v58
	v_cvt_f32_i32_e32 v58, v58
	s_waitcnt vmcnt(26)
	v_cndmask_b32_e32 v9, 0, v9, vcc
	s_waitcnt vmcnt(8)
	v_cndmask_b32_e64 v0, 0, v52, s[38:39]
	v_cndmask_b32_e64 v10, 0, v10, s[0:1]
	v_lshlrev_b32_e32 v52, 16, v9
	v_and_b32_e32 v9, 0xffff0000, v9
	v_cndmask_b32_e64 v11, 0, v11, s[2:3]
	v_add_f32_e32 v53, 0, v52
	v_add_f32_e32 v54, 0, v9
	v_lshlrev_b32_e32 v55, 16, v10
	v_and_b32_e32 v10, 0xffff0000, v10
	v_rcp_iflag_f32_e32 v58, v58
	v_cndmask_b32_e64 v12, 0, v12, s[6:7]
	v_add_f32_e32 v53, v53, v55
	v_add_f32_e32 v54, v54, v10
	v_lshlrev_b32_e32 v56, 16, v11
	v_and_b32_e32 v11, 0xffff0000, v11
	v_add_f32_e32 v53, v53, v56
	v_add_f32_e32 v54, v54, v11
	v_lshlrev_b32_e32 v57, 16, v12
	v_and_b32_e32 v12, 0xffff0000, v12
	v_add_f32_e32 v53, v53, v57
	v_add_f32_e32 v54, v54, v12
	v_fma_f32 v59, v58, v53, -v57
	v_fma_f32 v58, v58, v54, -v12
	v_sub_f32_e32 v9, v54, v9
	v_add_u32_e32 v54, s95, v127
	v_min_i32_e32 v54, 3, v54
	v_add_u32_e32 v54, 1, v54
	v_cvt_f32_i32_e32 v54, v54
	v_cndmask_b32_e64 v13, v13, 0, s[8:9]
	v_sub_f32_e32 v52, v53, v52
	v_lshlrev_b32_e32 v53, 16, v13
	v_rcp_iflag_f32_e32 v54, v54
	v_and_b32_e32 v13, 0xffff0000, v13
	v_cvt_pk_bf16_f32 v58, v59, v58
	v_add_u32_e32 v116, 0, v145
	v_add_f32_e32 v52, v52, v53
	v_add_f32_e32 v9, v9, v13
	s_waitcnt lgkmcnt(0)
	s_barrier
	ds_write_b32 v116, v58 offset:34816
	v_fma_f32 v58, v54, v52, -v53
	v_fma_f32 v54, v54, v9, -v13
	v_cvt_pk_bf16_f32 v54, v58, v54
	v_add_u32_e32 v117, 0, v146
	ds_write_b32 v117, v54 offset:34816
	v_add_u32_e32 v54, s95, v128
	v_min_i32_e32 v54, 3, v54
	v_add_u32_e32 v54, 1, v54
	v_cvt_f32_i32_e32 v54, v54
	v_cndmask_b32_e64 v14, 0, v14, s[10:11]
	v_sub_f32_e32 v52, v52, v55
	v_sub_f32_e32 v9, v9, v10
	v_rcp_iflag_f32_e32 v54, v54
	v_lshlrev_b32_e32 v10, 16, v14
	v_and_b32_e32 v14, 0xffff0000, v14
	v_add_f32_e32 v52, v52, v10
	v_add_f32_e32 v9, v9, v14
	v_fma_f32 v55, v54, v52, -v10
	v_fma_f32 v54, v54, v9, -v14
	v_cvt_pk_bf16_f32 v54, v55, v54
	v_add_u32_e32 v168, 0, v147
	ds_write_b32 v168, v54 offset:34816
	v_add_u32_e32 v54, s95, v129
	v_min_i32_e32 v54, 3, v54
	v_add_u32_e32 v54, 1, v54
	v_cvt_f32_i32_e32 v54, v54
	v_cndmask_b32_e64 v15, 0, v15, s[12:13]
	v_sub_f32_e32 v52, v52, v56
	v_sub_f32_e32 v9, v9, v11
	v_rcp_iflag_f32_e32 v54, v54
	v_lshlrev_b32_e32 v11, 16, v15
	v_and_b32_e32 v15, 0xffff0000, v15
	v_add_f32_e32 v52, v52, v11
	v_add_f32_e32 v9, v9, v15
	v_fma_f32 v55, v54, v52, -v11
	v_fma_f32 v54, v54, v9, -v15
	v_cvt_pk_bf16_f32 v54, v55, v54
	v_add_u32_e32 v169, 0, v148
	ds_write_b32 v169, v54 offset:34816
	v_add_u32_e32 v54, s95, v130
	v_min_i32_e32 v54, 3, v54
	v_add_u32_e32 v54, 1, v54
	v_cvt_f32_i32_e32 v54, v54
	v_cndmask_b32_e64 v16, 0, v16, s[14:15]
	v_sub_f32_e32 v52, v52, v57
	v_sub_f32_e32 v9, v9, v12
	v_rcp_iflag_f32_e32 v54, v54
	v_lshlrev_b32_e32 v12, 16, v16
	v_add_f32_e32 v52, v52, v12
	v_and_b32_e32 v16, 0xffff0000, v16
	v_fma_f32 v55, v54, v52, -v12
	v_sub_f32_e32 v52, v52, v53
	v_add_u32_e32 v53, s95, v131
	v_min_i32_e32 v53, 3, v53
	v_add_u32_e32 v53, 1, v53
	v_cvt_f32_i32_e32 v53, v53
	v_cndmask_b32_e64 v17, 0, v17, s[16:17]
	v_add_f32_e32 v9, v9, v16
	v_fma_f32 v54, v54, v9, -v16
	v_rcp_iflag_f32_e32 v53, v53
	v_sub_f32_e32 v9, v9, v13
	v_lshlrev_b32_e32 v13, 16, v17
	v_cvt_pk_bf16_f32 v54, v55, v54
	v_add_u32_e32 v170, 0, v149
	v_add_f32_e32 v52, v52, v13
	ds_write_b32 v170, v54 offset:34816
	v_fma_f32 v54, v53, v52, -v13
	v_sub_f32_e32 v10, v52, v10
	v_add_u32_e32 v52, s95, v132
	v_min_i32_e32 v52, 3, v52
	v_add_u32_e32 v52, 1, v52
	v_cvt_f32_i32_e32 v52, v52
	v_and_b32_e32 v17, 0xffff0000, v17
	v_cndmask_b32_e64 v50, 0, v50, s[18:19]
	v_add_f32_e32 v9, v9, v17
	v_rcp_iflag_f32_e32 v52, v52
	v_fma_f32 v53, v53, v9, -v17
	v_sub_f32_e32 v9, v9, v14
	v_lshlrev_b32_e32 v14, 16, v50
	v_and_b32_e32 v50, 0xffff0000, v50
	v_cndmask_b32_e64 v51, 0, v51, s[20:21]
	v_cvt_pk_bf16_f32 v53, v54, v53
	v_add_u32_e32 v171, 0, v150
	v_add_f32_e32 v10, v10, v14
	v_add_f32_e32 v9, v9, v50
	ds_write_b32 v171, v53 offset:34816
	v_fma_f32 v53, v52, v10, -v14
	v_fma_f32 v52, v52, v9, -v50
	v_sub_f32_e32 v10, v10, v11
	v_sub_f32_e32 v9, v9, v15
	v_lshlrev_b32_e32 v11, 16, v51
	v_and_b32_e32 v15, 0xffff0000, v51
	v_add_u32_e32 v51, s95, v133
	v_min_i32_e32 v51, 3, v51
	v_add_u32_e32 v51, 1, v51
	v_cvt_f32_i32_e32 v51, v51
	v_cvt_pk_bf16_f32 v52, v53, v52
	v_add_u32_e32 v172, 0, v151
	v_add_f32_e32 v10, v10, v11
	v_rcp_iflag_f32_e32 v51, v51
	v_add_f32_e32 v9, v9, v15
	ds_write_b32 v172, v52 offset:34816
	v_cndmask_b32_e64 v8, 0, v8, s[22:23]
	v_fma_f32 v52, v51, v10, -v11
	v_fma_f32 v51, v51, v9, -v15
	v_sub_f32_e32 v9, v9, v16
	v_add_u32_e32 v16, s95, v134
	v_min_i32_e32 v16, 3, v16
	v_add_u32_e32 v16, 1, v16
	v_cvt_f32_i32_e32 v16, v16
	v_sub_f32_e32 v10, v10, v12
	v_lshlrev_b32_e32 v12, 16, v8
	v_and_b32_e32 v8, 0xffff0000, v8
	v_rcp_iflag_f32_e32 v16, v16
	v_cvt_pk_bf16_f32 v51, v52, v51
	v_add_u32_e32 v173, 0, v152
	v_add_f32_e32 v10, v10, v12
	v_add_f32_e32 v9, v9, v8
	ds_write_b32 v173, v51 offset:34816
	v_fma_f32 v51, v16, v10, -v12
	v_fma_f32 v16, v16, v9, -v8
	v_cvt_pk_bf16_f32 v16, v51, v16
	v_add_u32_e32 v174, 0, v153
	ds_write_b32 v174, v16 offset:34816
	v_add_u32_e32 v16, s95, v135
	v_min_i32_e32 v16, 3, v16
	v_add_u32_e32 v16, 1, v16
	v_cvt_f32_i32_e32 v16, v16
	v_cndmask_b32_e64 v7, 0, v7, s[24:25]
	v_sub_f32_e32 v10, v10, v13
	v_sub_f32_e32 v9, v9, v17
	v_rcp_iflag_f32_e32 v16, v16
	v_lshlrev_b32_e32 v13, 16, v7
	v_and_b32_e32 v7, 0xffff0000, v7
	v_add_f32_e32 v10, v10, v13
	v_add_f32_e32 v9, v9, v7
	v_fma_f32 v17, v16, v10, -v13
	v_fma_f32 v16, v16, v9, -v7
	v_cvt_pk_bf16_f32 v16, v17, v16
	v_add_u32_e32 v175, 0, v154
	ds_write_b32 v175, v16 offset:34816
	v_add_u32_e32 v16, s95, v136
	v_min_i32_e32 v16, 3, v16
	v_add_u32_e32 v16, 1, v16
	v_cvt_f32_i32_e32 v16, v16
	v_cndmask_b32_e64 v6, 0, v6, s[26:27]
	v_sub_f32_e32 v10, v10, v14
	v_sub_f32_e32 v9, v9, v50
	v_rcp_iflag_f32_e32 v16, v16
	v_lshlrev_b32_e32 v14, 16, v6
	v_and_b32_e32 v6, 0xffff0000, v6
	v_add_f32_e32 v10, v10, v14
	v_add_f32_e32 v9, v9, v6
	v_fma_f32 v17, v16, v10, -v14
	v_fma_f32 v16, v16, v9, -v6
	v_sub_f32_e32 v9, v9, v15
	v_add_u32_e32 v15, s95, v137
	v_min_i32_e32 v15, 3, v15
	v_add_u32_e32 v15, 1, v15
	v_cvt_f32_i32_e32 v15, v15
	v_cndmask_b32_e64 v5, 0, v5, s[28:29]
	v_sub_f32_e32 v10, v10, v11
	v_lshlrev_b32_e32 v11, 16, v5
	v_rcp_iflag_f32_e32 v15, v15
	v_cvt_pk_bf16_f32 v16, v17, v16
	v_add_u32_e32 v176, 0, v155
	v_add_f32_e32 v10, v10, v11
	ds_write_b32 v176, v16 offset:34816
	v_fma_f32 v16, v15, v10, -v11
	v_sub_f32_e32 v10, v10, v12
	v_add_u32_e32 v12, s95, v138
	v_min_i32_e32 v12, 3, v12
	v_add_u32_e32 v12, 1, v12
	v_cvt_f32_i32_e32 v12, v12
	v_and_b32_e32 v5, 0xffff0000, v5
	v_cndmask_b32_e64 v4, 0, v4, s[42:43]
	v_add_f32_e32 v9, v9, v5
	v_rcp_iflag_f32_e32 v12, v12
	v_fma_f32 v15, v15, v9, -v5
	v_sub_f32_e32 v8, v9, v8
	v_lshlrev_b32_e32 v9, 16, v4
	v_and_b32_e32 v4, 0xffff0000, v4
	v_add_f32_e32 v10, v10, v9
	v_add_f32_e32 v8, v8, v4
	v_fma_f32 v9, v12, v10, -v9
	v_fma_f32 v4, v12, v8, -v4
	v_cvt_pk_bf16_f32 v4, v9, v4
	v_add_u32_e32 v9, s95, v139
	v_min_i32_e32 v9, 3, v9
	v_add_u32_e32 v9, 1, v9
	v_cvt_f32_i32_e32 v9, v9
	v_cndmask_b32_e64 v3, 0, v3, s[34:35]
	v_add_u32_e32 v177, 0, v156
	v_add_u32_e32 v178, 0, v157
	v_rcp_iflag_f32_e32 v9, v9
	v_sub_f32_e32 v7, v8, v7
	v_lshlrev_b32_e32 v8, 16, v3
	v_and_b32_e32 v3, 0xffff0000, v3
	v_cvt_pk_bf16_f32 v15, v16, v15
	ds_write_b32 v177, v15 offset:34816
	ds_write_b32 v178, v4 offset:34816
	v_sub_f32_e32 v4, v10, v13
	v_add_f32_e32 v7, v7, v3
	v_add_f32_e32 v4, v4, v8
	v_fma_f32 v3, v9, v7, -v3
	v_fma_f32 v8, v9, v4, -v8
	v_cvt_pk_bf16_f32 v3, v8, v3
	v_add_u32_e32 v179, 0, v158
	ds_write_b32 v179, v3 offset:34816
	v_sub_f32_e32 v3, v4, v14
	v_sub_f32_e32 v4, v7, v6
	v_add_u32_e32 v7, s95, v140
	v_min_i32_e32 v7, 3, v7
	v_add_u32_e32 v7, 1, v7
	v_cvt_f32_i32_e32 v7, v7
	v_cndmask_b32_e64 v2, 0, v2, s[36:37]
	v_lshlrev_b32_e32 v6, 16, v2
	v_and_b32_e32 v2, 0xffff0000, v2
	v_rcp_iflag_f32_e32 v7, v7
	v_add_f32_e32 v4, v4, v2
	v_add_f32_e32 v3, v3, v6
	v_add_u32_e32 v180, 0, v159
	v_fma_f32 v2, v7, v4, -v2
	v_fma_f32 v6, v7, v3, -v6
	v_cvt_pk_bf16_f32 v2, v6, v2
	ds_write_b32 v180, v2 offset:34816
	v_sub_f32_e32 v2, v3, v11
	v_sub_f32_e32 v3, v4, v5
	v_add_u32_e32 v5, s95, v141
	v_min_i32_e32 v5, 3, v5
	v_add_u32_e32 v5, 1, v5
	v_cvt_f32_i32_e32 v5, v5
	s_or_b32 s0, s94, 0x80
	v_lshlrev_b32_e32 v4, 16, v0
	v_and_b32_e32 v0, 0xffff0000, v0
	v_rcp_iflag_f32_e32 v5, v5
	s_xor_b32 s1, s95, 0xffffff7f
	s_mul_i32 s2, s0, 0x1e00
	v_add_f32_e32 v2, v2, v4
	v_add_f32_e32 v3, v3, v0
	s_mul_hi_i32 s3, s0, 0x1e00
	s_add_u32 s2, s91, s2
	v_fma_f32 v2, v5, v2, -v4
	v_fma_f32 v0, v5, v3, -v0
	s_addc_u32 s3, s92, s3
	v_mov_b32_e32 v105, v1
	v_cvt_pk_bf16_f32 v0, v2, v0
	v_add_u32_e32 v181, 0, v160
	v_cmp_lt_i32_e32 vcc, s1, v141
	v_lshl_add_u64 v[2:3], s[2:3], 0, v[104:105]
	s_mov_b64 s[2:3], 0x1520
	ds_write_b32 v181, v0 offset:34816
	v_lshl_add_u64 v[2:3], v[2:3], 0, s[2:3]
	v_cndmask_b32_e32 v0, 0, v141, vcc
	s_movk_i32 s6, 0x1e00
	v_mad_i64_i32 v[4:5], s[2:3], v0, s6, v[2:3]
	global_load_dword v0, v[4:5], off
	v_add_u32_e32 v185, v144, v143
	v_add_u32_e32 v184, v144, v161
	v_lshlrev_b32_e32 v104, 1, v90
	v_mov_b32_e32 v103, v1
	v_add_u32_e32 v183, v144, v163
	v_lshlrev_b32_e32 v114, 1, v98
	v_mov_b32_e32 v115, v1
	s_waitcnt vmcnt(0)
	v_cndmask_b32_e32 v182, 0, v0, vcc
	v_cmp_lt_i32_e32 vcc, s1, v124
	v_mov_b32_e32 v211, 0
	s_nop 0
	v_cndmask_b32_e32 v0, 0, v124, vcc
	v_mad_i64_i32 v[4:5], s[2:3], v0, s6, v[2:3]
	s_and_saveexec_b64 s[98:99], vcc
	global_load_dword v211, v[4:5], off
	s_mov_b64 exec, s[98:99]
	v_cmp_lt_i32_e32 vcc, s1, v125
	v_mov_b32_e32 v212, 0
	s_nop 0
	v_cndmask_b32_e32 v0, 0, v125, vcc
	v_mad_i64_i32 v[4:5], s[2:3], v0, s6, v[2:3]
	s_and_saveexec_b64 s[98:99], vcc
	global_load_dword v212, v[4:5], off
	s_mov_b64 exec, s[98:99]
	v_cmp_lt_i32_e32 vcc, s1, v126
	v_mov_b32_e32 v213, 0
	s_nop 0
	v_cndmask_b32_e32 v0, 0, v126, vcc
	v_mad_i64_i32 v[4:5], s[2:3], v0, s6, v[2:3]
	s_and_saveexec_b64 s[98:99], vcc
	global_load_dword v213, v[4:5], off
	s_mov_b64 exec, s[98:99]
	v_cmp_lt_i32_e32 vcc, s1, v83
	v_mov_b32_e32 v214, 0
	s_nop 0
	v_cndmask_b32_e32 v0, 0, v83, vcc
	v_mad_i64_i32 v[4:5], s[2:3], v0, s6, v[2:3]
	s_and_saveexec_b64 s[98:99], vcc
	global_load_dword v214, v[4:5], off
	s_mov_b64 exec, s[98:99]
	v_cmp_gt_i32_e32 vcc, s1, v83
	s_nop 1
	v_cndmask_b32_e64 v0, v127, 0, vcc
	v_mad_i64_i32 v[4:5], s[2:3], v0, s6, v[2:3]
	global_load_dword v0, v[4:5], off
	s_waitcnt vmcnt(0)
	v_cndmask_b32_e64 v191, v0, 0, vcc
	v_cmp_lt_i32_e32 vcc, s1, v128
	v_mov_b32_e32 v210, 0
	s_nop 0
	v_cndmask_b32_e32 v0, 0, v128, vcc
	v_mad_i64_i32 v[4:5], s[2:3], v0, s6, v[2:3]
	s_and_saveexec_b64 s[98:99], vcc
	global_load_dword v210, v[4:5], off
	s_mov_b64 exec, s[98:99]
	v_cmp_lt_i32_e32 vcc, s1, v129
	v_mov_b32_e32 v209, 0
	s_nop 0
	v_cndmask_b32_e32 v0, 0, v129, vcc
	v_mad_i64_i32 v[4:5], s[2:3], v0, s6, v[2:3]
	s_and_saveexec_b64 s[98:99], vcc
	global_load_dword v209, v[4:5], off
	s_mov_b64 exec, s[98:99]
	v_cmp_lt_i32_e32 vcc, s1, v130
	v_mov_b32_e32 v208, 0
	s_nop 0
	v_cndmask_b32_e32 v0, 0, v130, vcc
	v_mad_i64_i32 v[4:5], s[2:3], v0, s6, v[2:3]
	s_and_saveexec_b64 s[98:99], vcc
	global_load_dword v208, v[4:5], off
	s_mov_b64 exec, s[98:99]
	v_cmp_lt_i32_e32 vcc, s1, v131
	v_mov_b32_e32 v207, 0
	s_nop 0
	v_cndmask_b32_e32 v0, 0, v131, vcc
	v_mad_i64_i32 v[4:5], s[2:3], v0, s6, v[2:3]
	s_and_saveexec_b64 s[98:99], vcc
	global_load_dword v207, v[4:5], off
	s_mov_b64 exec, s[98:99]
	v_cmp_lt_i32_e32 vcc, s1, v132
	v_mov_b32_e32 v206, 0
	s_nop 0
	v_cndmask_b32_e32 v0, 0, v132, vcc
	v_mad_i64_i32 v[4:5], s[2:3], v0, s6, v[2:3]
	s_and_saveexec_b64 s[98:99], vcc
	global_load_dword v206, v[4:5], off
	s_mov_b64 exec, s[98:99]
	v_cmp_lt_i32_e32 vcc, s1, v133
	v_mov_b32_e32 v205, 0
	s_nop 0
	v_cndmask_b32_e32 v0, 0, v133, vcc
	v_mad_i64_i32 v[4:5], s[2:3], v0, s6, v[2:3]
	s_and_saveexec_b64 s[98:99], vcc
	global_load_dword v205, v[4:5], off
	s_mov_b64 exec, s[98:99]
	v_cmp_lt_i32_e32 vcc, s1, v134
	v_mov_b32_e32 v204, 0
	s_nop 0
	v_cndmask_b32_e32 v0, 0, v134, vcc
	v_mad_i64_i32 v[4:5], s[2:3], v0, s6, v[2:3]
	s_and_saveexec_b64 s[98:99], vcc
	global_load_dword v204, v[4:5], off
	s_mov_b64 exec, s[98:99]
	v_cmp_lt_i32_e32 vcc, s1, v135
	v_mov_b32_e32 v192, 0
	s_nop 0
	v_cndmask_b32_e32 v0, 0, v135, vcc
	v_mad_i64_i32 v[4:5], s[2:3], v0, s6, v[2:3]
	s_and_saveexec_b64 s[98:99], vcc
	global_load_dword v192, v[4:5], off
	s_mov_b64 exec, s[98:99]
	v_cmp_lt_i32_e32 vcc, s1, v136
	v_mov_b32_e32 v190, 0
	s_nop 0
	v_cndmask_b32_e32 v0, 0, v136, vcc
	v_mad_i64_i32 v[4:5], s[2:3], v0, s6, v[2:3]
	s_and_saveexec_b64 s[98:99], vcc
	global_load_dword v190, v[4:5], off
	s_mov_b64 exec, s[98:99]
	v_cmp_lt_i32_e32 vcc, s1, v137
	v_mov_b32_e32 v189, 0
	s_nop 0
	v_cndmask_b32_e32 v0, 0, v137, vcc
	v_mad_i64_i32 v[4:5], s[2:3], v0, s6, v[2:3]
	s_and_saveexec_b64 s[98:99], vcc
	global_load_dword v189, v[4:5], off
	s_mov_b64 exec, s[98:99]
	v_cmp_lt_i32_e32 vcc, s1, v138
	v_mov_b32_e32 v188, 0
	s_nop 0
	v_cndmask_b32_e32 v0, 0, v138, vcc
	v_mad_i64_i32 v[4:5], s[2:3], v0, s6, v[2:3]
	s_and_saveexec_b64 s[98:99], vcc
	global_load_dword v188, v[4:5], off
	s_mov_b64 exec, s[98:99]
	v_cmp_lt_i32_e32 vcc, s1, v139
	v_mov_b32_e32 v187, 0
	s_nop 0
	v_cndmask_b32_e32 v0, 0, v139, vcc
	v_mad_i64_i32 v[4:5], s[2:3], v0, s6, v[2:3]
	s_and_saveexec_b64 s[98:99], vcc
	global_load_dword v187, v[4:5], off
	s_mov_b64 exec, s[98:99]
	v_cmp_lt_i32_e32 vcc, s1, v140
	s_and_b32 s1, s0, 0xf80
	s_nop 0
	v_cndmask_b32_e32 v0, 0, v140, vcc
	v_mad_i64_i32 v[2:3], s[2:3], v0, s6, v[2:3]
	global_load_dword v0, v[2:3], off
	v_add_u32_e32 v2, s94, v142
	v_ashrrev_i32_e32 v3, 31, v2
	v_lshlrev_b64 v[2:3], 12, v[2:3]
	s_waitcnt lgkmcnt(0)
	s_barrier
	v_lshl_add_u64 v[2:3], s[70:71], 0, v[2:3]
	s_mov_b64 s[2:3], 0x26000900
	ds_read_b128 v[74:77], v185 offset:34816
	ds_read_b128 v[78:81], v185 offset:34848
	ds_read_b128 v[70:73], v185 offset:34880
	ds_read_b128 v[66:69], v185 offset:34912
	ds_read_b128 v[62:65], v185 offset:34944
	ds_read_b128 v[58:61], v185 offset:34976
	ds_read_b128 v[54:57], v185 offset:35008
	ds_read_b128 v[50:53], v185 offset:35040
	v_lshl_add_u64 v[106:107], v[2:3], 0, s[2:3]
	ds_read_b128 v[2:5], v184
	ds_read_b128 v[108:111], v184 offset:32
	ds_read_b128 v[228:231], v184 offset:64
	ds_read_b128 v[242:245], v184 offset:96
	s_waitcnt lgkmcnt(3)
	v_mfma_f32_32x32x16_bf16 v[2:17], v[2:5], v[74:77], 0
	s_waitcnt vmcnt(0)
	v_cndmask_b32_e32 v186, 0, v0, vcc
	s_waitcnt lgkmcnt(2)
	v_mfma_f32_32x32x16_bf16 v[2:17], v[108:111], v[78:81], v[2:17]
	ds_read_b128 v[108:111], v184 offset:128
	s_waitcnt lgkmcnt(2)
	v_mfma_f32_32x32x16_bf16 v[2:17], v[228:231], v[70:73], v[2:17]
	ds_read_b128 v[228:231], v184 offset:160
	s_waitcnt lgkmcnt(2)
	v_mfma_f32_32x32x16_bf16 v[2:17], v[242:245], v[66:69], v[2:17]
	ds_read_b128 v[242:245], v184 offset:192
	s_waitcnt lgkmcnt(2)
	v_mfma_f32_32x32x16_bf16 v[2:17], v[108:111], v[62:65], v[2:17]
	ds_read_b128 v[108:111], v184 offset:224
	s_waitcnt lgkmcnt(2)
	v_mfma_f32_32x32x16_bf16 v[2:17], v[228:231], v[58:61], v[2:17]
	s_waitcnt lgkmcnt(1)
	v_mfma_f32_32x32x16_bf16 v[2:17], v[242:245], v[54:57], v[2:17]
	s_waitcnt lgkmcnt(0)
	v_mfma_f32_32x32x16_bf16 v[2:17], v[108:111], v[50:53], v[2:17]
	v_lshlrev_b32_e32 v108, 1, v92
	v_mov_b32_e32 v109, v1
	s_nop 9
	v_mul_f32_e32 v0, v46, v2
	v_mul_f32_e32 v2, v47, v3
	v_cvt_pk_bf16_f32 v2, v0, v2
	v_mul_f32_e32 v0, v48, v4
	v_mul_f32_e32 v3, v49, v5
	v_cvt_pk_bf16_f32 v3, v0, v3
	v_lshlrev_b32_e32 v0, 1, v88
	v_lshl_add_u64 v[4:5], v[106:107], 0, v[0:1]
	global_store_dwordx2 v[4:5], v[2:3], off
	v_mul_f32_e32 v2, v42, v6
	v_mul_f32_e32 v3, v43, v7
	v_cvt_pk_bf16_f32 v2, v2, v3
	v_mul_f32_e32 v3, v44, v8
	v_mul_f32_e32 v4, v45, v9
	v_cvt_pk_bf16_f32 v3, v3, v4
	v_lshl_add_u64 v[4:5], v[106:107], 0, v[104:105]
	global_store_dwordx2 v[4:5], v[2:3], off
	v_mul_f32_e32 v2, v38, v10
	v_mul_f32_e32 v3, v39, v11
	v_cvt_pk_bf16_f32 v2, v2, v3
	v_mul_f32_e32 v3, v40, v12
	v_mul_f32_e32 v4, v41, v13
	v_cvt_pk_bf16_f32 v3, v3, v4
	v_lshl_add_u64 v[4:5], v[106:107], 0, v[108:109]
	global_store_dwordx2 v[4:5], v[2:3], off
	v_mul_f32_e32 v2, v34, v14
	v_mul_f32_e32 v3, v35, v15
	v_cvt_pk_bf16_f32 v2, v2, v3
	v_mul_f32_e32 v3, v36, v16
	v_mul_f32_e32 v4, v37, v17
	v_cvt_pk_bf16_f32 v3, v3, v4
	v_lshl_add_u64 v[4:5], v[106:107], 0, v[102:103]
	global_store_dwordx2 v[4:5], v[2:3], off
	ds_read_b128 v[228:231], v183
	ds_read_b128 v[242:245], v183 offset:32
	ds_read_b128 v[246:249], v183 offset:64
	s_waitcnt lgkmcnt(2)
	v_mfma_f32_32x32x16_bf16 v[2:17], v[228:231], v[74:77], 0
	ds_read_b128 v[228:231], v183 offset:96
	s_waitcnt lgkmcnt(2)
	v_mfma_f32_32x32x16_bf16 v[2:17], v[242:245], v[78:81], v[2:17]
	ds_read_b128 v[242:245], v183 offset:128
	v_lshlrev_b32_e32 v110, 1, v94
	v_mov_b32_e32 v111, v1
	v_lshlrev_b32_e32 v112, 1, v96
	v_mov_b32_e32 v113, v1
	s_waitcnt lgkmcnt(2)
	v_mfma_f32_32x32x16_bf16 v[2:17], v[246:249], v[70:73], v[2:17]
	ds_read_b128 v[246:249], v183 offset:160
	s_waitcnt lgkmcnt(2)
	v_mfma_f32_32x32x16_bf16 v[2:17], v[228:231], v[66:69], v[2:17]
	ds_read_b128 v[228:231], v183 offset:192
	s_waitcnt lgkmcnt(2)
	v_mfma_f32_32x32x16_bf16 v[2:17], v[242:245], v[62:65], v[2:17]
	ds_read_b128 v[242:245], v183 offset:224
	s_waitcnt lgkmcnt(2)
	v_mfma_f32_32x32x16_bf16 v[2:17], v[246:249], v[58:61], v[2:17]
	s_waitcnt lgkmcnt(1)
	v_mfma_f32_32x32x16_bf16 v[2:17], v[228:231], v[54:57], v[2:17]
	s_waitcnt lgkmcnt(0)
	v_mfma_f32_32x32x16_bf16 v[2:17], v[242:245], v[50:53], v[2:17]
	s_nop 11
	v_mul_f32_e32 v2, v30, v2
	v_mul_f32_e32 v3, v31, v3
	v_cvt_pk_bf16_f32 v2, v2, v3
	v_mul_f32_e32 v3, v32, v4
	v_mul_f32_e32 v4, v33, v5
	v_cvt_pk_bf16_f32 v3, v3, v4
	v_lshl_add_u64 v[4:5], v[106:107], 0, v[110:111]
	global_store_dwordx2 v[4:5], v[2:3], off
	v_mul_f32_e32 v2, v26, v6
	v_mul_f32_e32 v3, v27, v7
	v_cvt_pk_bf16_f32 v2, v2, v3
	v_mul_f32_e32 v3, v28, v8
	v_mul_f32_e32 v4, v29, v9
	v_cvt_pk_bf16_f32 v3, v3, v4
	v_lshl_add_u64 v[4:5], v[106:107], 0, v[112:113]
	global_store_dwordx2 v[4:5], v[2:3], off
	v_mul_f32_e32 v2, v22, v10
	v_mul_f32_e32 v3, v23, v11
	v_cvt_pk_bf16_f32 v2, v2, v3
	v_mul_f32_e32 v3, v24, v12
	v_mul_f32_e32 v4, v25, v13
	v_add_u32_e32 v12, s1, v83
	v_cvt_pk_bf16_f32 v3, v3, v4
	v_lshl_add_u64 v[4:5], v[106:107], 0, v[114:115]
	v_min_i32_e32 v12, 3, v12
	global_store_dwordx2 v[4:5], v[2:3], off
	v_mul_f32_e32 v2, v18, v14
	v_mul_f32_e32 v3, v19, v15
	v_add_u32_e32 v12, 1, v12
	v_cvt_pk_bf16_f32 v2, v2, v3
	v_mul_f32_e32 v3, v20, v16
	v_mul_f32_e32 v4, v21, v17
	v_cvt_f32_i32_e32 v12, v12
	v_cvt_pk_bf16_f32 v3, v3, v4
	v_lshlrev_b32_e32 v4, 1, v100
	v_mov_b32_e32 v5, v1
	v_lshl_add_u64 v[4:5], v[106:107], 0, v[4:5]
	global_store_dwordx2 v[4:5], v[2:3], off
	v_lshlrev_b32_e32 v2, 16, v211
	v_and_b32_e32 v4, 0xffff0000, v211
	v_add_f32_e32 v3, 0, v2
	v_add_f32_e32 v5, 0, v4
	v_lshlrev_b32_e32 v6, 16, v212
	v_and_b32_e32 v7, 0xffff0000, v212
	v_rcp_iflag_f32_e32 v12, v12
	v_add_f32_e32 v3, v3, v6
	v_add_f32_e32 v5, v5, v7
	v_lshlrev_b32_e32 v8, 16, v213
	v_and_b32_e32 v9, 0xffff0000, v213
	v_add_f32_e32 v3, v3, v8
	v_add_f32_e32 v5, v5, v9
	v_lshlrev_b32_e32 v10, 16, v214
	v_and_b32_e32 v11, 0xffff0000, v214
	v_add_f32_e32 v3, v3, v10
	v_add_f32_e32 v5, v5, v11
	v_fma_f32 v13, v12, v3, -v10
	v_fma_f32 v12, v12, v5, -v11
	v_cvt_pk_bf16_f32 v12, v13, v12
	s_waitcnt lgkmcnt(0)
	s_barrier
	ds_write_b32 v116, v12 offset:34816
	v_add_u32_e32 v12, s1, v127
	v_min_i32_e32 v12, 3, v12
	v_add_u32_e32 v12, 1, v12
	v_cvt_f32_i32_e32 v12, v12
	v_sub_f32_e32 v2, v3, v2
	v_sub_f32_e32 v3, v5, v4
	v_lshlrev_b32_e32 v4, 16, v191
	v_rcp_iflag_f32_e32 v12, v12
	v_and_b32_e32 v5, 0xffff0000, v191
	v_add_f32_e32 v2, v2, v4
	v_add_f32_e32 v3, v3, v5
	v_fma_f32 v13, v12, v2, -v4
	v_fma_f32 v12, v12, v3, -v5
	v_cvt_pk_bf16_f32 v12, v13, v12
	ds_write_b32 v117, v12 offset:34816
	v_add_u32_e32 v12, s1, v128
	v_min_i32_e32 v12, 3, v12
	v_add_u32_e32 v12, 1, v12
	v_cvt_f32_i32_e32 v12, v12
	v_sub_f32_e32 v2, v2, v6
	v_sub_f32_e32 v3, v3, v7
	v_lshlrev_b32_e32 v6, 16, v210
	v_rcp_iflag_f32_e32 v12, v12
	v_and_b32_e32 v7, 0xffff0000, v210
	v_add_f32_e32 v2, v2, v6
	v_add_f32_e32 v3, v3, v7
	v_fma_f32 v13, v12, v2, -v6
	v_fma_f32 v12, v12, v3, -v7
	v_cvt_pk_bf16_f32 v12, v13, v12
	ds_write_b32 v168, v12 offset:34816
	v_add_u32_e32 v12, s1, v129
	v_min_i32_e32 v12, 3, v12
	v_add_u32_e32 v12, 1, v12
	v_cvt_f32_i32_e32 v12, v12
	v_sub_f32_e32 v2, v2, v8
	v_sub_f32_e32 v3, v3, v9
	v_lshlrev_b32_e32 v8, 16, v209
	v_rcp_iflag_f32_e32 v12, v12
	v_and_b32_e32 v9, 0xffff0000, v209
	v_add_f32_e32 v2, v2, v8
	v_add_f32_e32 v3, v3, v9
	v_fma_f32 v13, v12, v2, -v8
	v_fma_f32 v12, v12, v3, -v9
	v_cvt_pk_bf16_f32 v12, v13, v12
	ds_write_b32 v169, v12 offset:34816
	v_add_u32_e32 v12, s1, v130
	v_min_i32_e32 v12, 3, v12
	v_add_u32_e32 v12, 1, v12
	v_cvt_f32_i32_e32 v12, v12
	v_sub_f32_e32 v2, v2, v10
	v_sub_f32_e32 v3, v3, v11
	v_lshlrev_b32_e32 v10, 16, v208
	v_rcp_iflag_f32_e32 v12, v12
	v_and_b32_e32 v11, 0xffff0000, v208
	v_add_f32_e32 v2, v2, v10
	v_add_f32_e32 v3, v3, v11
	v_fma_f32 v13, v12, v2, -v10
	v_fma_f32 v12, v12, v3, -v11
	v_cvt_pk_bf16_f32 v12, v13, v12
	ds_write_b32 v170, v12 offset:34816
	v_add_u32_e32 v12, s1, v131
	v_min_i32_e32 v12, 3, v12
	v_add_u32_e32 v12, 1, v12
	v_cvt_f32_i32_e32 v12, v12
	v_sub_f32_e32 v2, v2, v4
	v_sub_f32_e32 v3, v3, v5
	v_lshlrev_b32_e32 v4, 16, v207
	v_rcp_iflag_f32_e32 v12, v12
	v_and_b32_e32 v5, 0xffff0000, v207
	v_add_f32_e32 v2, v2, v4
	v_add_f32_e32 v3, v3, v5
	v_fma_f32 v13, v12, v2, -v4
	v_fma_f32 v12, v12, v3, -v5
	v_cvt_pk_bf16_f32 v12, v13, v12
	ds_write_b32 v171, v12 offset:34816
	v_add_u32_e32 v12, s1, v132
	v_min_i32_e32 v12, 3, v12
	v_add_u32_e32 v12, 1, v12
	v_cvt_f32_i32_e32 v12, v12
	v_sub_f32_e32 v2, v2, v6
	v_sub_f32_e32 v3, v3, v7
	v_lshlrev_b32_e32 v6, 16, v206
	v_rcp_iflag_f32_e32 v12, v12
	v_and_b32_e32 v7, 0xffff0000, v206
	v_add_f32_e32 v2, v2, v6
	v_add_f32_e32 v3, v3, v7
	v_fma_f32 v13, v12, v2, -v6
	v_fma_f32 v12, v12, v3, -v7
	v_cvt_pk_bf16_f32 v12, v13, v12
	ds_write_b32 v172, v12 offset:34816
	v_add_u32_e32 v12, s1, v133
	v_min_i32_e32 v12, 3, v12
	v_add_u32_e32 v12, 1, v12
	v_cvt_f32_i32_e32 v12, v12
	v_sub_f32_e32 v2, v2, v8
	v_sub_f32_e32 v3, v3, v9
	v_lshlrev_b32_e32 v8, 16, v205
	v_rcp_iflag_f32_e32 v12, v12
	v_and_b32_e32 v9, 0xffff0000, v205
	v_add_f32_e32 v2, v2, v8
	v_add_f32_e32 v3, v3, v9
	v_fma_f32 v13, v12, v2, -v8
	v_fma_f32 v12, v12, v3, -v9
	v_cvt_pk_bf16_f32 v12, v13, v12
	ds_write_b32 v173, v12 offset:34816
	v_add_u32_e32 v12, s1, v134
	v_min_i32_e32 v12, 3, v12
	v_add_u32_e32 v12, 1, v12
	v_cvt_f32_i32_e32 v12, v12
	v_sub_f32_e32 v2, v2, v10
	v_sub_f32_e32 v3, v3, v11
	v_lshlrev_b32_e32 v10, 16, v204
	v_rcp_iflag_f32_e32 v12, v12
	v_and_b32_e32 v11, 0xffff0000, v204
	v_add_f32_e32 v2, v2, v10
	v_add_f32_e32 v3, v3, v11
	v_fma_f32 v13, v12, v2, -v10
	v_fma_f32 v12, v12, v3, -v11
	v_cvt_pk_bf16_f32 v12, v13, v12
	ds_write_b32 v174, v12 offset:34816
	v_add_u32_e32 v12, s1, v135
	v_min_i32_e32 v12, 3, v12
	v_add_u32_e32 v12, 1, v12
	v_cvt_f32_i32_e32 v12, v12
	v_sub_f32_e32 v2, v2, v4
	v_sub_f32_e32 v3, v3, v5
	v_lshlrev_b32_e32 v4, 16, v192
	v_rcp_iflag_f32_e32 v12, v12
	v_and_b32_e32 v5, 0xffff0000, v192
	v_add_f32_e32 v2, v2, v4
	v_add_f32_e32 v3, v3, v5
	v_fma_f32 v13, v12, v2, -v4
	v_fma_f32 v12, v12, v3, -v5
	v_cvt_pk_bf16_f32 v12, v13, v12
	ds_write_b32 v175, v12 offset:34816
	v_add_u32_e32 v12, s1, v136
	v_min_i32_e32 v12, 3, v12
	v_add_u32_e32 v12, 1, v12
	v_cvt_f32_i32_e32 v12, v12
	v_sub_f32_e32 v2, v2, v6
	v_sub_f32_e32 v3, v3, v7
	v_lshlrev_b32_e32 v6, 16, v190
	v_rcp_iflag_f32_e32 v12, v12
	v_and_b32_e32 v7, 0xffff0000, v190
	v_add_f32_e32 v2, v2, v6
	v_add_f32_e32 v3, v3, v7
	v_fma_f32 v13, v12, v2, -v6
	v_fma_f32 v12, v12, v3, -v7
	v_cvt_pk_bf16_f32 v12, v13, v12
	ds_write_b32 v176, v12 offset:34816
	v_add_u32_e32 v12, s1, v137
	v_min_i32_e32 v12, 3, v12
	v_add_u32_e32 v12, 1, v12
	v_cvt_f32_i32_e32 v12, v12
	v_sub_f32_e32 v2, v2, v8
	v_sub_f32_e32 v3, v3, v9
	v_lshlrev_b32_e32 v8, 16, v189
	v_rcp_iflag_f32_e32 v12, v12
	v_and_b32_e32 v9, 0xffff0000, v189
	v_add_f32_e32 v2, v2, v8
	v_add_f32_e32 v3, v3, v9
	v_fma_f32 v13, v12, v2, -v8
	v_fma_f32 v12, v12, v3, -v9
	v_cvt_pk_bf16_f32 v12, v13, v12
	ds_write_b32 v177, v12 offset:34816
	v_add_u32_e32 v12, s1, v138
	v_min_i32_e32 v12, 3, v12
	v_add_u32_e32 v12, 1, v12
	v_cvt_f32_i32_e32 v12, v12
	v_sub_f32_e32 v2, v2, v10
	v_lshlrev_b32_e32 v10, 16, v188
	v_sub_f32_e32 v3, v3, v11
	v_rcp_iflag_f32_e32 v12, v12
	v_and_b32_e32 v11, 0xffff0000, v188
	v_add_f32_e32 v2, v2, v10
	v_add_f32_e32 v3, v3, v11
	v_fma_f32 v10, v12, v2, -v10
	v_fma_f32 v11, v12, v3, -v11
	v_cvt_pk_bf16_f32 v10, v10, v11
	ds_write_b32 v178, v10 offset:34816
	v_add_u32_e32 v10, s1, v139
	v_min_i32_e32 v10, 3, v10
	v_add_u32_e32 v10, 1, v10
	v_cvt_f32_i32_e32 v10, v10
	v_sub_f32_e32 v2, v2, v4
	v_lshlrev_b32_e32 v4, 16, v187
	v_add_f32_e32 v2, v2, v4
	v_rcp_iflag_f32_e32 v10, v10
	v_sub_f32_e32 v3, v3, v5
	v_and_b32_e32 v5, 0xffff0000, v187
	v_add_f32_e32 v3, v3, v5
	v_fma_f32 v4, v10, v2, -v4
	v_sub_f32_e32 v2, v2, v6
	v_add_u32_e32 v6, s1, v140
	v_min_i32_e32 v6, 3, v6
	v_add_u32_e32 v6, 1, v6
	v_cvt_f32_i32_e32 v6, v6
	v_fma_f32 v5, v10, v3, -v5
	v_cvt_pk_bf16_f32 v4, v4, v5
	ds_write_b32 v179, v4 offset:34816
	v_rcp_iflag_f32_e32 v6, v6
	v_sub_f32_e32 v3, v3, v7
	v_lshlrev_b32_e32 v4, 16, v186
	v_and_b32_e32 v5, 0xffff0000, v186
	v_add_f32_e32 v2, v2, v4
	v_add_f32_e32 v3, v3, v5
	v_fma_f32 v4, v6, v2, -v4
	v_fma_f32 v5, v6, v3, -v5
	v_add_u32_e32 v6, s1, v141
	v_min_i32_e32 v6, 3, v6
	v_add_u32_e32 v6, 1, v6
	v_cvt_f32_i32_e32 v6, v6
	v_cvt_pk_bf16_f32 v4, v4, v5
	ds_write_b32 v180, v4 offset:34816
	v_sub_f32_e32 v2, v2, v8
	v_rcp_iflag_f32_e32 v6, v6
	v_lshlrev_b32_e32 v4, 16, v182
	v_sub_f32_e32 v3, v3, v9
	v_and_b32_e32 v5, 0xffff0000, v182
	v_add_f32_e32 v2, v2, v4
	v_add_f32_e32 v3, v3, v5
	v_fma_f32 v2, v6, v2, -v4
	v_fma_f32 v3, v6, v3, -v5
	v_cvt_pk_bf16_f32 v2, v2, v3
	ds_write_b32 v181, v2 offset:34816
	v_add_u32_e32 v2, s0, v142
	v_ashrrev_i32_e32 v3, 31, v2
	v_lshlrev_b64 v[2:3], 12, v[2:3]
	s_waitcnt lgkmcnt(0)
	s_barrier
	v_lshl_add_u64 v[2:3], s[70:71], 0, v[2:3]
	ds_read_b128 v[74:77], v185 offset:34816
	ds_read_b128 v[78:81], v185 offset:34848
	ds_read_b128 v[70:73], v185 offset:34880
	ds_read_b128 v[66:69], v185 offset:34912
	ds_read_b128 v[62:65], v185 offset:34944
	ds_read_b128 v[58:61], v185 offset:34976
	ds_read_b128 v[54:57], v185 offset:35008
	ds_read_b128 v[50:53], v185 offset:35040
	v_lshl_add_u64 v[106:107], v[2:3], 0, s[2:3]
	ds_read_b128 v[2:5], v184
	ds_read_b128 v[168:171], v184 offset:32
	ds_read_b128 v[228:231], v184 offset:64
	ds_read_b128 v[242:245], v184 offset:96
	s_waitcnt lgkmcnt(3)
	v_mfma_f32_32x32x16_bf16 v[2:17], v[2:5], v[74:77], 0
	s_waitcnt lgkmcnt(2)
	v_mfma_f32_32x32x16_bf16 v[2:17], v[168:171], v[78:81], v[2:17]
	ds_read_b128 v[168:171], v184 offset:128
	s_waitcnt lgkmcnt(2)
	v_mfma_f32_32x32x16_bf16 v[2:17], v[228:231], v[70:73], v[2:17]
	ds_read_b128 v[228:231], v184 offset:160
	s_waitcnt lgkmcnt(2)
	v_mfma_f32_32x32x16_bf16 v[2:17], v[242:245], v[66:69], v[2:17]
	ds_read_b128 v[242:245], v184 offset:192
	s_waitcnt lgkmcnt(2)
	v_mfma_f32_32x32x16_bf16 v[2:17], v[168:171], v[62:65], v[2:17]
	ds_read_b128 v[168:171], v184 offset:224
	s_waitcnt lgkmcnt(2)
	v_mfma_f32_32x32x16_bf16 v[2:17], v[228:231], v[58:61], v[2:17]
	s_waitcnt lgkmcnt(1)
	v_mfma_f32_32x32x16_bf16 v[2:17], v[242:245], v[54:57], v[2:17]
	s_waitcnt lgkmcnt(0)
	v_mfma_f32_32x32x16_bf16 v[2:17], v[168:171], v[50:53], v[2:17]
	s_nop 11
	v_mul_f32_e32 v2, v46, v2
	v_mul_f32_e32 v3, v47, v3
	v_cvt_pk_bf16_f32 v2, v2, v3
	v_mul_f32_e32 v3, v48, v4
	v_mul_f32_e32 v4, v49, v5
	v_cvt_pk_bf16_f32 v3, v3, v4
	v_lshl_add_u64 v[4:5], v[106:107], 0, v[0:1]
	global_store_dwordx2 v[4:5], v[2:3], off
	v_mul_f32_e32 v0, v42, v6
	v_mul_f32_e32 v2, v43, v7
	v_mul_f32_e32 v3, v45, v9
	v_cvt_pk_bf16_f32 v2, v0, v2
	v_mul_f32_e32 v0, v44, v8
	v_cvt_pk_bf16_f32 v3, v0, v3
	v_lshl_add_u64 v[4:5], v[106:107], 0, v[104:105]
	global_store_dwordx2 v[4:5], v[2:3], off
	v_mul_f32_e32 v0, v38, v10
	v_mul_f32_e32 v2, v39, v11
	v_mul_f32_e32 v3, v41, v13
	v_cvt_pk_bf16_f32 v2, v0, v2
	v_mul_f32_e32 v0, v40, v12
	v_cvt_pk_bf16_f32 v3, v0, v3
	v_lshl_add_u64 v[4:5], v[106:107], 0, v[108:109]
	global_store_dwordx2 v[4:5], v[2:3], off
	v_mul_f32_e32 v0, v34, v14
	v_mul_f32_e32 v2, v35, v15
	v_mul_f32_e32 v3, v37, v17
	v_lshl_add_u64 v[4:5], v[106:107], 0, v[102:103]
	v_cvt_pk_bf16_f32 v2, v0, v2
	v_mul_f32_e32 v0, v36, v16
	v_cvt_pk_bf16_f32 v3, v0, v3
	global_store_dwordx2 v[4:5], v[2:3], off
	ds_read_b128 v[2:5], v183
	ds_read_b128 v[34:37], v183 offset:32
	ds_read_b128 v[228:231], v183 offset:64
	ds_read_b128 v[242:245], v183 offset:96
	s_waitcnt lgkmcnt(3)
	v_mfma_f32_32x32x16_bf16 v[2:17], v[2:5], v[74:77], 0
	s_waitcnt lgkmcnt(2)
	v_mfma_f32_32x32x16_bf16 v[2:17], v[34:37], v[78:81], v[2:17]
	ds_read_b128 v[34:37], v183 offset:128
	s_waitcnt lgkmcnt(2)
	v_mfma_f32_32x32x16_bf16 v[2:17], v[228:231], v[70:73], v[2:17]
	ds_read_b128 v[228:231], v183 offset:160
	s_waitcnt lgkmcnt(2)
	v_mfma_f32_32x32x16_bf16 v[2:17], v[242:245], v[66:69], v[2:17]
	ds_read_b128 v[242:245], v183 offset:192
	s_waitcnt lgkmcnt(2)
	v_mfma_f32_32x32x16_bf16 v[2:17], v[34:37], v[62:65], v[2:17]
	ds_read_b128 v[34:37], v183 offset:224
	s_waitcnt lgkmcnt(2)
	v_mfma_f32_32x32x16_bf16 v[2:17], v[228:231], v[58:61], v[2:17]
	s_waitcnt lgkmcnt(1)
	v_mfma_f32_32x32x16_bf16 v[2:17], v[242:245], v[54:57], v[2:17]
	s_waitcnt lgkmcnt(0)
	v_mfma_f32_32x32x16_bf16 v[2:17], v[34:37], v[50:53], v[2:17]
	s_nop 11
	v_mul_f32_e32 v0, v30, v2
	v_mul_f32_e32 v2, v31, v3
	v_mul_f32_e32 v3, v33, v5
	v_cvt_pk_bf16_f32 v2, v0, v2
	v_mul_f32_e32 v0, v32, v4
	v_cvt_pk_bf16_f32 v3, v0, v3
	v_lshl_add_u64 v[4:5], v[106:107], 0, v[110:111]
	global_store_dwordx2 v[4:5], v[2:3], off
	v_mul_f32_e32 v0, v26, v6
	v_mul_f32_e32 v2, v27, v7
	v_mul_f32_e32 v3, v29, v9
	v_cvt_pk_bf16_f32 v2, v0, v2
	v_mul_f32_e32 v0, v28, v8
	v_cvt_pk_bf16_f32 v3, v0, v3
	v_lshl_add_u64 v[4:5], v[106:107], 0, v[112:113]
	global_store_dwordx2 v[4:5], v[2:3], off
	v_mul_f32_e32 v0, v22, v10
	v_mul_f32_e32 v2, v23, v11
	v_mul_f32_e32 v3, v25, v13
	v_cvt_pk_bf16_f32 v2, v0, v2
	v_mul_f32_e32 v0, v24, v12
	v_cvt_pk_bf16_f32 v3, v0, v3
	v_lshl_add_u64 v[4:5], v[106:107], 0, v[114:115]
	global_store_dwordx2 v[4:5], v[2:3], off
	v_mul_f32_e32 v0, v18, v14
	v_mul_f32_e32 v2, v19, v15
	v_mul_f32_e32 v3, v21, v17
	v_cvt_pk_bf16_f32 v2, v0, v2
	v_mul_f32_e32 v0, v20, v16
	v_cvt_pk_bf16_f32 v3, v0, v3

.LBB0_215:
	s_or_b64 exec, exec, s[84:85]
	s_waitcnt vmcnt(38)
	v_cndmask_b32_e64 v4, 0, v4, s[8:9]
	s_waitcnt vmcnt(37)
	v_cndmask_b32_e64 v5, 0, v5, s[10:11]
	v_lshlrev_b32_e32 v71, 16, v4
	v_and_b32_e32 v72, 0xffff0000, v4
	s_waitcnt vmcnt(28)
	v_cndmask_b32_e64 v70, 0, v51, s[2:3]
	v_cndmask_b32_e64 v7, 0, v7, s[12:13]
	v_add_f32_e32 v51, 0, v71
	v_add_f32_e32 v4, 0, v72
	v_lshlrev_b32_e32 v73, 16, v5
	v_and_b32_e32 v74, 0xffff0000, v5
	v_cndmask_b32_e64 v8, 0, v8, s[14:15]
	v_add_f32_e32 v51, v51, v73
	v_add_f32_e32 v4, v4, v74
	v_lshlrev_b32_e32 v75, 16, v7
	v_and_b32_e32 v76, 0xffff0000, v7
	v_cndmask_b32_e64 v10, 0, v10, s[16:17]
	v_add_f32_e32 v5, v51, v75
	v_add_f32_e32 v4, v4, v76
	v_lshlrev_b32_e32 v77, 16, v8
	v_and_b32_e32 v78, 0xffff0000, v8
	v_cndmask_b32_e64 v11, 0, v11, s[18:19]
	v_add_f32_e32 v5, v5, v77
	v_add_f32_e32 v4, v4, v78
	v_lshlrev_b32_e32 v79, 16, v10
	v_and_b32_e32 v80, 0xffff0000, v10
	v_cndmask_b32_e64 v13, 0, v13, s[20:21]
	v_add_f32_e32 v5, v5, v79
	v_add_f32_e32 v4, v4, v80
	v_lshlrev_b32_e32 v81, 16, v11
	v_and_b32_e32 v103, 0xffff0000, v11
	s_waitcnt vmcnt(27)
	v_cndmask_b32_e64 v69, 0, v52, s[6:7]
	v_cndmask_b32_e64 v14, 0, v14, s[22:23]
	v_add_f32_e32 v5, v5, v81
	v_add_f32_e32 v4, v4, v103
	v_lshlrev_b32_e32 v104, 16, v13
	v_and_b32_e32 v105, 0xffff0000, v13
	s_waitcnt vmcnt(8)
	v_cndmask_b32_e64 v0, 0, v65, s[62:63]
	v_cndmask_b32_e64 v65, 0, v57, s[68:69]
	v_cndmask_b32_e64 v66, 0, v56, s[28:29]
	v_cndmask_b32_e32 v16, 0, v16, vcc
	v_add_f32_e32 v5, v5, v104
	v_add_f32_e32 v4, v4, v105
	v_lshlrev_b32_e32 v56, 16, v14
	v_and_b32_e32 v57, 0xffff0000, v14
	v_lshlrev_b32_e32 v13, 16, v69
	v_and_b32_e32 v14, 0xffff0000, v69
	v_add_u32_e32 v69, s95, v83
	v_cndmask_b32_e64 v67, 0, v54, s[26:27]
	v_cndmask_b32_e64 v68, 0, v53, s[24:25]
	v_cndmask_b32_e64 v17, 0, v17, s[0:1]
	v_add_f32_e32 v5, v5, v56
	v_add_f32_e32 v4, v4, v57
	v_lshlrev_b32_e32 v53, 16, v16
	v_and_b32_e32 v54, 0xffff0000, v16
	v_min_i32_e32 v69, 15, v69
	v_add_f32_e32 v5, v5, v53
	v_add_f32_e32 v4, v4, v54
	v_lshlrev_b32_e32 v51, 16, v17
	v_and_b32_e32 v52, 0xffff0000, v17
	v_add_u32_e32 v69, 1, v69
	v_add_f32_e32 v5, v5, v51
	v_add_f32_e32 v4, v4, v52
	v_lshlrev_b32_e32 v16, 16, v70
	v_and_b32_e32 v17, 0xffff0000, v70
	v_cvt_f32_i32_e32 v69, v69
	v_add_f32_e32 v5, v5, v16
	v_add_f32_e32 v4, v4, v17
	v_add_f32_e32 v5, v5, v13
	v_add_f32_e32 v4, v4, v14
	v_lshlrev_b32_e32 v10, 16, v68
	v_and_b32_e32 v11, 0xffff0000, v68
	v_add_f32_e32 v5, v5, v10
	v_add_f32_e32 v4, v4, v11
	v_lshlrev_b32_e32 v7, 16, v67
	v_and_b32_e32 v8, 0xffff0000, v67
	v_add_f32_e32 v5, v5, v7
	v_add_f32_e32 v67, v4, v8
	v_lshlrev_b32_e32 v4, 16, v66
	v_rcp_iflag_f32_e32 v69, v69
	v_add_f32_e32 v68, v5, v4
	v_and_b32_e32 v5, 0xffff0000, v66
	v_add_f32_e32 v66, v67, v5
	v_lshlrev_b32_e32 v67, 16, v65
	v_and_b32_e32 v65, 0xffff0000, v65
	v_add_f32_e32 v66, v66, v65
	v_add_f32_e32 v68, v68, v67
	v_fma_f32 v65, v69, v66, -v65
	v_fma_f32 v67, v69, v68, -v67
	v_cvt_pk_bf16_f32 v65, v67, v65
	v_add_u32_e32 v116, 0, v145
	s_waitcnt lgkmcnt(0)
	s_barrier
	ds_write_b32 v116, v65 offset:34816
	v_sub_f32_e32 v65, v68, v71
	v_add_u32_e32 v68, s95, v127
	v_min_i32_e32 v68, 15, v68
	v_add_u32_e32 v68, 1, v68
	v_cvt_f32_i32_e32 v68, v68
	v_cndmask_b32_e64 v59, v59, 0, s[34:35]
	v_sub_f32_e32 v66, v66, v72
	v_lshlrev_b32_e32 v67, 16, v59
	v_rcp_iflag_f32_e32 v68, v68
	v_and_b32_e32 v59, 0xffff0000, v59
	v_add_f32_e32 v65, v65, v67
	v_add_f32_e32 v66, v66, v59
	v_fma_f32 v67, v68, v65, -v67
	v_fma_f32 v59, v68, v66, -v59
	v_cvt_pk_bf16_f32 v59, v67, v59
	v_add_u32_e32 v67, s95, v128
	v_min_i32_e32 v67, 15, v67
	v_add_u32_e32 v67, 1, v67
	v_cvt_f32_i32_e32 v67, v67
	v_cndmask_b32_e64 v60, 0, v60, s[36:37]
	v_add_u32_e32 v117, 0, v146
	ds_write_b32 v117, v59 offset:34816
	v_rcp_iflag_f32_e32 v67, v67
	v_sub_f32_e32 v59, v65, v73
	v_sub_f32_e32 v65, v66, v74
	v_lshlrev_b32_e32 v66, 16, v60
	v_and_b32_e32 v60, 0xffff0000, v60
	v_add_f32_e32 v59, v59, v66
	v_add_f32_e32 v65, v65, v60
	v_fma_f32 v66, v67, v59, -v66
	v_fma_f32 v60, v67, v65, -v60
	v_cvt_pk_bf16_f32 v60, v66, v60
	v_add_u32_e32 v66, s95, v129
	v_min_i32_e32 v66, 15, v66
	v_add_u32_e32 v66, 1, v66
	v_cvt_f32_i32_e32 v66, v66
	v_cndmask_b32_e64 v61, 0, v61, s[38:39]
	v_add_u32_e32 v168, 0, v147
	ds_write_b32 v168, v60 offset:34816
	v_rcp_iflag_f32_e32 v66, v66
	v_sub_f32_e32 v59, v59, v75
	v_sub_f32_e32 v60, v65, v76
	v_lshlrev_b32_e32 v65, 16, v61
	v_and_b32_e32 v61, 0xffff0000, v61
	v_add_f32_e32 v59, v59, v65
	v_add_f32_e32 v60, v60, v61
	v_fma_f32 v65, v66, v59, -v65
	v_fma_f32 v61, v66, v60, -v61
	v_cvt_pk_bf16_f32 v61, v65, v61
	v_add_u32_e32 v65, s95, v130
	v_min_i32_e32 v65, 15, v65
	v_add_u32_e32 v65, 1, v65
	v_cvt_f32_i32_e32 v65, v65
	v_cndmask_b32_e64 v62, 0, v62, s[40:41]
	v_add_u32_e32 v169, 0, v148
	ds_write_b32 v169, v61 offset:34816
	v_rcp_iflag_f32_e32 v65, v65
	v_sub_f32_e32 v59, v59, v77
	v_lshlrev_b32_e32 v61, 16, v62
	v_sub_f32_e32 v60, v60, v78
	v_and_b32_e32 v62, 0xffff0000, v62
	v_add_f32_e32 v59, v59, v61
	v_add_f32_e32 v60, v60, v62
	v_fma_f32 v61, v65, v59, -v61
	v_cndmask_b32_e64 v63, 0, v63, s[42:43]
	v_fma_f32 v62, v65, v60, -v62
	v_cvt_pk_bf16_f32 v61, v61, v62
	v_add_u32_e32 v170, 0, v149
	ds_write_b32 v170, v61 offset:34816
	v_lshlrev_b32_e32 v61, 16, v63
	v_and_b32_e32 v62, 0xffff0000, v63
	v_add_u32_e32 v63, s95, v131
	v_min_i32_e32 v63, 15, v63
	v_add_u32_e32 v63, 1, v63
	v_cvt_f32_i32_e32 v63, v63
	v_sub_f32_e32 v59, v59, v79
	v_sub_f32_e32 v60, v60, v80
	v_add_f32_e32 v59, v59, v61
	v_rcp_iflag_f32_e32 v63, v63
	v_add_f32_e32 v60, v60, v62
	v_cndmask_b32_e64 v64, 0, v64, s[44:45]
	v_add_u32_e32 v171, 0, v150
	v_fma_f32 v61, v63, v59, -v61
	v_fma_f32 v62, v63, v60, -v62
	v_add_u32_e32 v63, s95, v132
	v_min_i32_e32 v63, 15, v63
	v_add_u32_e32 v63, 1, v63
	v_cvt_f32_i32_e32 v63, v63
	v_cvt_pk_bf16_f32 v61, v61, v62
	ds_write_b32 v171, v61 offset:34816
	v_sub_f32_e32 v59, v59, v81
	v_rcp_iflag_f32_e32 v63, v63
	v_sub_f32_e32 v60, v60, v103
	v_lshlrev_b32_e32 v61, 16, v64
	v_and_b32_e32 v62, 0xffff0000, v64
	v_add_f32_e32 v59, v59, v61
	v_add_f32_e32 v60, v60, v62
	v_fma_f32 v61, v63, v59, -v61
	v_fma_f32 v62, v63, v60, -v62
	v_cvt_pk_bf16_f32 v61, v61, v62
	v_add_u32_e32 v62, s95, v133
	v_min_i32_e32 v62, 15, v62
	v_add_u32_e32 v62, 1, v62
	v_cvt_f32_i32_e32 v62, v62
	v_cndmask_b32_e64 v58, 0, v58, s[46:47]
	v_add_u32_e32 v172, 0, v151
	ds_write_b32 v172, v61 offset:34816
	v_rcp_iflag_f32_e32 v62, v62
	v_sub_f32_e32 v59, v59, v104
	v_lshlrev_b32_e32 v61, 16, v58
	v_add_f32_e32 v59, v59, v61
	v_fma_f32 v61, v62, v59, -v61
	v_sub_f32_e32 v56, v59, v56
	v_add_u32_e32 v59, s95, v134
	v_min_i32_e32 v59, 15, v59
	v_add_u32_e32 v59, 1, v59
	v_cvt_f32_i32_e32 v59, v59
	v_sub_f32_e32 v60, v60, v105
	v_and_b32_e32 v58, 0xffff0000, v58
	v_add_f32_e32 v60, v60, v58
	v_fma_f32 v58, v62, v60, -v58
	v_rcp_iflag_f32_e32 v59, v59
	v_cndmask_b32_e64 v55, 0, v55, s[48:49]
	v_cvt_pk_bf16_f32 v58, v61, v58
	v_add_u32_e32 v173, 0, v152
	ds_write_b32 v173, v58 offset:34816
	v_lshlrev_b32_e32 v58, 16, v55
	v_add_f32_e32 v56, v56, v58
	v_fma_f32 v58, v59, v56, -v58
	v_sub_f32_e32 v53, v56, v53
	v_add_u32_e32 v56, s95, v135
	v_min_i32_e32 v56, 15, v56
	v_add_u32_e32 v56, 1, v56
	v_cvt_f32_i32_e32 v56, v56
	v_sub_f32_e32 v57, v60, v57
	v_and_b32_e32 v55, 0xffff0000, v55
	v_add_f32_e32 v57, v57, v55
	v_fma_f32 v55, v59, v57, -v55
	v_rcp_iflag_f32_e32 v56, v56
	v_cndmask_b32_e64 v50, 0, v50, s[50:51]
	v_cvt_pk_bf16_f32 v55, v58, v55
	v_add_u32_e32 v174, 0, v153
	ds_write_b32 v174, v55 offset:34816
	v_sub_f32_e32 v54, v57, v54
	v_lshlrev_b32_e32 v55, 16, v50
	v_and_b32_e32 v50, 0xffff0000, v50
	v_add_f32_e32 v54, v54, v50
	v_add_f32_e32 v53, v53, v55
	v_fma_f32 v50, v56, v54, -v50
	v_fma_f32 v55, v56, v53, -v55
	v_cvt_pk_bf16_f32 v50, v55, v50
	v_add_u32_e32 v175, 0, v154
	ds_write_b32 v175, v50 offset:34816
	v_sub_f32_e32 v50, v53, v51
	v_add_u32_e32 v53, s95, v136
	v_min_i32_e32 v53, 15, v53
	v_add_u32_e32 v53, 1, v53
	v_cvt_f32_i32_e32 v53, v53
	v_cndmask_b32_e64 v15, 0, v15, s[52:53]
	v_sub_f32_e32 v51, v54, v52
	v_lshlrev_b32_e32 v52, 16, v15
	v_rcp_iflag_f32_e32 v53, v53
	v_and_b32_e32 v15, 0xffff0000, v15
	v_add_f32_e32 v51, v51, v15
	v_add_f32_e32 v50, v50, v52
	v_fma_f32 v15, v53, v51, -v15
	v_fma_f32 v52, v53, v50, -v52
	v_cvt_pk_bf16_f32 v15, v52, v15
	v_add_u32_e32 v176, 0, v155
	ds_write_b32 v176, v15 offset:34816
	v_sub_f32_e32 v15, v50, v16
	v_add_u32_e32 v50, s95, v137
	v_min_i32_e32 v50, 15, v50
	v_add_u32_e32 v50, 1, v50
	v_cvt_f32_i32_e32 v50, v50
	v_cndmask_b32_e64 v12, 0, v12, s[54:55]
	v_sub_f32_e32 v16, v51, v17
	v_lshlrev_b32_e32 v17, 16, v12
	v_rcp_iflag_f32_e32 v50, v50
	v_and_b32_e32 v12, 0xffff0000, v12
	v_add_f32_e32 v16, v16, v12
	v_add_f32_e32 v15, v15, v17
	v_fma_f32 v12, v50, v16, -v12
	v_fma_f32 v17, v50, v15, -v17
	v_cvt_pk_bf16_f32 v12, v17, v12
	v_add_u32_e32 v177, 0, v156
	ds_write_b32 v177, v12 offset:34816
	v_sub_f32_e32 v12, v15, v13
	v_add_u32_e32 v15, s95, v138
	v_min_i32_e32 v15, 15, v15
	v_add_u32_e32 v15, 1, v15
	v_cvt_f32_i32_e32 v15, v15
	v_cndmask_b32_e64 v9, 0, v9, s[56:57]
	v_sub_f32_e32 v13, v16, v14
	v_lshlrev_b32_e32 v14, 16, v9
	v_rcp_iflag_f32_e32 v15, v15
	v_and_b32_e32 v9, 0xffff0000, v9
	v_add_f32_e32 v13, v13, v9
	v_add_f32_e32 v12, v12, v14
	v_fma_f32 v9, v15, v13, -v9
	v_fma_f32 v14, v15, v12, -v14
	v_cvt_pk_bf16_f32 v9, v14, v9
	v_add_u32_e32 v178, 0, v157
	ds_write_b32 v178, v9 offset:34816
	v_sub_f32_e32 v9, v12, v10
	v_add_u32_e32 v12, s95, v139
	v_min_i32_e32 v12, 15, v12
	v_add_u32_e32 v12, 1, v12
	v_cvt_f32_i32_e32 v12, v12
	v_cndmask_b32_e64 v6, 0, v6, s[58:59]
	v_sub_f32_e32 v10, v13, v11
	v_lshlrev_b32_e32 v11, 16, v6
	v_rcp_iflag_f32_e32 v12, v12
	v_and_b32_e32 v6, 0xffff0000, v6
	v_add_f32_e32 v10, v10, v6
	v_add_f32_e32 v9, v9, v11
	v_fma_f32 v6, v12, v10, -v6
	v_fma_f32 v11, v12, v9, -v11
	v_cvt_pk_bf16_f32 v6, v11, v6
	v_add_u32_e32 v179, 0, v158
	ds_write_b32 v179, v6 offset:34816
	v_sub_f32_e32 v6, v9, v7
	v_add_u32_e32 v9, s95, v140
	v_min_i32_e32 v9, 15, v9
	v_add_u32_e32 v9, 1, v9
	v_cvt_f32_i32_e32 v9, v9
	v_cndmask_b32_e64 v3, 0, v3, s[60:61]
	v_sub_f32_e32 v7, v10, v8
	v_lshlrev_b32_e32 v8, 16, v3
	v_rcp_iflag_f32_e32 v9, v9
	v_and_b32_e32 v3, 0xffff0000, v3
	v_add_f32_e32 v7, v7, v3
	v_add_f32_e32 v6, v6, v8
	v_fma_f32 v3, v9, v7, -v3
	v_fma_f32 v8, v9, v6, -v8
	v_cvt_pk_bf16_f32 v3, v8, v3
	v_add_u32_e32 v180, 0, v159
	ds_write_b32 v180, v3 offset:34816
	v_sub_f32_e32 v3, v6, v4
	v_add_u32_e32 v6, s95, v141
	v_min_i32_e32 v6, 15, v6
	v_add_u32_e32 v6, 1, v6
	v_cvt_f32_i32_e32 v6, v6
	v_sub_f32_e32 v4, v7, v5
	v_lshlrev_b32_e32 v5, 16, v0
	v_and_b32_e32 v0, 0xffff0000, v0
	v_rcp_iflag_f32_e32 v6, v6
	s_or_b32 s0, s94, 0x80
	v_add_f32_e32 v3, v3, v5
	v_add_f32_e32 v4, v4, v0
	s_xor_b32 s1, s95, 0xffffff7f
	s_mul_i32 s2, s0, 0x1e00
	v_fma_f32 v3, v6, v3, -v5
	v_fma_f32 v0, v6, v4, -v0
	s_mul_hi_i32 s3, s0, 0x1e00
	s_add_u32 s2, s91, s2
	v_cvt_pk_bf16_f32 v0, v3, v0
	s_addc_u32 s3, s92, s3
	v_mov_b32_e32 v3, v1
	v_add_u32_e32 v181, 0, v160
	v_cmp_lt_i32_e32 vcc, s1, v141
	v_lshl_add_u64 v[2:3], s[2:3], 0, v[2:3]
	s_mov_b64 s[2:3], 0x1720
	ds_write_b32 v181, v0 offset:34816
	v_lshl_add_u64 v[2:3], v[2:3], 0, s[2:3]
	v_cndmask_b32_e32 v0, 0, v141, vcc
	s_movk_i32 s6, 0x1e00
	v_mad_i64_i32 v[4:5], s[2:3], v0, s6, v[2:3]
	global_load_dword v0, v[4:5], off
	v_add_u32_e32 v185, v144, v143
	v_add_u32_e32 v183, v144, v161
	v_lshlrev_b32_e32 v104, 1, v90
	v_mov_b32_e32 v105, v1
	v_mov_b32_e32 v103, v1
	v_add_u32_e32 v184, v144, v163
	v_lshlrev_b32_e32 v114, 1, v98
	v_mov_b32_e32 v115, v1
	v_readlane_b32 s56, v253, 1
	s_mov_b64 s[8:9], 0
	v_readlane_b32 s58, v253, 3
	s_movk_i32 s56, 0x5ff
	s_mov_b32 s61, 0xf800000
	v_readlane_b32 s57, v253, 2
	v_readlane_b32 s59, v253, 4
	s_waitcnt vmcnt(0)
	v_cndmask_b32_e32 v182, 0, v0, vcc
	v_cmp_lt_i32_e32 vcc, s1, v85
	v_mov_b32_e32 v209, 0
	s_nop 0
	v_cndmask_b32_e32 v0, 0, v85, vcc
	v_mad_i64_i32 v[4:5], s[2:3], v0, s6, v[2:3]
	s_and_saveexec_b64 s[98:99], vcc
	global_load_dword v209, v[4:5], off
	s_mov_b64 exec, s[98:99]
	v_cmp_lt_i32_e32 vcc, s1, v91
	v_mov_b32_e32 v211, 0
	s_nop 0
	v_cndmask_b32_e32 v0, 0, v91, vcc
	v_mad_i64_i32 v[4:5], s[2:3], v0, s6, v[2:3]
	s_and_saveexec_b64 s[98:99], vcc
	global_load_dword v211, v[4:5], off
	s_mov_b64 exec, s[98:99]
	v_cmp_lt_i32_e32 vcc, s1, v93
	v_mov_b32_e32 v212, 0
	s_nop 0
	v_cndmask_b32_e32 v0, 0, v93, vcc
	v_mad_i64_i32 v[4:5], s[2:3], v0, s6, v[2:3]
	s_and_saveexec_b64 s[98:99], vcc
	global_load_dword v212, v[4:5], off
	s_mov_b64 exec, s[98:99]
	v_cmp_lt_i32_e32 vcc, s1, v95
	v_mov_b32_e32 v213, 0
	s_nop 0
	v_cndmask_b32_e32 v0, 0, v95, vcc
	v_mad_i64_i32 v[4:5], s[2:3], v0, s6, v[2:3]
	s_and_saveexec_b64 s[98:99], vcc
	global_load_dword v213, v[4:5], off
	s_mov_b64 exec, s[98:99]
	v_cmp_lt_i32_e32 vcc, s1, v97
	v_mov_b32_e32 v214, 0
	s_nop 0
	v_cndmask_b32_e32 v0, 0, v97, vcc
	v_mad_i64_i32 v[4:5], s[2:3], v0, s6, v[2:3]
	s_and_saveexec_b64 s[98:99], vcc
	global_load_dword v214, v[4:5], off
	s_mov_b64 exec, s[98:99]
	v_cmp_lt_i32_e32 vcc, s1, v99
	v_mov_b32_e32 v215, 0
	s_nop 0
	v_cndmask_b32_e32 v0, 0, v99, vcc
	v_mad_i64_i32 v[4:5], s[2:3], v0, s6, v[2:3]
	s_and_saveexec_b64 s[98:99], vcc
	global_load_dword v215, v[4:5], off
	s_mov_b64 exec, s[98:99]
	v_cmp_lt_i32_e32 vcc, s1, v101
	v_mov_b32_e32 v217, 0
	s_nop 0
	v_cndmask_b32_e32 v0, 0, v101, vcc
	v_mad_i64_i32 v[4:5], s[2:3], v0, s6, v[2:3]
	s_and_saveexec_b64 s[98:99], vcc
	global_load_dword v217, v[4:5], off
	s_mov_b64 exec, s[98:99]
	v_cmp_lt_i32_e32 vcc, s1, v119
	v_mov_b32_e32 v218, 0
	s_nop 0
	v_cndmask_b32_e32 v0, 0, v119, vcc
	v_mad_i64_i32 v[4:5], s[2:3], v0, s6, v[2:3]
	s_and_saveexec_b64 s[98:99], vcc
	global_load_dword v218, v[4:5], off
	s_mov_b64 exec, s[98:99]
	v_cmp_lt_i32_e32 vcc, s1, v120
	v_mov_b32_e32 v219, 0
	s_nop 0
	v_cndmask_b32_e32 v0, 0, v120, vcc
	v_mad_i64_i32 v[4:5], s[2:3], v0, s6, v[2:3]
	s_and_saveexec_b64 s[98:99], vcc
	global_load_dword v219, v[4:5], off
	s_mov_b64 exec, s[98:99]
	v_cmp_lt_i32_e32 vcc, s1, v121
	v_mov_b32_e32 v220, 0
	s_nop 0
	v_cndmask_b32_e32 v0, 0, v121, vcc
	v_mad_i64_i32 v[4:5], s[2:3], v0, s6, v[2:3]
	s_and_saveexec_b64 s[98:99], vcc
	global_load_dword v220, v[4:5], off
	s_mov_b64 exec, s[98:99]
	v_cmp_lt_i32_e32 vcc, s1, v122
	v_mov_b32_e32 v221, 0
	s_nop 0
	v_cndmask_b32_e32 v0, 0, v122, vcc
	v_mad_i64_i32 v[4:5], s[2:3], v0, s6, v[2:3]
	s_and_saveexec_b64 s[98:99], vcc
	global_load_dword v221, v[4:5], off
	s_mov_b64 exec, s[98:99]
	v_cmp_lt_i32_e32 vcc, s1, v123
	v_mov_b32_e32 v223, 0
	s_nop 0
	v_cndmask_b32_e32 v0, 0, v123, vcc
	v_mad_i64_i32 v[4:5], s[2:3], v0, s6, v[2:3]
	s_and_saveexec_b64 s[98:99], vcc
	global_load_dword v223, v[4:5], off
	s_mov_b64 exec, s[98:99]
	v_cmp_lt_i32_e32 vcc, s1, v124
	v_mov_b32_e32 v224, 0
	s_nop 0
	v_cndmask_b32_e32 v0, 0, v124, vcc
	v_mad_i64_i32 v[4:5], s[2:3], v0, s6, v[2:3]
	s_and_saveexec_b64 s[98:99], vcc
	global_load_dword v224, v[4:5], off
	s_mov_b64 exec, s[98:99]
	v_cmp_lt_i32_e32 vcc, s1, v125
	v_mov_b32_e32 v225, 0
	s_nop 0
	v_cndmask_b32_e32 v0, 0, v125, vcc
	v_mad_i64_i32 v[4:5], s[2:3], v0, s6, v[2:3]
	s_and_saveexec_b64 s[98:99], vcc
	global_load_dword v225, v[4:5], off
	s_mov_b64 exec, s[98:99]
	v_cmp_lt_i32_e32 vcc, s1, v126
	v_mov_b32_e32 v227, 0
	s_nop 0
	v_cndmask_b32_e32 v0, 0, v126, vcc
	v_mad_i64_i32 v[4:5], s[2:3], v0, s6, v[2:3]
	s_and_saveexec_b64 s[98:99], vcc
	global_load_dword v227, v[4:5], off
	s_mov_b64 exec, s[98:99]
	v_cmp_lt_i32_e32 vcc, s1, v83
	v_mov_b32_e32 v226, 0
	s_nop 0
	v_cndmask_b32_e32 v0, 0, v83, vcc
	v_mad_i64_i32 v[4:5], s[2:3], v0, s6, v[2:3]
	s_and_saveexec_b64 s[98:99], vcc
	global_load_dword v226, v[4:5], off
	s_mov_b64 exec, s[98:99]
	v_cmp_gt_i32_e32 vcc, s1, v83
	s_nop 1
	v_cndmask_b32_e64 v0, v127, 0, vcc
	v_mad_i64_i32 v[4:5], s[2:3], v0, s6, v[2:3]
	global_load_dword v0, v[4:5], off
	s_waitcnt vmcnt(0)
	v_cndmask_b32_e64 v222, v0, 0, vcc
	v_cmp_lt_i32_e32 vcc, s1, v128
	v_mov_b32_e32 v216, 0
	s_nop 0
	v_cndmask_b32_e32 v0, 0, v128, vcc
	v_mad_i64_i32 v[4:5], s[2:3], v0, s6, v[2:3]
	s_and_saveexec_b64 s[98:99], vcc
	global_load_dword v216, v[4:5], off
	s_mov_b64 exec, s[98:99]
	v_cmp_lt_i32_e32 vcc, s1, v129
	v_mov_b32_e32 v210, 0
	s_nop 0
	v_cndmask_b32_e32 v0, 0, v129, vcc
	v_mad_i64_i32 v[4:5], s[2:3], v0, s6, v[2:3]
	s_and_saveexec_b64 s[98:99], vcc
	global_load_dword v210, v[4:5], off
	s_mov_b64 exec, s[98:99]
	v_cmp_lt_i32_e32 vcc, s1, v130
	v_mov_b32_e32 v208, 0
	s_nop 0
	v_cndmask_b32_e32 v0, 0, v130, vcc
	v_mad_i64_i32 v[4:5], s[2:3], v0, s6, v[2:3]
	s_and_saveexec_b64 s[98:99], vcc
	global_load_dword v208, v[4:5], off
	s_mov_b64 exec, s[98:99]
	v_cmp_lt_i32_e32 vcc, s1, v131
	v_mov_b32_e32 v207, 0
	s_nop 0
	v_cndmask_b32_e32 v0, 0, v131, vcc
	v_mad_i64_i32 v[4:5], s[2:3], v0, s6, v[2:3]
	s_and_saveexec_b64 s[98:99], vcc
	global_load_dword v207, v[4:5], off
	s_mov_b64 exec, s[98:99]
	v_cmp_lt_i32_e32 vcc, s1, v132
	v_mov_b32_e32 v206, 0
	s_nop 0
	v_cndmask_b32_e32 v0, 0, v132, vcc
	v_mad_i64_i32 v[4:5], s[2:3], v0, s6, v[2:3]
	s_and_saveexec_b64 s[98:99], vcc
	global_load_dword v206, v[4:5], off
	s_mov_b64 exec, s[98:99]
	v_cmp_lt_i32_e32 vcc, s1, v133
	v_mov_b32_e32 v205, 0
	s_nop 0
	v_cndmask_b32_e32 v0, 0, v133, vcc
	v_mad_i64_i32 v[4:5], s[2:3], v0, s6, v[2:3]
	s_and_saveexec_b64 s[98:99], vcc
	global_load_dword v205, v[4:5], off
	s_mov_b64 exec, s[98:99]
	v_cmp_lt_i32_e32 vcc, s1, v134
	v_mov_b32_e32 v204, 0
	s_nop 0
	v_cndmask_b32_e32 v0, 0, v134, vcc
	v_mad_i64_i32 v[4:5], s[2:3], v0, s6, v[2:3]
	s_and_saveexec_b64 s[98:99], vcc
	global_load_dword v204, v[4:5], off
	s_mov_b64 exec, s[98:99]
	v_cmp_lt_i32_e32 vcc, s1, v135
	v_mov_b32_e32 v192, 0
	s_nop 0
	v_cndmask_b32_e32 v0, 0, v135, vcc
	v_mad_i64_i32 v[4:5], s[2:3], v0, s6, v[2:3]
	s_and_saveexec_b64 s[98:99], vcc
	global_load_dword v192, v[4:5], off
	s_mov_b64 exec, s[98:99]
	v_cmp_lt_i32_e32 vcc, s1, v136
	v_mov_b32_e32 v190, 0
	s_nop 0
	v_cndmask_b32_e32 v0, 0, v136, vcc
	v_mad_i64_i32 v[4:5], s[2:3], v0, s6, v[2:3]
	s_and_saveexec_b64 s[98:99], vcc
	global_load_dword v190, v[4:5], off
	s_mov_b64 exec, s[98:99]
	v_cmp_lt_i32_e32 vcc, s1, v137
	v_mov_b32_e32 v189, 0
	s_nop 0
	v_cndmask_b32_e32 v0, 0, v137, vcc
	v_mad_i64_i32 v[4:5], s[2:3], v0, s6, v[2:3]
	s_and_saveexec_b64 s[98:99], vcc
	global_load_dword v189, v[4:5], off
	s_mov_b64 exec, s[98:99]
	v_cmp_lt_i32_e32 vcc, s1, v138
	v_mov_b32_e32 v188, 0
	s_nop 0
	v_cndmask_b32_e32 v0, 0, v138, vcc
	v_mad_i64_i32 v[4:5], s[2:3], v0, s6, v[2:3]
	s_and_saveexec_b64 s[98:99], vcc
	global_load_dword v188, v[4:5], off
	s_mov_b64 exec, s[98:99]
	v_cmp_lt_i32_e32 vcc, s1, v139
	v_mov_b32_e32 v187, 0
	s_nop 0
	v_cndmask_b32_e32 v0, 0, v139, vcc
	v_mad_i64_i32 v[4:5], s[2:3], v0, s6, v[2:3]
	s_and_saveexec_b64 s[98:99], vcc
	global_load_dword v187, v[4:5], off
	s_mov_b64 exec, s[98:99]
	v_cmp_lt_i32_e32 vcc, s1, v140
	s_and_b32 s1, s0, 0xf80
	s_nop 0
	v_cndmask_b32_e32 v0, 0, v140, vcc
	v_mad_i64_i32 v[2:3], s[2:3], v0, s6, v[2:3]
	global_load_dword v0, v[2:3], off
	v_add_u32_e32 v2, s94, v142
	v_ashrrev_i32_e32 v3, 31, v2
	v_lshlrev_b64 v[2:3], 12, v[2:3]
	s_waitcnt lgkmcnt(0)
	s_barrier
	v_lshl_add_u64 v[2:3], s[70:71], 0, v[2:3]
	s_mov_b64 s[2:3], 0x26000b00
	ds_read_b128 v[74:77], v185 offset:34816
	ds_read_b128 v[78:81], v185 offset:34848
	ds_read_b128 v[70:73], v185 offset:34880
	ds_read_b128 v[66:69], v185 offset:34912
	ds_read_b128 v[62:65], v185 offset:34944
	ds_read_b128 v[58:61], v185 offset:34976
	ds_read_b128 v[54:57], v185 offset:35008
	ds_read_b128 v[50:53], v185 offset:35040
	v_lshl_add_u64 v[106:107], v[2:3], 0, s[2:3]
	ds_read_b128 v[2:5], v183
	ds_read_b128 v[108:111], v183 offset:32
	ds_read_b128 v[228:231], v183 offset:64
	ds_read_b128 v[242:245], v183 offset:96
	s_waitcnt lgkmcnt(3)
	v_mfma_f32_32x32x16_bf16 v[2:17], v[2:5], v[74:77], 0
	s_waitcnt vmcnt(0)
	v_cndmask_b32_e32 v186, 0, v0, vcc
	s_waitcnt lgkmcnt(2)
	v_mfma_f32_32x32x16_bf16 v[2:17], v[108:111], v[78:81], v[2:17]
	ds_read_b128 v[108:111], v183 offset:128
	s_waitcnt lgkmcnt(2)
	v_mfma_f32_32x32x16_bf16 v[2:17], v[228:231], v[70:73], v[2:17]
	ds_read_b128 v[228:231], v183 offset:160
	s_waitcnt lgkmcnt(2)
	v_mfma_f32_32x32x16_bf16 v[2:17], v[242:245], v[66:69], v[2:17]
	ds_read_b128 v[242:245], v183 offset:192
	s_waitcnt lgkmcnt(2)
	v_mfma_f32_32x32x16_bf16 v[2:17], v[108:111], v[62:65], v[2:17]
	ds_read_b128 v[108:111], v183 offset:224
	s_waitcnt lgkmcnt(2)
	v_mfma_f32_32x32x16_bf16 v[2:17], v[228:231], v[58:61], v[2:17]
	s_waitcnt lgkmcnt(1)
	v_mfma_f32_32x32x16_bf16 v[2:17], v[242:245], v[54:57], v[2:17]
	s_waitcnt lgkmcnt(0)
	v_mfma_f32_32x32x16_bf16 v[2:17], v[108:111], v[50:53], v[2:17]
	v_lshlrev_b32_e32 v108, 1, v92
	v_mov_b32_e32 v109, v1
	s_nop 9
	v_mul_f32_e32 v0, v46, v2
	v_mul_f32_e32 v2, v47, v3
	v_cvt_pk_bf16_f32 v2, v0, v2
	v_mul_f32_e32 v0, v48, v4
	v_mul_f32_e32 v3, v49, v5
	v_cvt_pk_bf16_f32 v3, v0, v3
	v_lshlrev_b32_e32 v0, 1, v88
	v_lshl_add_u64 v[4:5], v[106:107], 0, v[0:1]
	global_store_dwordx2 v[4:5], v[2:3], off
	v_mul_f32_e32 v2, v42, v6
	v_mul_f32_e32 v3, v43, v7
	v_cvt_pk_bf16_f32 v2, v2, v3
	v_mul_f32_e32 v3, v44, v8
	v_mul_f32_e32 v4, v45, v9
	v_cvt_pk_bf16_f32 v3, v3, v4
	v_lshl_add_u64 v[4:5], v[106:107], 0, v[104:105]
	global_store_dwordx2 v[4:5], v[2:3], off
	v_mul_f32_e32 v2, v38, v10
	v_mul_f32_e32 v3, v39, v11
	v_cvt_pk_bf16_f32 v2, v2, v3
	v_mul_f32_e32 v3, v40, v12
	v_mul_f32_e32 v4, v41, v13
	v_cvt_pk_bf16_f32 v3, v3, v4
	v_lshl_add_u64 v[4:5], v[106:107], 0, v[108:109]
	global_store_dwordx2 v[4:5], v[2:3], off
	v_mul_f32_e32 v2, v34, v14
	v_mul_f32_e32 v3, v35, v15
	v_cvt_pk_bf16_f32 v2, v2, v3
	v_mul_f32_e32 v3, v36, v16
	v_mul_f32_e32 v4, v37, v17
	v_cvt_pk_bf16_f32 v3, v3, v4
	v_lshl_add_u64 v[4:5], v[106:107], 0, v[102:103]
	global_store_dwordx2 v[4:5], v[2:3], off
	ds_read_b128 v[228:231], v184
	ds_read_b128 v[242:245], v184 offset:32
	ds_read_b128 v[246:249], v184 offset:64
	s_waitcnt lgkmcnt(2)
	v_mfma_f32_32x32x16_bf16 v[2:17], v[228:231], v[74:77], 0
	ds_read_b128 v[228:231], v184 offset:96
	s_waitcnt lgkmcnt(2)
	v_mfma_f32_32x32x16_bf16 v[2:17], v[242:245], v[78:81], v[2:17]
	ds_read_b128 v[242:245], v184 offset:128
	v_lshlrev_b32_e32 v110, 1, v94
	v_mov_b32_e32 v111, v1
	v_lshlrev_b32_e32 v112, 1, v96
	v_mov_b32_e32 v113, v1
	s_waitcnt lgkmcnt(2)
	v_mfma_f32_32x32x16_bf16 v[2:17], v[246:249], v[70:73], v[2:17]
	ds_read_b128 v[246:249], v184 offset:160
	s_waitcnt lgkmcnt(2)
	v_mfma_f32_32x32x16_bf16 v[2:17], v[228:231], v[66:69], v[2:17]
	ds_read_b128 v[228:231], v184 offset:192
	s_waitcnt lgkmcnt(2)
	v_mfma_f32_32x32x16_bf16 v[2:17], v[242:245], v[62:65], v[2:17]
	ds_read_b128 v[242:245], v184 offset:224
	v_add_u32_e32 v68, s1, v83
	v_min_i32_e32 v68, 15, v68
	v_add_u32_e32 v68, 1, v68
	v_cvt_f32_i32_e32 v68, v68
	v_lshlrev_b32_e32 v66, 16, v226
	v_and_b32_e32 v67, 0xffff0000, v226
	s_waitcnt lgkmcnt(2)
	v_mfma_f32_32x32x16_bf16 v[2:17], v[246:249], v[58:61], v[2:17]
	v_lshlrev_b32_e32 v62, 16, v217
	v_and_b32_e32 v63, 0xffff0000, v217
	v_rcp_iflag_f32_e32 v68, v68
	s_waitcnt lgkmcnt(1)
	v_mfma_f32_32x32x16_bf16 v[2:17], v[228:231], v[54:57], v[2:17]
	v_lshlrev_b32_e32 v58, 16, v214
	v_and_b32_e32 v59, 0xffff0000, v214
	v_lshlrev_b32_e32 v60, 16, v215
	v_and_b32_e32 v61, 0xffff0000, v215
	s_waitcnt lgkmcnt(0)
	v_mfma_f32_32x32x16_bf16 v[2:17], v[242:245], v[50:53], v[2:17]
	v_lshlrev_b32_e32 v50, 16, v209
	v_and_b32_e32 v51, 0xffff0000, v209
	v_lshlrev_b32_e32 v52, 16, v211
	v_and_b32_e32 v53, 0xffff0000, v211
	v_lshlrev_b32_e32 v54, 16, v212
	v_and_b32_e32 v55, 0xffff0000, v212
	v_lshlrev_b32_e32 v56, 16, v213
	s_nop 4
	v_mul_f32_e32 v2, v30, v2
	v_mul_f32_e32 v3, v31, v3
	v_cvt_pk_bf16_f32 v2, v2, v3
	v_mul_f32_e32 v3, v32, v4
	v_mul_f32_e32 v4, v33, v5
	v_cvt_pk_bf16_f32 v3, v3, v4
	v_lshl_add_u64 v[4:5], v[106:107], 0, v[110:111]
	global_store_dwordx2 v[4:5], v[2:3], off
	v_mul_f32_e32 v2, v26, v6
	v_mul_f32_e32 v3, v27, v7
	v_cvt_pk_bf16_f32 v2, v2, v3
	v_mul_f32_e32 v3, v28, v8
	v_mul_f32_e32 v4, v29, v9
	v_cvt_pk_bf16_f32 v3, v3, v4
	v_lshl_add_u64 v[4:5], v[106:107], 0, v[112:113]
	global_store_dwordx2 v[4:5], v[2:3], off
	v_mul_f32_e32 v2, v22, v10
	v_mul_f32_e32 v3, v23, v11
	v_cvt_pk_bf16_f32 v2, v2, v3
	v_mul_f32_e32 v3, v24, v12
	v_mul_f32_e32 v4, v25, v13
	v_cvt_pk_bf16_f32 v3, v3, v4
	v_lshl_add_u64 v[4:5], v[106:107], 0, v[114:115]
	global_store_dwordx2 v[4:5], v[2:3], off
	v_mul_f32_e32 v2, v18, v14
	v_mul_f32_e32 v3, v19, v15
	v_cvt_pk_bf16_f32 v2, v2, v3
	v_mul_f32_e32 v3, v20, v16
	v_mul_f32_e32 v4, v21, v17
	v_cvt_pk_bf16_f32 v3, v3, v4
	v_lshlrev_b32_e32 v4, 1, v100
	v_mov_b32_e32 v5, v1
	v_lshl_add_u64 v[4:5], v[106:107], 0, v[4:5]
	global_store_dwordx2 v[4:5], v[2:3], off
	v_add_f32_e32 v2, 0, v50
	v_add_f32_e32 v3, 0, v51
	v_add_f32_e32 v2, v2, v52
	v_add_f32_e32 v3, v3, v53
	v_add_f32_e32 v2, v2, v54
	v_add_f32_e32 v3, v3, v55
	v_add_f32_e32 v2, v2, v56
	v_and_b32_e32 v57, 0xffff0000, v213
	v_add_f32_e32 v3, v3, v57
	v_add_f32_e32 v2, v2, v58
	v_add_f32_e32 v3, v3, v59
	v_add_f32_e32 v2, v2, v60
	v_add_f32_e32 v3, v3, v61
	v_add_f32_e32 v2, v2, v62
	v_lshlrev_b32_e32 v16, 16, v218
	v_add_f32_e32 v3, v3, v63
	v_add_f32_e32 v2, v2, v16
	v_and_b32_e32 v17, 0xffff0000, v218
	v_lshlrev_b32_e32 v14, 16, v219
	v_add_f32_e32 v3, v3, v17
	v_add_f32_e32 v2, v2, v14
	v_and_b32_e32 v15, 0xffff0000, v219
	v_lshlrev_b32_e32 v12, 16, v220
	v_add_f32_e32 v3, v3, v15
	v_add_f32_e32 v2, v2, v12
	v_and_b32_e32 v13, 0xffff0000, v220
	v_lshlrev_b32_e32 v10, 16, v221
	v_add_f32_e32 v3, v3, v13
	v_add_f32_e32 v2, v2, v10
	v_and_b32_e32 v11, 0xffff0000, v221
	v_lshlrev_b32_e32 v8, 16, v223
	v_add_f32_e32 v3, v3, v11
	v_add_f32_e32 v2, v2, v8
	v_and_b32_e32 v9, 0xffff0000, v223
	v_lshlrev_b32_e32 v6, 16, v224
	v_add_f32_e32 v3, v3, v9
	v_add_f32_e32 v2, v2, v6
	v_and_b32_e32 v7, 0xffff0000, v224
	v_lshlrev_b32_e32 v4, 16, v225
	v_add_f32_e32 v3, v3, v7
	v_add_f32_e32 v64, v2, v4
	v_and_b32_e32 v5, 0xffff0000, v225
	v_lshlrev_b32_e32 v2, 16, v227
	v_add_f32_e32 v65, v3, v5
	v_add_f32_e32 v64, v64, v2
	v_and_b32_e32 v3, 0xffff0000, v227
	v_add_f32_e32 v65, v65, v3
	v_add_f32_e32 v64, v64, v66
	v_add_f32_e32 v65, v65, v67
	v_fma_f32 v66, v68, v64, -v66
	v_fma_f32 v67, v68, v65, -v67
	v_cvt_pk_bf16_f32 v66, v66, v67
	s_waitcnt lgkmcnt(0)
	s_barrier
	ds_write_b32 v116, v66 offset:34816
	v_add_u32_e32 v66, s1, v127
	v_min_i32_e32 v66, 15, v66
	v_add_u32_e32 v66, 1, v66
	v_cvt_f32_i32_e32 v66, v66
	v_sub_f32_e32 v50, v64, v50
	v_lshlrev_b32_e32 v64, 16, v222
	v_sub_f32_e32 v51, v65, v51
	v_rcp_iflag_f32_e32 v66, v66
	v_and_b32_e32 v65, 0xffff0000, v222
	v_add_f32_e32 v50, v50, v64
	v_add_f32_e32 v51, v51, v65
	v_fma_f32 v64, v66, v50, -v64
	v_fma_f32 v65, v66, v51, -v65
	v_cvt_pk_bf16_f32 v64, v64, v65
	ds_write_b32 v117, v64 offset:34816
	v_add_u32_e32 v64, s1, v128
	v_min_i32_e32 v64, 15, v64
	v_add_u32_e32 v64, 1, v64
	v_cvt_f32_i32_e32 v64, v64
	v_sub_f32_e32 v50, v50, v52
	v_lshlrev_b32_e32 v52, 16, v216
	v_add_f32_e32 v50, v50, v52
	v_rcp_iflag_f32_e32 v64, v64
	v_sub_f32_e32 v51, v51, v53
	v_and_b32_e32 v53, 0xffff0000, v216
	v_add_f32_e32 v51, v51, v53
	v_fma_f32 v52, v64, v50, -v52
	v_sub_f32_e32 v50, v50, v54
	v_add_u32_e32 v54, s1, v129
	v_min_i32_e32 v54, 15, v54
	v_add_u32_e32 v54, 1, v54
	v_cvt_f32_i32_e32 v54, v54
	v_fma_f32 v53, v64, v51, -v53
	v_cvt_pk_bf16_f32 v52, v52, v53
	ds_write_b32 v168, v52 offset:34816
	v_rcp_iflag_f32_e32 v54, v54
	v_sub_f32_e32 v51, v51, v55
	v_lshlrev_b32_e32 v52, 16, v210
	v_and_b32_e32 v53, 0xffff0000, v210
	v_add_f32_e32 v50, v50, v52
	v_add_f32_e32 v51, v51, v53
	v_fma_f32 v52, v54, v50, -v52
	v_fma_f32 v53, v54, v51, -v53
	v_add_u32_e32 v54, s1, v130
	v_min_i32_e32 v54, 15, v54
	v_add_u32_e32 v54, 1, v54
	v_cvt_f32_i32_e32 v54, v54
	v_cvt_pk_bf16_f32 v52, v52, v53
	ds_write_b32 v169, v52 offset:34816
	v_sub_f32_e32 v50, v50, v56
	v_rcp_iflag_f32_e32 v54, v54
	v_sub_f32_e32 v51, v51, v57
	v_lshlrev_b32_e32 v52, 16, v208
	v_and_b32_e32 v53, 0xffff0000, v208
	v_add_f32_e32 v50, v50, v52
	v_add_f32_e32 v51, v51, v53
	v_fma_f32 v52, v54, v50, -v52
	v_fma_f32 v53, v54, v51, -v53
	v_add_u32_e32 v54, s1, v131
	v_min_i32_e32 v54, 15, v54
	v_add_u32_e32 v54, 1, v54
	v_cvt_f32_i32_e32 v54, v54
	v_cvt_pk_bf16_f32 v52, v52, v53
	ds_write_b32 v170, v52 offset:34816
	v_sub_f32_e32 v50, v50, v58
	v_rcp_iflag_f32_e32 v54, v54
	v_sub_f32_e32 v51, v51, v59
	v_lshlrev_b32_e32 v52, 16, v207
	v_and_b32_e32 v53, 0xffff0000, v207
	v_add_f32_e32 v50, v50, v52
	v_add_f32_e32 v51, v51, v53
	v_fma_f32 v52, v54, v50, -v52
	v_fma_f32 v53, v54, v51, -v53
	v_add_u32_e32 v54, s1, v132
	v_min_i32_e32 v54, 15, v54
	v_add_u32_e32 v54, 1, v54
	v_cvt_f32_i32_e32 v54, v54
	v_cvt_pk_bf16_f32 v52, v52, v53
	ds_write_b32 v171, v52 offset:34816
	v_sub_f32_e32 v50, v50, v60
	v_rcp_iflag_f32_e32 v54, v54
	v_sub_f32_e32 v51, v51, v61
	v_lshlrev_b32_e32 v52, 16, v206
	v_and_b32_e32 v53, 0xffff0000, v206
	v_add_f32_e32 v50, v50, v52
	v_add_f32_e32 v51, v51, v53
	v_fma_f32 v52, v54, v50, -v52
	v_fma_f32 v53, v54, v51, -v53
	v_add_u32_e32 v54, s1, v133
	v_min_i32_e32 v54, 15, v54
	v_add_u32_e32 v54, 1, v54
	v_cvt_f32_i32_e32 v54, v54
	v_cvt_pk_bf16_f32 v52, v52, v53
	ds_write_b32 v172, v52 offset:34816
	v_sub_f32_e32 v50, v50, v62
	v_rcp_iflag_f32_e32 v54, v54
	v_lshlrev_b32_e32 v52, 16, v205
	v_sub_f32_e32 v51, v51, v63
	v_and_b32_e32 v53, 0xffff0000, v205
	v_add_f32_e32 v50, v50, v52
	v_add_f32_e32 v51, v51, v53
	v_fma_f32 v52, v54, v50, -v52
	v_fma_f32 v53, v54, v51, -v53
	v_cvt_pk_bf16_f32 v52, v52, v53
	ds_write_b32 v173, v52 offset:34816
	v_add_u32_e32 v52, s1, v134
	v_min_i32_e32 v52, 15, v52
	v_add_u32_e32 v52, 1, v52
	v_cvt_f32_i32_e32 v52, v52
	v_sub_f32_e32 v16, v50, v16
	v_lshlrev_b32_e32 v50, 16, v204
	v_sub_f32_e32 v17, v51, v17
	v_rcp_iflag_f32_e32 v52, v52
	v_and_b32_e32 v51, 0xffff0000, v204
	v_add_f32_e32 v16, v16, v50
	v_add_f32_e32 v17, v17, v51
	v_fma_f32 v50, v52, v16, -v50
	v_fma_f32 v51, v52, v17, -v51
	v_cvt_pk_bf16_f32 v50, v50, v51
	ds_write_b32 v174, v50 offset:34816
	v_add_u32_e32 v50, s1, v135
	v_min_i32_e32 v50, 15, v50
	v_add_u32_e32 v50, 1, v50
	v_cvt_f32_i32_e32 v50, v50
	v_sub_f32_e32 v14, v16, v14
	v_lshlrev_b32_e32 v16, 16, v192
	v_sub_f32_e32 v15, v17, v15
	v_rcp_iflag_f32_e32 v50, v50
	v_and_b32_e32 v17, 0xffff0000, v192
	v_add_f32_e32 v14, v14, v16
	v_add_f32_e32 v15, v15, v17
	v_fma_f32 v16, v50, v14, -v16
	v_fma_f32 v17, v50, v15, -v17
	v_cvt_pk_bf16_f32 v16, v16, v17
	ds_write_b32 v175, v16 offset:34816
	v_add_u32_e32 v16, s1, v136
	v_min_i32_e32 v16, 15, v16
	v_add_u32_e32 v16, 1, v16
	v_cvt_f32_i32_e32 v16, v16
	v_sub_f32_e32 v12, v14, v12
	v_lshlrev_b32_e32 v14, 16, v190
	v_sub_f32_e32 v13, v15, v13
	v_rcp_iflag_f32_e32 v16, v16
	v_and_b32_e32 v15, 0xffff0000, v190
	v_add_f32_e32 v12, v12, v14
	v_add_f32_e32 v13, v13, v15
	v_fma_f32 v14, v16, v12, -v14
	v_fma_f32 v15, v16, v13, -v15
	v_cvt_pk_bf16_f32 v14, v14, v15
	ds_write_b32 v176, v14 offset:34816
	v_add_u32_e32 v14, s1, v137
	v_min_i32_e32 v14, 15, v14
	v_add_u32_e32 v14, 1, v14
	v_cvt_f32_i32_e32 v14, v14
	v_sub_f32_e32 v10, v12, v10
	v_lshlrev_b32_e32 v12, 16, v189
	v_sub_f32_e32 v11, v13, v11
	v_rcp_iflag_f32_e32 v14, v14
	v_and_b32_e32 v13, 0xffff0000, v189
	v_add_f32_e32 v10, v10, v12
	v_add_f32_e32 v11, v11, v13
	v_fma_f32 v12, v14, v10, -v12
	v_fma_f32 v13, v14, v11, -v13
	v_cvt_pk_bf16_f32 v12, v12, v13
	ds_write_b32 v177, v12 offset:34816
	v_add_u32_e32 v12, s1, v138
	v_min_i32_e32 v12, 15, v12
	v_add_u32_e32 v12, 1, v12
	v_cvt_f32_i32_e32 v12, v12
	v_sub_f32_e32 v8, v10, v8
	v_lshlrev_b32_e32 v10, 16, v188
	v_sub_f32_e32 v9, v11, v9
	v_rcp_iflag_f32_e32 v12, v12
	v_and_b32_e32 v11, 0xffff0000, v188
	v_add_f32_e32 v8, v8, v10
	v_add_f32_e32 v9, v9, v11
	v_fma_f32 v10, v12, v8, -v10
	v_fma_f32 v11, v12, v9, -v11
	v_cvt_pk_bf16_f32 v10, v10, v11
	ds_write_b32 v178, v10 offset:34816
	v_add_u32_e32 v10, s1, v139
	v_min_i32_e32 v10, 15, v10
	v_add_u32_e32 v10, 1, v10
	v_cvt_f32_i32_e32 v10, v10
	v_sub_f32_e32 v6, v8, v6
	v_lshlrev_b32_e32 v8, 16, v187
	v_sub_f32_e32 v7, v9, v7
	v_rcp_iflag_f32_e32 v10, v10
	v_and_b32_e32 v9, 0xffff0000, v187
	v_add_f32_e32 v6, v6, v8
	v_add_f32_e32 v7, v7, v9
	v_fma_f32 v8, v10, v6, -v8
	v_fma_f32 v9, v10, v7, -v9
	v_cvt_pk_bf16_f32 v8, v8, v9
	ds_write_b32 v179, v8 offset:34816
	v_add_u32_e32 v8, s1, v140
	v_min_i32_e32 v8, 15, v8
	v_add_u32_e32 v8, 1, v8
	v_cvt_f32_i32_e32 v8, v8
	v_sub_f32_e32 v4, v6, v4
	v_lshlrev_b32_e32 v6, 16, v186
	v_sub_f32_e32 v5, v7, v5
	v_rcp_iflag_f32_e32 v8, v8
	v_and_b32_e32 v7, 0xffff0000, v186
	v_add_f32_e32 v4, v4, v6
	v_add_f32_e32 v5, v5, v7
	v_fma_f32 v6, v8, v4, -v6
	v_fma_f32 v7, v8, v5, -v7
	v_cvt_pk_bf16_f32 v6, v6, v7
	ds_write_b32 v180, v6 offset:34816
	v_add_u32_e32 v6, s1, v141
	v_min_i32_e32 v6, 15, v6
	v_add_u32_e32 v6, 1, v6
	v_cvt_f32_i32_e32 v6, v6
	v_sub_f32_e32 v2, v4, v2
	v_lshlrev_b32_e32 v4, 16, v182
	v_sub_f32_e32 v3, v5, v3
	v_rcp_iflag_f32_e32 v6, v6
	v_and_b32_e32 v5, 0xffff0000, v182
	v_add_f32_e32 v2, v2, v4
	v_add_f32_e32 v3, v3, v5
	v_fma_f32 v2, v6, v2, -v4
	v_fma_f32 v3, v6, v3, -v5
	v_cvt_pk_bf16_f32 v2, v2, v3
	ds_write_b32 v181, v2 offset:34816
	v_add_u32_e32 v2, s0, v142
	v_ashrrev_i32_e32 v3, 31, v2
	v_lshlrev_b64 v[2:3], 12, v[2:3]
	s_waitcnt lgkmcnt(0)
	s_barrier
	v_lshl_add_u64 v[2:3], s[70:71], 0, v[2:3]
	ds_read_b128 v[74:77], v185 offset:34816
	ds_read_b128 v[78:81], v185 offset:34848
	ds_read_b128 v[70:73], v185 offset:34880
	ds_read_b128 v[66:69], v185 offset:34912
	ds_read_b128 v[62:65], v185 offset:34944
	ds_read_b128 v[58:61], v185 offset:34976
	ds_read_b128 v[54:57], v185 offset:35008
	ds_read_b128 v[50:53], v185 offset:35040
	v_lshl_add_u64 v[106:107], v[2:3], 0, s[2:3]
	ds_read_b128 v[2:5], v183
	ds_read_b128 v[168:171], v183 offset:32
	ds_read_b128 v[228:231], v183 offset:64
	ds_read_b128 v[242:245], v183 offset:96
	s_waitcnt lgkmcnt(3)
	v_mfma_f32_32x32x16_bf16 v[2:17], v[2:5], v[74:77], 0
	s_waitcnt lgkmcnt(2)
	v_mfma_f32_32x32x16_bf16 v[2:17], v[168:171], v[78:81], v[2:17]
	ds_read_b128 v[168:171], v183 offset:128
	s_waitcnt lgkmcnt(2)
	v_mfma_f32_32x32x16_bf16 v[2:17], v[228:231], v[70:73], v[2:17]
	ds_read_b128 v[228:231], v183 offset:160
	s_waitcnt lgkmcnt(2)
	v_mfma_f32_32x32x16_bf16 v[2:17], v[242:245], v[66:69], v[2:17]
	ds_read_b128 v[242:245], v183 offset:192
	s_waitcnt lgkmcnt(2)
	v_mfma_f32_32x32x16_bf16 v[2:17], v[168:171], v[62:65], v[2:17]
	ds_read_b128 v[168:171], v183 offset:224
	s_waitcnt lgkmcnt(2)
	v_mfma_f32_32x32x16_bf16 v[2:17], v[228:231], v[58:61], v[2:17]
	s_waitcnt lgkmcnt(1)
	v_mfma_f32_32x32x16_bf16 v[2:17], v[242:245], v[54:57], v[2:17]
	s_waitcnt lgkmcnt(0)
	v_mfma_f32_32x32x16_bf16 v[2:17], v[168:171], v[50:53], v[2:17]
	s_nop 11
	v_mul_f32_e32 v2, v46, v2
	v_mul_f32_e32 v3, v47, v3
	v_cvt_pk_bf16_f32 v2, v2, v3
	v_mul_f32_e32 v3, v48, v4
	v_mul_f32_e32 v4, v49, v5
	v_cvt_pk_bf16_f32 v3, v3, v4
	v_lshl_add_u64 v[4:5], v[106:107], 0, v[0:1]
	global_store_dwordx2 v[4:5], v[2:3], off
	v_mul_f32_e32 v0, v42, v6
	v_mul_f32_e32 v2, v43, v7
	v_mul_f32_e32 v3, v45, v9
	v_cvt_pk_bf16_f32 v2, v0, v2
	v_mul_f32_e32 v0, v44, v8
	v_cvt_pk_bf16_f32 v3, v0, v3
	v_lshl_add_u64 v[4:5], v[106:107], 0, v[104:105]
	global_store_dwordx2 v[4:5], v[2:3], off
	v_mul_f32_e32 v0, v38, v10
	v_mul_f32_e32 v2, v39, v11
	v_mul_f32_e32 v3, v41, v13
	v_cvt_pk_bf16_f32 v2, v0, v2
	v_mul_f32_e32 v0, v40, v12
	v_cvt_pk_bf16_f32 v3, v0, v3
	v_lshl_add_u64 v[4:5], v[106:107], 0, v[108:109]
	global_store_dwordx2 v[4:5], v[2:3], off
	v_mul_f32_e32 v0, v34, v14
	v_mul_f32_e32 v2, v35, v15
	v_mul_f32_e32 v3, v37, v17
	v_lshl_add_u64 v[4:5], v[106:107], 0, v[102:103]
	v_cvt_pk_bf16_f32 v2, v0, v2
	v_mul_f32_e32 v0, v36, v16
	v_cvt_pk_bf16_f32 v3, v0, v3
	global_store_dwordx2 v[4:5], v[2:3], off
	ds_read_b128 v[2:5], v184
	ds_read_b128 v[34:37], v184 offset:32
	ds_read_b128 v[228:231], v184 offset:64
	ds_read_b128 v[242:245], v184 offset:96
	s_waitcnt lgkmcnt(3)
	v_mfma_f32_32x32x16_bf16 v[2:17], v[2:5], v[74:77], 0
	s_waitcnt lgkmcnt(2)
	v_mfma_f32_32x32x16_bf16 v[2:17], v[34:37], v[78:81], v[2:17]
	ds_read_b128 v[34:37], v184 offset:128
	s_waitcnt lgkmcnt(2)
	v_mfma_f32_32x32x16_bf16 v[2:17], v[228:231], v[70:73], v[2:17]
	ds_read_b128 v[228:231], v184 offset:160
	s_waitcnt lgkmcnt(2)
	v_mfma_f32_32x32x16_bf16 v[2:17], v[242:245], v[66:69], v[2:17]
	ds_read_b128 v[242:245], v184 offset:192
	s_waitcnt lgkmcnt(2)
	v_mfma_f32_32x32x16_bf16 v[2:17], v[34:37], v[62:65], v[2:17]
	ds_read_b128 v[34:37], v184 offset:224
	s_waitcnt lgkmcnt(2)
	v_mfma_f32_32x32x16_bf16 v[2:17], v[228:231], v[58:61], v[2:17]
	s_waitcnt lgkmcnt(1)
	v_mfma_f32_32x32x16_bf16 v[2:17], v[242:245], v[54:57], v[2:17]
	s_waitcnt lgkmcnt(0)
	v_mfma_f32_32x32x16_bf16 v[2:17], v[34:37], v[50:53], v[2:17]
	s_nop 11
	v_mul_f32_e32 v0, v30, v2
	v_mul_f32_e32 v2, v31, v3
	v_mul_f32_e32 v3, v33, v5
	v_cvt_pk_bf16_f32 v2, v0, v2
	v_mul_f32_e32 v0, v32, v4
	v_cvt_pk_bf16_f32 v3, v0, v3
	v_lshl_add_u64 v[4:5], v[106:107], 0, v[110:111]
	global_store_dwordx2 v[4:5], v[2:3], off
	v_mul_f32_e32 v0, v26, v6
	v_mul_f32_e32 v2, v27, v7
	v_mul_f32_e32 v3, v29, v9
	v_cvt_pk_bf16_f32 v2, v0, v2
	v_mul_f32_e32 v0, v28, v8
	v_cvt_pk_bf16_f32 v3, v0, v3
	v_lshl_add_u64 v[4:5], v[106:107], 0, v[112:113]
	global_store_dwordx2 v[4:5], v[2:3], off
	v_mul_f32_e32 v0, v22, v10
	v_mul_f32_e32 v2, v23, v11
	v_mul_f32_e32 v3, v25, v13
	v_cvt_pk_bf16_f32 v2, v0, v2
	v_mul_f32_e32 v0, v24, v12
	v_cvt_pk_bf16_f32 v3, v0, v3
	v_lshl_add_u64 v[4:5], v[106:107], 0, v[114:115]
	global_store_dwordx2 v[4:5], v[2:3], off
	v_mul_f32_e32 v0, v18, v14
	v_mul_f32_e32 v2, v19, v15
	v_mul_f32_e32 v3, v21, v17
	v_cvt_pk_bf16_f32 v2, v0, v2
	v_mul_f32_e32 v0, v20, v16
	v_cvt_pk_bf16_f32 v3, v0, v3

.LBB0_220:
	s_or_b64 exec, exec, s[52:53]
	s_waitcnt vmcnt(26)
	v_cndmask_b32_e64 v14, 0, v14, s[8:9]
	v_cndmask_b32_e32 v10, 0, v10, vcc
	v_lshlrev_b32_e32 v65, 16, v14
	v_and_b32_e32 v66, 0xffff0000, v14
	v_add_u32_e32 v14, s95, v83
	s_waitcnt vmcnt(8)
	v_cndmask_b32_e64 v0, 0, v57, s[46:47]
	v_cndmask_b32_e64 v57, 0, v56, s[28:29]
	v_cndmask_b32_e64 v11, 0, v11, s[0:1]
	v_lshlrev_b32_e32 v56, 16, v10
	v_min_i32_e32 v14, 7, v14
	v_cndmask_b32_e64 v12, 0, v12, s[2:3]
	v_add_f32_e32 v58, 0, v56
	v_and_b32_e32 v59, 0xffff0000, v10
	v_lshlrev_b32_e32 v60, 16, v11
	v_add_u32_e32 v14, 1, v14
	v_add_f32_e32 v10, 0, v59
	v_add_f32_e32 v58, v58, v60
	v_and_b32_e32 v61, 0xffff0000, v11
	v_lshlrev_b32_e32 v62, 16, v12
	v_cvt_f32_i32_e32 v14, v14
	v_cndmask_b32_e64 v13, 0, v13, s[6:7]
	v_add_f32_e32 v10, v10, v61
	v_add_f32_e32 v11, v58, v62
	v_and_b32_e32 v58, 0xffff0000, v12
	v_add_f32_e32 v10, v10, v58
	v_lshlrev_b32_e32 v63, 16, v13
	v_and_b32_e32 v64, 0xffff0000, v13
	v_cndmask_b32_e64 v15, 0, v15, s[10:11]
	v_add_f32_e32 v11, v11, v63
	v_add_f32_e32 v10, v10, v64
	v_cndmask_b32_e64 v16, 0, v16, s[12:13]
	v_add_f32_e32 v11, v11, v65
	v_add_f32_e32 v10, v10, v66
	v_lshlrev_b32_e32 v67, 16, v15
	v_and_b32_e32 v68, 0xffff0000, v15
	v_rcp_iflag_f32_e32 v14, v14
	v_cndmask_b32_e64 v17, 0, v17, s[14:15]
	v_add_f32_e32 v11, v11, v67
	v_add_f32_e32 v10, v10, v68
	v_lshlrev_b32_e32 v69, 16, v16
	v_and_b32_e32 v70, 0xffff0000, v16
	v_add_f32_e32 v12, v11, v69
	v_add_f32_e32 v13, v10, v70
	v_lshlrev_b32_e32 v10, 16, v17
	v_and_b32_e32 v11, 0xffff0000, v17
	v_add_u32_e32 v16, s95, v127
	v_add_f32_e32 v12, v12, v10
	v_add_f32_e32 v13, v13, v11
	v_min_i32_e32 v16, 7, v16
	v_fma_f32 v15, v14, v12, -v10
	v_fma_f32 v14, v14, v13, -v11
	v_add_u32_e32 v16, 1, v16
	v_cndmask_b32_e64 v50, v50, 0, s[16:17]
	v_cvt_pk_bf16_f32 v14, v15, v14
	v_add_u32_e32 v116, 0, v145
	v_cvt_f32_i32_e32 v16, v16
	s_waitcnt lgkmcnt(0)
	s_barrier
	ds_write_b32 v116, v14 offset:34816
	v_sub_f32_e32 v14, v12, v56
	v_sub_f32_e32 v15, v13, v59
	v_lshlrev_b32_e32 v12, 16, v50
	v_and_b32_e32 v13, 0xffff0000, v50
	v_add_u32_e32 v50, s95, v128
	v_min_i32_e32 v50, 7, v50
	v_add_u32_e32 v50, 1, v50
	v_rcp_iflag_f32_e32 v16, v16
	v_cvt_f32_i32_e32 v50, v50
	v_add_f32_e32 v14, v14, v12
	v_add_f32_e32 v15, v15, v13
	v_fma_f32 v17, v16, v14, -v12
	v_fma_f32 v16, v16, v15, -v13
	v_rcp_iflag_f32_e32 v50, v50
	v_cndmask_b32_e64 v51, 0, v51, s[18:19]
	v_cvt_pk_bf16_f32 v16, v17, v16
	v_add_u32_e32 v117, 0, v146
	ds_write_b32 v117, v16 offset:34816
	v_sub_f32_e32 v16, v14, v60
	v_sub_f32_e32 v17, v15, v61
	v_lshlrev_b32_e32 v14, 16, v51
	v_and_b32_e32 v15, 0xffff0000, v51
	v_add_f32_e32 v16, v16, v14
	v_add_f32_e32 v17, v17, v15
	v_fma_f32 v51, v50, v16, -v14
	v_fma_f32 v50, v50, v17, -v15
	v_cndmask_b32_e64 v52, 0, v52, s[20:21]
	v_cvt_pk_bf16_f32 v50, v51, v50
	v_add_u32_e32 v168, 0, v147
	ds_write_b32 v168, v50 offset:34816
	v_sub_f32_e32 v50, v16, v62
	v_sub_f32_e32 v51, v17, v58
	v_lshlrev_b32_e32 v16, 16, v52
	v_and_b32_e32 v17, 0xffff0000, v52
	v_add_u32_e32 v52, s95, v129
	v_min_i32_e32 v52, 7, v52
	v_add_u32_e32 v52, 1, v52
	v_cvt_f32_i32_e32 v52, v52
	v_add_f32_e32 v50, v50, v16
	v_add_f32_e32 v51, v51, v17
	v_cndmask_b32_e64 v53, 0, v53, s[22:23]
	v_rcp_iflag_f32_e32 v52, v52
	v_add_u32_e32 v169, 0, v148
	v_cndmask_b32_e64 v54, 0, v54, s[24:25]
	v_add_u32_e32 v170, 0, v149
	v_fma_f32 v56, v52, v50, -v16
	v_fma_f32 v52, v52, v51, -v17
	v_cvt_pk_bf16_f32 v52, v56, v52
	v_sub_f32_e32 v56, v51, v64
	v_and_b32_e32 v51, 0xffff0000, v53
	ds_write_b32 v169, v52 offset:34816
	v_sub_f32_e32 v52, v50, v63
	v_lshlrev_b32_e32 v50, 16, v53
	v_add_f32_e32 v53, v56, v51
	v_add_u32_e32 v56, s95, v130
	v_min_i32_e32 v56, 7, v56
	v_add_u32_e32 v56, 1, v56
	v_cvt_f32_i32_e32 v56, v56
	v_add_f32_e32 v52, v52, v50
	v_cndmask_b32_e64 v55, 0, v55, s[26:27]
	v_add_u32_e32 v171, 0, v150
	v_rcp_iflag_f32_e32 v56, v56
	v_add_u32_e32 v172, 0, v151
	v_cndmask_b32_e64 v9, 0, v9, s[50:51]
	v_add_u32_e32 v173, 0, v152
	v_fma_f32 v58, v56, v52, -v50
	v_fma_f32 v56, v56, v53, -v51
	v_cvt_pk_bf16_f32 v56, v58, v56
	ds_write_b32 v170, v56 offset:34816
	v_sub_f32_e32 v56, v52, v65
	v_sub_f32_e32 v58, v53, v66
	v_lshlrev_b32_e32 v52, 16, v54
	v_and_b32_e32 v53, 0xffff0000, v54
	v_add_f32_e32 v54, v56, v52
	v_add_f32_e32 v56, v58, v53
	v_add_u32_e32 v58, s95, v131
	v_min_i32_e32 v58, 7, v58
	v_add_u32_e32 v58, 1, v58
	v_cvt_f32_i32_e32 v58, v58
	v_add_u32_e32 v174, 0, v153
	v_cndmask_b32_e64 v8, 0, v8, s[34:35]
	v_cndmask_b32_e64 v7, 0, v7, s[36:37]
	v_rcp_iflag_f32_e32 v58, v58
	v_add_u32_e32 v175, 0, v154
	v_cndmask_b32_e64 v6, 0, v6, s[38:39]
	v_add_u32_e32 v176, 0, v155
	v_fma_f32 v59, v58, v54, -v52
	v_fma_f32 v58, v58, v56, -v53
	v_cvt_pk_bf16_f32 v58, v59, v58
	v_add_u32_e32 v59, s95, v132
	v_min_i32_e32 v59, 7, v59
	v_add_u32_e32 v59, 1, v59
	v_cvt_f32_i32_e32 v59, v59
	ds_write_b32 v171, v58 offset:34816
	v_sub_f32_e32 v58, v54, v67
	v_sub_f32_e32 v56, v56, v68
	v_rcp_iflag_f32_e32 v59, v59
	v_lshlrev_b32_e32 v54, 16, v55
	v_and_b32_e32 v55, 0xffff0000, v55
	v_add_f32_e32 v58, v58, v54
	v_add_f32_e32 v56, v56, v55
	v_fma_f32 v60, v59, v58, -v54
	v_fma_f32 v59, v59, v56, -v55
	v_cvt_pk_bf16_f32 v59, v60, v59
	v_add_u32_e32 v60, s95, v133
	v_min_i32_e32 v60, 7, v60
	v_add_u32_e32 v60, 1, v60
	v_cvt_f32_i32_e32 v60, v60
	ds_write_b32 v172, v59 offset:34816
	v_sub_f32_e32 v58, v58, v69
	v_sub_f32_e32 v59, v56, v70
	v_rcp_iflag_f32_e32 v60, v60
	v_lshlrev_b32_e32 v56, 16, v57
	v_and_b32_e32 v57, 0xffff0000, v57
	v_add_f32_e32 v58, v58, v56
	v_add_f32_e32 v59, v59, v57
	v_fma_f32 v61, v60, v58, -v56
	v_fma_f32 v60, v60, v59, -v57
	v_sub_f32_e32 v11, v59, v11
	v_add_u32_e32 v59, s95, v134
	v_min_i32_e32 v59, 7, v59
	v_add_u32_e32 v59, 1, v59
	v_cvt_f32_i32_e32 v59, v59
	v_sub_f32_e32 v10, v58, v10
	v_lshlrev_b32_e32 v58, 16, v9
	v_and_b32_e32 v9, 0xffff0000, v9
	v_rcp_iflag_f32_e32 v59, v59
	v_add_f32_e32 v11, v11, v9
	v_add_f32_e32 v10, v10, v58
	v_cvt_pk_bf16_f32 v60, v61, v60
	v_fma_f32 v9, v59, v11, -v9
	v_fma_f32 v58, v59, v10, -v58
	v_cvt_pk_bf16_f32 v9, v58, v9
	ds_write_b32 v173, v60 offset:34816
	ds_write_b32 v174, v9 offset:34816
	v_sub_f32_e32 v9, v10, v12
	v_add_u32_e32 v12, s95, v135
	v_min_i32_e32 v12, 7, v12
	v_add_u32_e32 v12, 1, v12
	v_cvt_f32_i32_e32 v12, v12
	v_sub_f32_e32 v10, v11, v13
	v_lshlrev_b32_e32 v11, 16, v8
	v_and_b32_e32 v8, 0xffff0000, v8
	v_rcp_iflag_f32_e32 v12, v12
	v_add_f32_e32 v9, v9, v11
	v_add_f32_e32 v10, v10, v8
	v_cndmask_b32_e64 v5, 0, v5, s[40:41]
	v_fma_f32 v11, v12, v9, -v11
	v_fma_f32 v8, v12, v10, -v8
	v_cvt_pk_bf16_f32 v8, v11, v8
	v_add_u32_e32 v11, s95, v136
	v_min_i32_e32 v11, 7, v11
	v_add_u32_e32 v11, 1, v11
	v_cvt_f32_i32_e32 v11, v11
	ds_write_b32 v175, v8 offset:34816
	v_sub_f32_e32 v8, v9, v14
	v_sub_f32_e32 v9, v10, v15
	v_rcp_iflag_f32_e32 v11, v11
	v_lshlrev_b32_e32 v10, 16, v7
	v_and_b32_e32 v7, 0xffff0000, v7
	v_add_f32_e32 v8, v8, v10
	v_add_f32_e32 v9, v9, v7
	v_fma_f32 v10, v11, v8, -v10
	v_fma_f32 v7, v11, v9, -v7
	v_cvt_pk_bf16_f32 v7, v10, v7
	v_add_u32_e32 v10, s95, v137
	v_min_i32_e32 v10, 7, v10
	v_add_u32_e32 v10, 1, v10
	v_cvt_f32_i32_e32 v10, v10
	ds_write_b32 v176, v7 offset:34816
	v_sub_f32_e32 v7, v8, v16
	v_sub_f32_e32 v8, v9, v17
	v_rcp_iflag_f32_e32 v10, v10
	v_lshlrev_b32_e32 v9, 16, v6
	v_and_b32_e32 v6, 0xffff0000, v6
	v_add_f32_e32 v7, v7, v9
	v_add_f32_e32 v8, v8, v6
	v_fma_f32 v9, v10, v7, -v9
	v_fma_f32 v6, v10, v8, -v6
	v_cvt_pk_bf16_f32 v6, v9, v6
	v_add_u32_e32 v9, s95, v138
	v_min_i32_e32 v9, 7, v9
	v_add_u32_e32 v9, 1, v9
	v_cvt_f32_i32_e32 v9, v9
	v_add_u32_e32 v177, 0, v156
	ds_write_b32 v177, v6 offset:34816
	v_sub_f32_e32 v6, v7, v50
	v_rcp_iflag_f32_e32 v9, v9
	v_sub_f32_e32 v7, v8, v51
	v_lshlrev_b32_e32 v8, 16, v5
	v_and_b32_e32 v5, 0xffff0000, v5
	v_add_f32_e32 v6, v6, v8
	v_add_f32_e32 v7, v7, v5
	v_fma_f32 v8, v9, v6, -v8
	v_fma_f32 v5, v9, v7, -v5
	v_cvt_pk_bf16_f32 v5, v8, v5
	v_add_u32_e32 v8, s95, v139
	v_min_i32_e32 v8, 7, v8
	v_add_u32_e32 v8, 1, v8
	v_cvt_f32_i32_e32 v8, v8
	v_cndmask_b32_e64 v4, 0, v4, s[42:43]
	v_add_u32_e32 v178, 0, v157
	ds_write_b32 v178, v5 offset:34816
	v_rcp_iflag_f32_e32 v8, v8
	v_sub_f32_e32 v5, v6, v52
	v_sub_f32_e32 v6, v7, v53
	v_lshlrev_b32_e32 v7, 16, v4
	v_and_b32_e32 v4, 0xffff0000, v4
	v_add_f32_e32 v5, v5, v7
	v_add_f32_e32 v6, v6, v4
	v_fma_f32 v7, v8, v5, -v7
	v_fma_f32 v4, v8, v6, -v4
	v_cvt_pk_bf16_f32 v4, v7, v4
	v_add_u32_e32 v7, s95, v140
	v_min_i32_e32 v7, 7, v7
	v_add_u32_e32 v7, 1, v7
	v_cvt_f32_i32_e32 v7, v7
	v_cndmask_b32_e64 v3, 0, v3, s[44:45]
	v_add_u32_e32 v179, 0, v158
	ds_write_b32 v179, v4 offset:34816
	v_rcp_iflag_f32_e32 v7, v7
	v_sub_f32_e32 v4, v5, v54
	v_sub_f32_e32 v5, v6, v55
	v_lshlrev_b32_e32 v6, 16, v3
	v_and_b32_e32 v3, 0xffff0000, v3
	v_add_f32_e32 v4, v4, v6
	v_add_f32_e32 v5, v5, v3
	v_fma_f32 v6, v7, v4, -v6
	v_fma_f32 v3, v7, v5, -v3
	v_cvt_pk_bf16_f32 v3, v6, v3
	v_add_u32_e32 v6, s95, v141
	v_min_i32_e32 v6, 7, v6
	v_add_u32_e32 v6, 1, v6
	v_cvt_f32_i32_e32 v6, v6
	v_add_u32_e32 v180, 0, v159
	ds_write_b32 v180, v3 offset:34816
	v_sub_f32_e32 v3, v4, v56
	v_rcp_iflag_f32_e32 v6, v6
	v_sub_f32_e32 v4, v5, v57
	v_lshlrev_b32_e32 v5, 16, v0
	v_and_b32_e32 v0, 0xffff0000, v0
	s_or_b32 s0, s94, 0x80
	v_add_f32_e32 v3, v3, v5
	v_add_f32_e32 v4, v4, v0
	s_xor_b32 s1, s95, 0xffffff7f
	s_mul_i32 s2, s0, 0x1e00
	v_fma_f32 v3, v6, v3, -v5
	v_fma_f32 v0, v6, v4, -v0
	s_mul_hi_i32 s3, s0, 0x1e00
	s_add_u32 s2, s91, s2
	v_cvt_pk_bf16_f32 v0, v3, v0
	s_addc_u32 s3, s92, s3
	v_mov_b32_e32 v3, v1
	v_add_u32_e32 v181, 0, v160
	v_cmp_lt_i32_e32 vcc, s1, v141
	v_lshl_add_u64 v[2:3], s[2:3], 0, v[2:3]
	s_mov_b64 s[2:3], 0x1620
	ds_write_b32 v181, v0 offset:34816
	v_lshl_add_u64 v[2:3], v[2:3], 0, s[2:3]
	v_cndmask_b32_e32 v0, 0, v141, vcc
	s_movk_i32 s6, 0x1e00
	v_mad_i64_i32 v[4:5], s[2:3], v0, s6, v[2:3]
	global_load_dword v0, v[4:5], off
	v_add_u32_e32 v185, v144, v143
	v_add_u32_e32 v183, v144, v161
	v_lshlrev_b32_e32 v104, 1, v90
	v_mov_b32_e32 v105, v1
	v_mov_b32_e32 v103, v1
	v_add_u32_e32 v184, v144, v163
	v_lshlrev_b32_e32 v114, 1, v98
	v_mov_b32_e32 v115, v1
	s_waitcnt vmcnt(0)
	v_cndmask_b32_e32 v182, 0, v0, vcc
	v_cmp_lt_i32_e32 vcc, s1, v120
	v_mov_b32_e32 v211, 0
	s_nop 0
	v_cndmask_b32_e32 v0, 0, v120, vcc
	v_mad_i64_i32 v[4:5], s[2:3], v0, s6, v[2:3]
	s_and_saveexec_b64 s[98:99], vcc
	global_load_dword v211, v[4:5], off
	s_mov_b64 exec, s[98:99]
	v_cmp_lt_i32_e32 vcc, s1, v121
	v_mov_b32_e32 v212, 0
	s_nop 0
	v_cndmask_b32_e32 v0, 0, v121, vcc
	v_mad_i64_i32 v[4:5], s[2:3], v0, s6, v[2:3]
	s_and_saveexec_b64 s[98:99], vcc
	global_load_dword v212, v[4:5], off
	s_mov_b64 exec, s[98:99]
	v_cmp_lt_i32_e32 vcc, s1, v122
	v_mov_b32_e32 v213, 0
	s_nop 0
	v_cndmask_b32_e32 v0, 0, v122, vcc
	v_mad_i64_i32 v[4:5], s[2:3], v0, s6, v[2:3]
	s_and_saveexec_b64 s[98:99], vcc
	global_load_dword v213, v[4:5], off
	s_mov_b64 exec, s[98:99]
	v_cmp_lt_i32_e32 vcc, s1, v123
	v_mov_b32_e32 v214, 0
	s_nop 0
	v_cndmask_b32_e32 v0, 0, v123, vcc
	v_mad_i64_i32 v[4:5], s[2:3], v0, s6, v[2:3]
	s_and_saveexec_b64 s[98:99], vcc
	global_load_dword v214, v[4:5], off
	s_mov_b64 exec, s[98:99]
	v_cmp_lt_i32_e32 vcc, s1, v124
	v_mov_b32_e32 v215, 0
	s_nop 0
	v_cndmask_b32_e32 v0, 0, v124, vcc
	v_mad_i64_i32 v[4:5], s[2:3], v0, s6, v[2:3]
	s_and_saveexec_b64 s[98:99], vcc
	global_load_dword v215, v[4:5], off
	s_mov_b64 exec, s[98:99]
	v_cmp_lt_i32_e32 vcc, s1, v125
	v_mov_b32_e32 v216, 0
	s_nop 0
	v_cndmask_b32_e32 v0, 0, v125, vcc
	v_mad_i64_i32 v[4:5], s[2:3], v0, s6, v[2:3]
	s_and_saveexec_b64 s[98:99], vcc
	global_load_dword v216, v[4:5], off
	s_mov_b64 exec, s[98:99]
	v_cmp_lt_i32_e32 vcc, s1, v126
	v_mov_b32_e32 v218, 0
	s_nop 0
	v_cndmask_b32_e32 v0, 0, v126, vcc
	v_mad_i64_i32 v[4:5], s[2:3], v0, s6, v[2:3]
	s_and_saveexec_b64 s[98:99], vcc
	global_load_dword v218, v[4:5], off
	s_mov_b64 exec, s[98:99]
	v_cmp_lt_i32_e32 vcc, s1, v83
	v_mov_b32_e32 v217, 0
	s_nop 0
	v_cndmask_b32_e32 v0, 0, v83, vcc
	v_mad_i64_i32 v[4:5], s[2:3], v0, s6, v[2:3]
	s_and_saveexec_b64 s[98:99], vcc
	global_load_dword v217, v[4:5], off
	s_mov_b64 exec, s[98:99]
	v_cmp_gt_i32_e32 vcc, s1, v83
	s_nop 1
	v_cndmask_b32_e64 v0, v127, 0, vcc
	v_mad_i64_i32 v[4:5], s[2:3], v0, s6, v[2:3]
	global_load_dword v0, v[4:5], off
	s_waitcnt vmcnt(0)
	v_cndmask_b32_e64 v191, v0, 0, vcc
	v_cmp_lt_i32_e32 vcc, s1, v128
	v_mov_b32_e32 v210, 0
	s_nop 0
	v_cndmask_b32_e32 v0, 0, v128, vcc
	v_mad_i64_i32 v[4:5], s[2:3], v0, s6, v[2:3]
	s_and_saveexec_b64 s[98:99], vcc
	global_load_dword v210, v[4:5], off
	s_mov_b64 exec, s[98:99]
	v_cmp_lt_i32_e32 vcc, s1, v129
	v_mov_b32_e32 v209, 0
	s_nop 0
	v_cndmask_b32_e32 v0, 0, v129, vcc
	v_mad_i64_i32 v[4:5], s[2:3], v0, s6, v[2:3]
	s_and_saveexec_b64 s[98:99], vcc
	global_load_dword v209, v[4:5], off
	s_mov_b64 exec, s[98:99]
	v_cmp_lt_i32_e32 vcc, s1, v130
	v_mov_b32_e32 v208, 0
	s_nop 0
	v_cndmask_b32_e32 v0, 0, v130, vcc
	v_mad_i64_i32 v[4:5], s[2:3], v0, s6, v[2:3]
	s_and_saveexec_b64 s[98:99], vcc
	global_load_dword v208, v[4:5], off
	s_mov_b64 exec, s[98:99]
	v_cmp_lt_i32_e32 vcc, s1, v131
	v_mov_b32_e32 v207, 0
	s_nop 0
	v_cndmask_b32_e32 v0, 0, v131, vcc
	v_mad_i64_i32 v[4:5], s[2:3], v0, s6, v[2:3]
	s_and_saveexec_b64 s[98:99], vcc
	global_load_dword v207, v[4:5], off
	s_mov_b64 exec, s[98:99]
	v_cmp_lt_i32_e32 vcc, s1, v132
	v_mov_b32_e32 v206, 0
	s_nop 0
	v_cndmask_b32_e32 v0, 0, v132, vcc
	v_mad_i64_i32 v[4:5], s[2:3], v0, s6, v[2:3]
	s_and_saveexec_b64 s[98:99], vcc
	global_load_dword v206, v[4:5], off
	s_mov_b64 exec, s[98:99]
	v_cmp_lt_i32_e32 vcc, s1, v133
	v_mov_b32_e32 v205, 0
	s_nop 0
	v_cndmask_b32_e32 v0, 0, v133, vcc
	v_mad_i64_i32 v[4:5], s[2:3], v0, s6, v[2:3]
	s_and_saveexec_b64 s[98:99], vcc
	global_load_dword v205, v[4:5], off
	s_mov_b64 exec, s[98:99]
	v_cmp_lt_i32_e32 vcc, s1, v134
	v_mov_b32_e32 v204, 0
	s_nop 0
	v_cndmask_b32_e32 v0, 0, v134, vcc
	v_mad_i64_i32 v[4:5], s[2:3], v0, s6, v[2:3]
	s_and_saveexec_b64 s[98:99], vcc
	global_load_dword v204, v[4:5], off
	s_mov_b64 exec, s[98:99]
	v_cmp_lt_i32_e32 vcc, s1, v135
	v_mov_b32_e32 v192, 0
	s_nop 0
	v_cndmask_b32_e32 v0, 0, v135, vcc
	v_mad_i64_i32 v[4:5], s[2:3], v0, s6, v[2:3]
	s_and_saveexec_b64 s[98:99], vcc
	global_load_dword v192, v[4:5], off
	s_mov_b64 exec, s[98:99]
	v_cmp_lt_i32_e32 vcc, s1, v136
	v_mov_b32_e32 v190, 0
	s_nop 0
	v_cndmask_b32_e32 v0, 0, v136, vcc
	v_mad_i64_i32 v[4:5], s[2:3], v0, s6, v[2:3]
	s_and_saveexec_b64 s[98:99], vcc
	global_load_dword v190, v[4:5], off
	s_mov_b64 exec, s[98:99]
	v_cmp_lt_i32_e32 vcc, s1, v137
	v_mov_b32_e32 v189, 0
	s_nop 0
	v_cndmask_b32_e32 v0, 0, v137, vcc
	v_mad_i64_i32 v[4:5], s[2:3], v0, s6, v[2:3]
	s_and_saveexec_b64 s[98:99], vcc
	global_load_dword v189, v[4:5], off
	s_mov_b64 exec, s[98:99]
	v_cmp_lt_i32_e32 vcc, s1, v138
	v_mov_b32_e32 v188, 0
	s_nop 0
	v_cndmask_b32_e32 v0, 0, v138, vcc
	v_mad_i64_i32 v[4:5], s[2:3], v0, s6, v[2:3]
	s_and_saveexec_b64 s[98:99], vcc
	global_load_dword v188, v[4:5], off
	s_mov_b64 exec, s[98:99]
	v_cmp_lt_i32_e32 vcc, s1, v139
	v_mov_b32_e32 v187, 0
	s_nop 0
	v_cndmask_b32_e32 v0, 0, v139, vcc
	v_mad_i64_i32 v[4:5], s[2:3], v0, s6, v[2:3]
	s_and_saveexec_b64 s[98:99], vcc
	global_load_dword v187, v[4:5], off
	s_mov_b64 exec, s[98:99]
	v_cmp_lt_i32_e32 vcc, s1, v140
	s_and_b32 s1, s0, 0xf80
	s_nop 0
	v_cndmask_b32_e32 v0, 0, v140, vcc
	v_mad_i64_i32 v[2:3], s[2:3], v0, s6, v[2:3]
	global_load_dword v0, v[2:3], off
	v_add_u32_e32 v2, s94, v142
	v_ashrrev_i32_e32 v3, 31, v2
	v_lshlrev_b64 v[2:3], 12, v[2:3]
	s_waitcnt lgkmcnt(0)
	s_barrier
	v_lshl_add_u64 v[2:3], s[70:71], 0, v[2:3]
	s_mov_b64 s[2:3], 0x26000a00
	ds_read_b128 v[74:77], v185 offset:34816
	ds_read_b128 v[78:81], v185 offset:34848
	ds_read_b128 v[70:73], v185 offset:34880
	ds_read_b128 v[66:69], v185 offset:34912
	ds_read_b128 v[62:65], v185 offset:34944
	ds_read_b128 v[58:61], v185 offset:34976
	ds_read_b128 v[54:57], v185 offset:35008
	ds_read_b128 v[50:53], v185 offset:35040
	v_lshl_add_u64 v[106:107], v[2:3], 0, s[2:3]
	ds_read_b128 v[2:5], v183
	ds_read_b128 v[108:111], v183 offset:32
	ds_read_b128 v[228:231], v183 offset:64
	ds_read_b128 v[242:245], v183 offset:96
	s_waitcnt lgkmcnt(3)
	v_mfma_f32_32x32x16_bf16 v[2:17], v[2:5], v[74:77], 0
	s_waitcnt vmcnt(0)
	v_cndmask_b32_e32 v186, 0, v0, vcc
	s_waitcnt lgkmcnt(2)
	v_mfma_f32_32x32x16_bf16 v[2:17], v[108:111], v[78:81], v[2:17]
	ds_read_b128 v[108:111], v183 offset:128
	s_waitcnt lgkmcnt(2)
	v_mfma_f32_32x32x16_bf16 v[2:17], v[228:231], v[70:73], v[2:17]
	ds_read_b128 v[228:231], v183 offset:160
	s_waitcnt lgkmcnt(2)
	v_mfma_f32_32x32x16_bf16 v[2:17], v[242:245], v[66:69], v[2:17]
	ds_read_b128 v[242:245], v183 offset:192
	s_waitcnt lgkmcnt(2)
	v_mfma_f32_32x32x16_bf16 v[2:17], v[108:111], v[62:65], v[2:17]
	ds_read_b128 v[108:111], v183 offset:224
	s_waitcnt lgkmcnt(2)
	v_mfma_f32_32x32x16_bf16 v[2:17], v[228:231], v[58:61], v[2:17]
	s_waitcnt lgkmcnt(1)
	v_mfma_f32_32x32x16_bf16 v[2:17], v[242:245], v[54:57], v[2:17]
	s_waitcnt lgkmcnt(0)
	v_mfma_f32_32x32x16_bf16 v[2:17], v[108:111], v[50:53], v[2:17]
	v_lshlrev_b32_e32 v108, 1, v92
	v_mov_b32_e32 v109, v1
	s_nop 9
	v_mul_f32_e32 v0, v46, v2
	v_mul_f32_e32 v2, v47, v3
	v_cvt_pk_bf16_f32 v2, v0, v2
	v_mul_f32_e32 v0, v48, v4
	v_mul_f32_e32 v3, v49, v5
	v_cvt_pk_bf16_f32 v3, v0, v3
	v_lshlrev_b32_e32 v0, 1, v88
	v_lshl_add_u64 v[4:5], v[106:107], 0, v[0:1]
	global_store_dwordx2 v[4:5], v[2:3], off
	v_mul_f32_e32 v2, v42, v6
	v_mul_f32_e32 v3, v43, v7
	v_cvt_pk_bf16_f32 v2, v2, v3
	v_mul_f32_e32 v3, v44, v8
	v_mul_f32_e32 v4, v45, v9
	v_cvt_pk_bf16_f32 v3, v3, v4
	v_lshl_add_u64 v[4:5], v[106:107], 0, v[104:105]
	global_store_dwordx2 v[4:5], v[2:3], off
	v_mul_f32_e32 v2, v38, v10
	v_mul_f32_e32 v3, v39, v11
	v_cvt_pk_bf16_f32 v2, v2, v3
	v_mul_f32_e32 v3, v40, v12
	v_mul_f32_e32 v4, v41, v13
	v_cvt_pk_bf16_f32 v3, v3, v4
	v_lshl_add_u64 v[4:5], v[106:107], 0, v[108:109]
	global_store_dwordx2 v[4:5], v[2:3], off
	v_mul_f32_e32 v2, v34, v14
	v_mul_f32_e32 v3, v35, v15
	v_cvt_pk_bf16_f32 v2, v2, v3
	v_mul_f32_e32 v3, v36, v16
	v_mul_f32_e32 v4, v37, v17
	v_cvt_pk_bf16_f32 v3, v3, v4
	v_lshl_add_u64 v[4:5], v[106:107], 0, v[102:103]
	global_store_dwordx2 v[4:5], v[2:3], off
	ds_read_b128 v[228:231], v184
	ds_read_b128 v[242:245], v184 offset:32
	ds_read_b128 v[246:249], v184 offset:64
	s_waitcnt lgkmcnt(2)
	v_mfma_f32_32x32x16_bf16 v[2:17], v[228:231], v[74:77], 0
	ds_read_b128 v[228:231], v184 offset:96
	s_waitcnt lgkmcnt(2)
	v_mfma_f32_32x32x16_bf16 v[2:17], v[242:245], v[78:81], v[2:17]
	ds_read_b128 v[242:245], v184 offset:128
	v_lshlrev_b32_e32 v110, 1, v94
	v_mov_b32_e32 v111, v1
	v_lshlrev_b32_e32 v112, 1, v96
	v_mov_b32_e32 v113, v1
	s_waitcnt lgkmcnt(2)
	v_mfma_f32_32x32x16_bf16 v[2:17], v[246:249], v[70:73], v[2:17]
	ds_read_b128 v[246:249], v184 offset:160
	s_waitcnt lgkmcnt(2)
	v_mfma_f32_32x32x16_bf16 v[2:17], v[228:231], v[66:69], v[2:17]
	ds_read_b128 v[228:231], v184 offset:192
	s_waitcnt lgkmcnt(2)
	v_mfma_f32_32x32x16_bf16 v[2:17], v[242:245], v[62:65], v[2:17]
	ds_read_b128 v[242:245], v184 offset:224
	s_waitcnt lgkmcnt(2)
	v_mfma_f32_32x32x16_bf16 v[2:17], v[246:249], v[58:61], v[2:17]
	s_waitcnt lgkmcnt(1)
	v_mfma_f32_32x32x16_bf16 v[2:17], v[228:231], v[54:57], v[2:17]
	s_waitcnt lgkmcnt(0)
	v_mfma_f32_32x32x16_bf16 v[2:17], v[242:245], v[50:53], v[2:17]
	v_add_u32_e32 v52, s1, v83
	v_min_i32_e32 v52, 7, v52
	v_add_u32_e32 v52, 1, v52
	v_cvt_f32_i32_e32 v52, v52
	v_lshlrev_b32_e32 v50, 16, v217
	v_and_b32_e32 v51, 0xffff0000, v217
	s_nop 5
	v_mul_f32_e32 v2, v30, v2
	v_mul_f32_e32 v3, v31, v3
	v_cvt_pk_bf16_f32 v2, v2, v3
	v_mul_f32_e32 v3, v32, v4
	v_mul_f32_e32 v4, v33, v5
	v_cvt_pk_bf16_f32 v3, v3, v4
	v_lshl_add_u64 v[4:5], v[106:107], 0, v[110:111]
	global_store_dwordx2 v[4:5], v[2:3], off
	v_mul_f32_e32 v2, v26, v6
	v_mul_f32_e32 v3, v27, v7
	v_cvt_pk_bf16_f32 v2, v2, v3
	v_mul_f32_e32 v3, v28, v8
	v_mul_f32_e32 v4, v29, v9
	v_cvt_pk_bf16_f32 v3, v3, v4
	v_lshl_add_u64 v[4:5], v[106:107], 0, v[112:113]
	global_store_dwordx2 v[4:5], v[2:3], off
	v_mul_f32_e32 v2, v22, v10
	v_mul_f32_e32 v3, v23, v11
	v_cvt_pk_bf16_f32 v2, v2, v3
	v_mul_f32_e32 v3, v24, v12
	v_mul_f32_e32 v4, v25, v13
	v_cvt_pk_bf16_f32 v3, v3, v4
	v_lshl_add_u64 v[4:5], v[106:107], 0, v[114:115]
	global_store_dwordx2 v[4:5], v[2:3], off
	v_mul_f32_e32 v2, v18, v14
	v_mul_f32_e32 v3, v19, v15
	v_cvt_pk_bf16_f32 v2, v2, v3
	v_mul_f32_e32 v3, v20, v16
	v_mul_f32_e32 v4, v21, v17
	v_cvt_pk_bf16_f32 v3, v3, v4
	v_lshlrev_b32_e32 v4, 1, v100
	v_mov_b32_e32 v5, v1
	v_lshl_add_u64 v[4:5], v[106:107], 0, v[4:5]
	global_store_dwordx2 v[4:5], v[2:3], off
	v_lshlrev_b32_e32 v2, 16, v211
	v_and_b32_e32 v4, 0xffff0000, v211
	v_add_f32_e32 v3, 0, v2
	v_add_f32_e32 v5, 0, v4
	v_lshlrev_b32_e32 v6, 16, v212
	v_and_b32_e32 v7, 0xffff0000, v212
	v_add_f32_e32 v3, v3, v6
	v_add_f32_e32 v5, v5, v7
	v_lshlrev_b32_e32 v8, 16, v213
	v_and_b32_e32 v9, 0xffff0000, v213
	v_add_f32_e32 v3, v3, v8
	v_add_f32_e32 v5, v5, v9
	v_lshlrev_b32_e32 v10, 16, v214
	v_and_b32_e32 v11, 0xffff0000, v214
	v_add_f32_e32 v3, v3, v10
	v_add_f32_e32 v5, v5, v11
	v_lshlrev_b32_e32 v12, 16, v215
	v_and_b32_e32 v13, 0xffff0000, v215
	v_add_f32_e32 v3, v3, v12
	v_add_f32_e32 v5, v5, v13
	v_lshlrev_b32_e32 v14, 16, v216
	v_and_b32_e32 v15, 0xffff0000, v216
	v_rcp_iflag_f32_e32 v52, v52
	v_add_f32_e32 v3, v3, v14
	v_add_f32_e32 v5, v5, v15
	v_lshlrev_b32_e32 v16, 16, v218
	v_and_b32_e32 v17, 0xffff0000, v218
	v_add_f32_e32 v3, v3, v16
	v_add_f32_e32 v5, v5, v17
	v_add_f32_e32 v3, v3, v50
	v_add_f32_e32 v5, v5, v51
	v_fma_f32 v53, v52, v3, -v50
	v_fma_f32 v52, v52, v5, -v51
	v_cvt_pk_bf16_f32 v52, v53, v52
	s_waitcnt lgkmcnt(0)
	s_barrier
	ds_write_b32 v116, v52 offset:34816
	v_add_u32_e32 v52, s1, v127
	v_min_i32_e32 v52, 7, v52
	v_add_u32_e32 v52, 1, v52
	v_cvt_f32_i32_e32 v52, v52
	v_sub_f32_e32 v2, v3, v2
	v_sub_f32_e32 v3, v5, v4
	v_lshlrev_b32_e32 v4, 16, v191
	v_rcp_iflag_f32_e32 v52, v52
	v_and_b32_e32 v5, 0xffff0000, v191
	v_add_f32_e32 v2, v2, v4
	v_add_f32_e32 v3, v3, v5
	v_fma_f32 v53, v52, v2, -v4
	v_fma_f32 v52, v52, v3, -v5
	v_cvt_pk_bf16_f32 v52, v53, v52
	ds_write_b32 v117, v52 offset:34816
	v_add_u32_e32 v52, s1, v128
	v_min_i32_e32 v52, 7, v52
	v_add_u32_e32 v52, 1, v52
	v_cvt_f32_i32_e32 v52, v52
	v_sub_f32_e32 v2, v2, v6
	v_sub_f32_e32 v3, v3, v7
	v_lshlrev_b32_e32 v6, 16, v210
	v_rcp_iflag_f32_e32 v52, v52
	v_and_b32_e32 v7, 0xffff0000, v210
	v_add_f32_e32 v2, v2, v6
	v_add_f32_e32 v3, v3, v7
	v_fma_f32 v53, v52, v2, -v6
	v_fma_f32 v52, v52, v3, -v7
	v_cvt_pk_bf16_f32 v52, v53, v52
	ds_write_b32 v168, v52 offset:34816
	v_add_u32_e32 v52, s1, v129
	v_min_i32_e32 v52, 7, v52
	v_add_u32_e32 v52, 1, v52
	v_cvt_f32_i32_e32 v52, v52
	v_sub_f32_e32 v2, v2, v8
	v_sub_f32_e32 v3, v3, v9
	v_lshlrev_b32_e32 v8, 16, v209
	v_rcp_iflag_f32_e32 v52, v52
	v_and_b32_e32 v9, 0xffff0000, v209
	v_add_f32_e32 v2, v2, v8
	v_add_f32_e32 v3, v3, v9
	v_fma_f32 v53, v52, v2, -v8
	v_fma_f32 v52, v52, v3, -v9
	v_cvt_pk_bf16_f32 v52, v53, v52
	ds_write_b32 v169, v52 offset:34816
	v_add_u32_e32 v52, s1, v130
	v_min_i32_e32 v52, 7, v52
	v_add_u32_e32 v52, 1, v52
	v_cvt_f32_i32_e32 v52, v52
	v_sub_f32_e32 v2, v2, v10
	v_sub_f32_e32 v3, v3, v11
	v_lshlrev_b32_e32 v10, 16, v208
	v_rcp_iflag_f32_e32 v52, v52
	v_and_b32_e32 v11, 0xffff0000, v208
	v_add_f32_e32 v2, v2, v10
	v_add_f32_e32 v3, v3, v11
	v_fma_f32 v53, v52, v2, -v10
	v_fma_f32 v52, v52, v3, -v11
	v_cvt_pk_bf16_f32 v52, v53, v52
	ds_write_b32 v170, v52 offset:34816
	v_add_u32_e32 v52, s1, v131
	v_min_i32_e32 v52, 7, v52
	v_add_u32_e32 v52, 1, v52
	v_cvt_f32_i32_e32 v52, v52
	v_sub_f32_e32 v2, v2, v12
	v_sub_f32_e32 v3, v3, v13
	v_lshlrev_b32_e32 v12, 16, v207
	v_rcp_iflag_f32_e32 v52, v52
	v_and_b32_e32 v13, 0xffff0000, v207
	v_add_f32_e32 v2, v2, v12
	v_add_f32_e32 v3, v3, v13
	v_fma_f32 v53, v52, v2, -v12
	v_fma_f32 v52, v52, v3, -v13
	v_cvt_pk_bf16_f32 v52, v53, v52
	ds_write_b32 v171, v52 offset:34816
	v_add_u32_e32 v52, s1, v132
	v_min_i32_e32 v52, 7, v52
	v_add_u32_e32 v52, 1, v52
	v_cvt_f32_i32_e32 v52, v52
	v_sub_f32_e32 v2, v2, v14
	v_sub_f32_e32 v3, v3, v15
	v_lshlrev_b32_e32 v14, 16, v206
	v_rcp_iflag_f32_e32 v52, v52
	v_and_b32_e32 v15, 0xffff0000, v206
	v_add_f32_e32 v2, v2, v14
	v_add_f32_e32 v3, v3, v15
	v_fma_f32 v53, v52, v2, -v14
	v_fma_f32 v52, v52, v3, -v15
	v_cvt_pk_bf16_f32 v52, v53, v52
	ds_write_b32 v172, v52 offset:34816
	v_add_u32_e32 v52, s1, v133
	v_min_i32_e32 v52, 7, v52
	v_add_u32_e32 v52, 1, v52
	v_cvt_f32_i32_e32 v52, v52
	v_sub_f32_e32 v2, v2, v16
	v_sub_f32_e32 v3, v3, v17
	v_lshlrev_b32_e32 v16, 16, v205
	v_rcp_iflag_f32_e32 v52, v52
	v_and_b32_e32 v17, 0xffff0000, v205
	v_add_f32_e32 v2, v2, v16
	v_add_f32_e32 v3, v3, v17
	v_fma_f32 v53, v52, v2, -v16
	v_fma_f32 v52, v52, v3, -v17
	v_cvt_pk_bf16_f32 v52, v53, v52
	ds_write_b32 v173, v52 offset:34816
	v_add_u32_e32 v52, s1, v134
	v_min_i32_e32 v52, 7, v52
	v_add_u32_e32 v52, 1, v52
	v_cvt_f32_i32_e32 v52, v52
	v_sub_f32_e32 v2, v2, v50
	v_lshlrev_b32_e32 v50, 16, v204
	v_sub_f32_e32 v3, v3, v51
	v_rcp_iflag_f32_e32 v52, v52
	v_and_b32_e32 v51, 0xffff0000, v204
	v_add_f32_e32 v2, v2, v50
	v_add_f32_e32 v3, v3, v51
	v_fma_f32 v50, v52, v2, -v50
	v_fma_f32 v51, v52, v3, -v51
	v_cvt_pk_bf16_f32 v50, v50, v51
	ds_write_b32 v174, v50 offset:34816
	v_add_u32_e32 v50, s1, v135
	v_min_i32_e32 v50, 7, v50
	v_add_u32_e32 v50, 1, v50
	v_cvt_f32_i32_e32 v50, v50
	v_sub_f32_e32 v2, v2, v4
	v_lshlrev_b32_e32 v4, 16, v192
	v_add_f32_e32 v2, v2, v4
	v_rcp_iflag_f32_e32 v50, v50
	v_sub_f32_e32 v3, v3, v5
	v_and_b32_e32 v5, 0xffff0000, v192
	v_add_f32_e32 v3, v3, v5
	v_fma_f32 v4, v50, v2, -v4
	v_sub_f32_e32 v2, v2, v6
	v_add_u32_e32 v6, s1, v136
	v_min_i32_e32 v6, 7, v6
	v_add_u32_e32 v6, 1, v6
	v_cvt_f32_i32_e32 v6, v6
	v_fma_f32 v5, v50, v3, -v5
	v_cvt_pk_bf16_f32 v4, v4, v5
	ds_write_b32 v175, v4 offset:34816
	v_rcp_iflag_f32_e32 v6, v6
	v_sub_f32_e32 v3, v3, v7
	v_lshlrev_b32_e32 v4, 16, v190
	v_and_b32_e32 v5, 0xffff0000, v190
	v_add_f32_e32 v2, v2, v4
	v_add_f32_e32 v3, v3, v5
	v_fma_f32 v4, v6, v2, -v4
	v_fma_f32 v5, v6, v3, -v5
	v_add_u32_e32 v6, s1, v137
	v_min_i32_e32 v6, 7, v6
	v_add_u32_e32 v6, 1, v6
	v_cvt_f32_i32_e32 v6, v6
	v_cvt_pk_bf16_f32 v4, v4, v5
	ds_write_b32 v176, v4 offset:34816
	v_sub_f32_e32 v2, v2, v8
	v_rcp_iflag_f32_e32 v6, v6
	v_sub_f32_e32 v3, v3, v9
	v_lshlrev_b32_e32 v4, 16, v189
	v_and_b32_e32 v5, 0xffff0000, v189
	v_add_f32_e32 v2, v2, v4
	v_add_f32_e32 v3, v3, v5
	v_fma_f32 v4, v6, v2, -v4
	v_fma_f32 v5, v6, v3, -v5
	v_add_u32_e32 v6, s1, v138
	v_min_i32_e32 v6, 7, v6
	v_add_u32_e32 v6, 1, v6
	v_cvt_f32_i32_e32 v6, v6
	v_cvt_pk_bf16_f32 v4, v4, v5
	ds_write_b32 v177, v4 offset:34816
	v_sub_f32_e32 v2, v2, v10
	v_rcp_iflag_f32_e32 v6, v6
	v_sub_f32_e32 v3, v3, v11
	v_lshlrev_b32_e32 v4, 16, v188
	v_and_b32_e32 v5, 0xffff0000, v188
	v_add_f32_e32 v2, v2, v4
	v_add_f32_e32 v3, v3, v5
	v_fma_f32 v4, v6, v2, -v4
	v_fma_f32 v5, v6, v3, -v5
	v_add_u32_e32 v6, s1, v139
	v_min_i32_e32 v6, 7, v6
	v_add_u32_e32 v6, 1, v6
	v_cvt_f32_i32_e32 v6, v6
	v_cvt_pk_bf16_f32 v4, v4, v5
	ds_write_b32 v178, v4 offset:34816
	v_sub_f32_e32 v2, v2, v12
	v_rcp_iflag_f32_e32 v6, v6
	v_sub_f32_e32 v3, v3, v13
	v_lshlrev_b32_e32 v4, 16, v187
	v_and_b32_e32 v5, 0xffff0000, v187
	v_add_f32_e32 v2, v2, v4
	v_add_f32_e32 v3, v3, v5
	v_fma_f32 v4, v6, v2, -v4
	v_fma_f32 v5, v6, v3, -v5
	v_add_u32_e32 v6, s1, v140
	v_min_i32_e32 v6, 7, v6
	v_add_u32_e32 v6, 1, v6
	v_cvt_f32_i32_e32 v6, v6
	v_cvt_pk_bf16_f32 v4, v4, v5
	ds_write_b32 v179, v4 offset:34816
	v_sub_f32_e32 v2, v2, v14
	v_rcp_iflag_f32_e32 v6, v6
	v_sub_f32_e32 v3, v3, v15
	v_lshlrev_b32_e32 v4, 16, v186
	v_and_b32_e32 v5, 0xffff0000, v186
	v_add_f32_e32 v2, v2, v4
	v_add_f32_e32 v3, v3, v5
	v_fma_f32 v4, v6, v2, -v4
	v_fma_f32 v5, v6, v3, -v5
	v_add_u32_e32 v6, s1, v141
	v_min_i32_e32 v6, 7, v6
	v_add_u32_e32 v6, 1, v6
	v_cvt_f32_i32_e32 v6, v6
	v_cvt_pk_bf16_f32 v4, v4, v5
	ds_write_b32 v180, v4 offset:34816
	v_sub_f32_e32 v2, v2, v16
	v_rcp_iflag_f32_e32 v6, v6
	v_lshlrev_b32_e32 v4, 16, v182
	v_sub_f32_e32 v3, v3, v17
	v_and_b32_e32 v5, 0xffff0000, v182
	v_add_f32_e32 v2, v2, v4
	v_add_f32_e32 v3, v3, v5
	v_fma_f32 v2, v6, v2, -v4
	v_fma_f32 v3, v6, v3, -v5
	v_cvt_pk_bf16_f32 v2, v2, v3
	ds_write_b32 v181, v2 offset:34816
	v_add_u32_e32 v2, s0, v142
	v_ashrrev_i32_e32 v3, 31, v2
	v_lshlrev_b64 v[2:3], 12, v[2:3]
	s_waitcnt lgkmcnt(0)
	s_barrier
	v_lshl_add_u64 v[2:3], s[70:71], 0, v[2:3]
	ds_read_b128 v[74:77], v185 offset:34816
	ds_read_b128 v[78:81], v185 offset:34848
	ds_read_b128 v[70:73], v185 offset:34880
	ds_read_b128 v[66:69], v185 offset:34912
	ds_read_b128 v[62:65], v185 offset:34944
	ds_read_b128 v[58:61], v185 offset:34976
	ds_read_b128 v[54:57], v185 offset:35008
	ds_read_b128 v[50:53], v185 offset:35040
	v_lshl_add_u64 v[106:107], v[2:3], 0, s[2:3]
	ds_read_b128 v[2:5], v183
	ds_read_b128 v[168:171], v183 offset:32
	ds_read_b128 v[228:231], v183 offset:64
	ds_read_b128 v[242:245], v183 offset:96
	s_waitcnt lgkmcnt(3)
	v_mfma_f32_32x32x16_bf16 v[2:17], v[2:5], v[74:77], 0
	s_waitcnt lgkmcnt(2)
	v_mfma_f32_32x32x16_bf16 v[2:17], v[168:171], v[78:81], v[2:17]
	ds_read_b128 v[168:171], v183 offset:128
	s_waitcnt lgkmcnt(2)
	v_mfma_f32_32x32x16_bf16 v[2:17], v[228:231], v[70:73], v[2:17]
	ds_read_b128 v[228:231], v183 offset:160
	s_waitcnt lgkmcnt(2)
	v_mfma_f32_32x32x16_bf16 v[2:17], v[242:245], v[66:69], v[2:17]
	ds_read_b128 v[242:245], v183 offset:192
	s_waitcnt lgkmcnt(2)
	v_mfma_f32_32x32x16_bf16 v[2:17], v[168:171], v[62:65], v[2:17]
	ds_read_b128 v[168:171], v183 offset:224
	s_waitcnt lgkmcnt(2)
	v_mfma_f32_32x32x16_bf16 v[2:17], v[228:231], v[58:61], v[2:17]
	s_waitcnt lgkmcnt(1)
	v_mfma_f32_32x32x16_bf16 v[2:17], v[242:245], v[54:57], v[2:17]
	s_waitcnt lgkmcnt(0)
	v_mfma_f32_32x32x16_bf16 v[2:17], v[168:171], v[50:53], v[2:17]
	s_nop 11
	v_mul_f32_e32 v2, v46, v2
	v_mul_f32_e32 v3, v47, v3
	v_cvt_pk_bf16_f32 v2, v2, v3
	v_mul_f32_e32 v3, v48, v4
	v_mul_f32_e32 v4, v49, v5
	v_cvt_pk_bf16_f32 v3, v3, v4
	v_lshl_add_u64 v[4:5], v[106:107], 0, v[0:1]
	global_store_dwordx2 v[4:5], v[2:3], off
	v_mul_f32_e32 v0, v42, v6
	v_mul_f32_e32 v2, v43, v7
	v_mul_f32_e32 v3, v45, v9
	v_cvt_pk_bf16_f32 v2, v0, v2
	v_mul_f32_e32 v0, v44, v8
	v_cvt_pk_bf16_f32 v3, v0, v3
	v_lshl_add_u64 v[4:5], v[106:107], 0, v[104:105]
	global_store_dwordx2 v[4:5], v[2:3], off
	v_mul_f32_e32 v0, v38, v10
	v_mul_f32_e32 v2, v39, v11
	v_mul_f32_e32 v3, v41, v13
	v_cvt_pk_bf16_f32 v2, v0, v2
	v_mul_f32_e32 v0, v40, v12
	v_cvt_pk_bf16_f32 v3, v0, v3
	v_lshl_add_u64 v[4:5], v[106:107], 0, v[108:109]
	global_store_dwordx2 v[4:5], v[2:3], off
	v_mul_f32_e32 v0, v34, v14
	v_mul_f32_e32 v2, v35, v15
	v_mul_f32_e32 v3, v37, v17
	v_lshl_add_u64 v[4:5], v[106:107], 0, v[102:103]
	v_cvt_pk_bf16_f32 v2, v0, v2
	v_mul_f32_e32 v0, v36, v16
	v_cvt_pk_bf16_f32 v3, v0, v3
	global_store_dwordx2 v[4:5], v[2:3], off
	ds_read_b128 v[2:5], v184
	ds_read_b128 v[34:37], v184 offset:32
	ds_read_b128 v[228:231], v184 offset:64
	ds_read_b128 v[242:245], v184 offset:96
	s_waitcnt lgkmcnt(3)
	v_mfma_f32_32x32x16_bf16 v[2:17], v[2:5], v[74:77], 0
	s_waitcnt lgkmcnt(2)
	v_mfma_f32_32x32x16_bf16 v[2:17], v[34:37], v[78:81], v[2:17]
	ds_read_b128 v[34:37], v184 offset:128
	s_waitcnt lgkmcnt(2)
	v_mfma_f32_32x32x16_bf16 v[2:17], v[228:231], v[70:73], v[2:17]
	ds_read_b128 v[228:231], v184 offset:160
	s_waitcnt lgkmcnt(2)
	v_mfma_f32_32x32x16_bf16 v[2:17], v[242:245], v[66:69], v[2:17]
	ds_read_b128 v[242:245], v184 offset:192
	s_waitcnt lgkmcnt(2)
	v_mfma_f32_32x32x16_bf16 v[2:17], v[34:37], v[62:65], v[2:17]
	ds_read_b128 v[34:37], v184 offset:224
	s_waitcnt lgkmcnt(2)
	v_mfma_f32_32x32x16_bf16 v[2:17], v[228:231], v[58:61], v[2:17]
	s_waitcnt lgkmcnt(1)
	v_mfma_f32_32x32x16_bf16 v[2:17], v[242:245], v[54:57], v[2:17]
	s_waitcnt lgkmcnt(0)
	v_mfma_f32_32x32x16_bf16 v[2:17], v[34:37], v[50:53], v[2:17]
	s_nop 11
	v_mul_f32_e32 v0, v30, v2
	v_mul_f32_e32 v2, v31, v3
	v_mul_f32_e32 v3, v33, v5
	v_cvt_pk_bf16_f32 v2, v0, v2
	v_mul_f32_e32 v0, v32, v4
	v_cvt_pk_bf16_f32 v3, v0, v3
	v_lshl_add_u64 v[4:5], v[106:107], 0, v[110:111]
	global_store_dwordx2 v[4:5], v[2:3], off
	v_mul_f32_e32 v0, v26, v6
	v_mul_f32_e32 v2, v27, v7
	v_mul_f32_e32 v3, v29, v9
	v_cvt_pk_bf16_f32 v2, v0, v2
	v_mul_f32_e32 v0, v28, v8
	v_cvt_pk_bf16_f32 v3, v0, v3
	v_lshl_add_u64 v[4:5], v[106:107], 0, v[112:113]
	global_store_dwordx2 v[4:5], v[2:3], off
	v_mul_f32_e32 v0, v22, v10
	v_mul_f32_e32 v2, v23, v11
	v_mul_f32_e32 v3, v25, v13
	v_cvt_pk_bf16_f32 v2, v0, v2
	v_mul_f32_e32 v0, v24, v12
	v_cvt_pk_bf16_f32 v3, v0, v3
	v_lshl_add_u64 v[4:5], v[106:107], 0, v[114:115]
	global_store_dwordx2 v[4:5], v[2:3], off
	v_mul_f32_e32 v0, v18, v14
	v_mul_f32_e32 v2, v19, v15
	v_mul_f32_e32 v3, v21, v17
	v_cvt_pk_bf16_f32 v2, v0, v2
	v_mul_f32_e32 v0, v20, v16
	v_cvt_pk_bf16_f32 v3, v0, v3

.LBB0_227:
	s_or_b64 exec, exec, s[40:41]
	v_add_u32_e32 v54, s95, v83
	v_min_i32_e32 v54, 1, v54
	v_add_u32_e32 v54, 1, v54
	v_cvt_f32_i32_e32 v54, v54
	s_waitcnt vmcnt(24)
	v_cndmask_b32_e32 v9, 0, v9, vcc
	s_waitcnt vmcnt(8)
	v_cndmask_b32_e64 v0, 0, v50, s[34:35]
	v_cndmask_b32_e64 v10, 0, v10, s[0:1]
	v_rcp_iflag_f32_e32 v54, v54
	v_lshlrev_b32_e32 v50, 16, v9
	v_and_b32_e32 v9, 0xffff0000, v9
	v_add_f32_e32 v51, 0, v50
	v_add_f32_e32 v52, 0, v9
	v_lshlrev_b32_e32 v53, 16, v10
	v_and_b32_e32 v10, 0xffff0000, v10
	v_add_f32_e32 v51, v51, v53
	v_add_f32_e32 v52, v52, v10
	v_fma_f32 v55, v54, v51, -v53
	v_fma_f32 v54, v54, v52, -v10
	v_sub_f32_e32 v9, v52, v9
	v_add_u32_e32 v52, s95, v127
	v_min_i32_e32 v52, 1, v52
	v_add_u32_e32 v52, 1, v52
	v_cvt_f32_i32_e32 v52, v52
	v_cndmask_b32_e64 v11, v11, 0, s[2:3]
	v_sub_f32_e32 v50, v51, v50
	v_lshlrev_b32_e32 v51, 16, v11
	v_rcp_iflag_f32_e32 v52, v52
	v_and_b32_e32 v11, 0xffff0000, v11
	v_cvt_pk_bf16_f32 v54, v55, v54
	v_add_u32_e32 v168, 0, v145
	v_add_f32_e32 v50, v50, v51
	v_add_f32_e32 v9, v9, v11
	s_waitcnt lgkmcnt(0)
	s_barrier
	ds_write_b32 v168, v54 offset:34816
	v_fma_f32 v54, v52, v50, -v51
	v_fma_f32 v52, v52, v9, -v11
	v_cvt_pk_bf16_f32 v52, v54, v52
	v_add_u32_e32 v169, 0, v146
	ds_write_b32 v169, v52 offset:34816
	v_add_u32_e32 v52, s95, v128
	v_min_i32_e32 v52, 1, v52
	v_add_u32_e32 v52, 1, v52
	v_cvt_f32_i32_e32 v52, v52
	v_cndmask_b32_e64 v12, 0, v12, s[6:7]
	v_sub_f32_e32 v50, v50, v53
	v_sub_f32_e32 v9, v9, v10
	v_rcp_iflag_f32_e32 v52, v52
	v_lshlrev_b32_e32 v10, 16, v12
	v_add_f32_e32 v50, v50, v10
	v_and_b32_e32 v12, 0xffff0000, v12
	v_fma_f32 v53, v52, v50, -v10
	v_sub_f32_e32 v50, v50, v51
	v_add_u32_e32 v51, s95, v129
	v_min_i32_e32 v51, 1, v51
	v_add_u32_e32 v51, 1, v51
	v_cvt_f32_i32_e32 v51, v51
	v_cndmask_b32_e64 v13, 0, v13, s[8:9]
	v_add_f32_e32 v9, v9, v12
	v_fma_f32 v52, v52, v9, -v12
	v_rcp_iflag_f32_e32 v51, v51
	v_sub_f32_e32 v9, v9, v11
	v_lshlrev_b32_e32 v11, 16, v13
	v_cvt_pk_bf16_f32 v52, v53, v52
	v_add_u32_e32 v170, 0, v147
	v_add_f32_e32 v50, v50, v11
	ds_write_b32 v170, v52 offset:34816
	v_fma_f32 v52, v51, v50, -v11
	v_sub_f32_e32 v10, v50, v10
	v_add_u32_e32 v50, s95, v130
	v_min_i32_e32 v50, 1, v50
	v_add_u32_e32 v50, 1, v50
	v_cvt_f32_i32_e32 v50, v50
	v_and_b32_e32 v13, 0xffff0000, v13
	v_cndmask_b32_e64 v14, 0, v14, s[10:11]
	v_add_f32_e32 v9, v9, v13
	v_rcp_iflag_f32_e32 v50, v50
	v_fma_f32 v51, v51, v9, -v13
	v_sub_f32_e32 v9, v9, v12
	v_lshlrev_b32_e32 v12, 16, v14
	v_and_b32_e32 v14, 0xffff0000, v14
	v_cndmask_b32_e64 v15, 0, v15, s[12:13]
	v_cvt_pk_bf16_f32 v51, v52, v51
	v_add_u32_e32 v171, 0, v148
	v_add_f32_e32 v10, v10, v12
	v_add_f32_e32 v9, v9, v14
	ds_write_b32 v171, v51 offset:34816
	v_fma_f32 v51, v50, v10, -v12
	v_fma_f32 v50, v50, v9, -v14
	v_sub_f32_e32 v10, v10, v11
	v_sub_f32_e32 v9, v9, v13
	v_lshlrev_b32_e32 v11, 16, v15
	v_and_b32_e32 v13, 0xffff0000, v15
	v_add_u32_e32 v15, s95, v131
	v_min_i32_e32 v15, 1, v15
	v_add_u32_e32 v15, 1, v15
	v_cvt_f32_i32_e32 v15, v15
	v_cvt_pk_bf16_f32 v50, v51, v50
	v_add_u32_e32 v172, 0, v149
	v_add_f32_e32 v10, v10, v11
	v_rcp_iflag_f32_e32 v15, v15
	v_add_f32_e32 v9, v9, v13
	ds_write_b32 v172, v50 offset:34816
	v_add_u32_e32 v173, 0, v150
	v_fma_f32 v50, v15, v10, -v11
	v_fma_f32 v15, v15, v9, -v13
	v_cvt_pk_bf16_f32 v15, v50, v15
	ds_write_b32 v173, v15 offset:34816
	v_add_u32_e32 v15, s95, v132
	v_min_i32_e32 v15, 1, v15
	v_add_u32_e32 v15, 1, v15
	v_cvt_f32_i32_e32 v15, v15
	v_cndmask_b32_e64 v16, 0, v16, s[14:15]
	v_sub_f32_e32 v10, v10, v12
	v_sub_f32_e32 v9, v9, v14
	v_rcp_iflag_f32_e32 v15, v15
	v_lshlrev_b32_e32 v12, 16, v16
	v_and_b32_e32 v14, 0xffff0000, v16
	v_add_f32_e32 v10, v10, v12
	v_add_f32_e32 v9, v9, v14
	v_fma_f32 v16, v15, v10, -v12
	v_fma_f32 v15, v15, v9, -v14
	v_cvt_pk_bf16_f32 v15, v16, v15
	v_add_u32_e32 v174, 0, v151
	ds_write_b32 v174, v15 offset:34816
	v_add_u32_e32 v15, s95, v133
	v_min_i32_e32 v15, 1, v15
	v_add_u32_e32 v15, 1, v15
	v_cvt_f32_i32_e32 v15, v15
	v_cndmask_b32_e64 v17, 0, v17, s[16:17]
	v_sub_f32_e32 v10, v10, v11
	v_sub_f32_e32 v9, v9, v13
	v_rcp_iflag_f32_e32 v15, v15
	v_lshlrev_b32_e32 v11, 16, v17
	v_and_b32_e32 v13, 0xffff0000, v17
	v_add_f32_e32 v10, v10, v11
	v_add_f32_e32 v9, v9, v13
	v_fma_f32 v16, v15, v10, -v11
	v_fma_f32 v15, v15, v9, -v13
	v_sub_f32_e32 v9, v9, v14
	v_add_u32_e32 v14, s95, v134
	v_min_i32_e32 v14, 1, v14
	v_add_u32_e32 v14, 1, v14
	v_cvt_f32_i32_e32 v14, v14
	v_cndmask_b32_e64 v8, 0, v8, s[18:19]
	v_sub_f32_e32 v10, v10, v12
	v_lshlrev_b32_e32 v12, 16, v8
	v_rcp_iflag_f32_e32 v14, v14
	v_and_b32_e32 v8, 0xffff0000, v8
	v_cvt_pk_bf16_f32 v15, v16, v15
	v_add_u32_e32 v175, 0, v152
	v_add_f32_e32 v10, v10, v12
	v_add_f32_e32 v9, v9, v8
	ds_write_b32 v175, v15 offset:34816
	v_fma_f32 v15, v14, v10, -v12
	v_fma_f32 v14, v14, v9, -v8
	v_sub_f32_e32 v9, v9, v13
	v_add_u32_e32 v13, s95, v135
	v_min_i32_e32 v13, 1, v13
	v_add_u32_e32 v13, 1, v13
	v_cvt_f32_i32_e32 v13, v13
	v_cndmask_b32_e64 v7, 0, v7, s[20:21]
	v_sub_f32_e32 v10, v10, v11
	v_lshlrev_b32_e32 v11, 16, v7
	v_rcp_iflag_f32_e32 v13, v13
	v_cvt_pk_bf16_f32 v14, v15, v14
	v_add_u32_e32 v176, 0, v153
	v_add_f32_e32 v10, v10, v11
	ds_write_b32 v176, v14 offset:34816
	v_fma_f32 v14, v13, v10, -v11
	v_sub_f32_e32 v10, v10, v12
	v_add_u32_e32 v12, s95, v136
	v_min_i32_e32 v12, 1, v12
	v_add_u32_e32 v12, 1, v12
	v_cvt_f32_i32_e32 v12, v12
	v_and_b32_e32 v7, 0xffff0000, v7
	v_cndmask_b32_e64 v6, 0, v6, s[22:23]
	v_add_f32_e32 v9, v9, v7
	v_rcp_iflag_f32_e32 v12, v12
	v_fma_f32 v13, v13, v9, -v7
	v_sub_f32_e32 v8, v9, v8
	v_lshlrev_b32_e32 v9, 16, v6
	v_cvt_pk_bf16_f32 v13, v14, v13
	v_add_u32_e32 v177, 0, v154
	v_add_f32_e32 v10, v10, v9
	ds_write_b32 v177, v13 offset:34816
	v_fma_f32 v13, v12, v10, -v9
	v_sub_f32_e32 v10, v10, v11
	v_add_u32_e32 v11, s95, v137
	v_min_i32_e32 v11, 1, v11
	v_add_u32_e32 v11, 1, v11
	v_cvt_f32_i32_e32 v11, v11
	v_and_b32_e32 v6, 0xffff0000, v6
	v_cndmask_b32_e64 v5, 0, v5, s[24:25]
	v_add_f32_e32 v8, v8, v6
	v_rcp_iflag_f32_e32 v11, v11
	v_fma_f32 v12, v12, v8, -v6
	v_sub_f32_e32 v7, v8, v7
	v_lshlrev_b32_e32 v8, 16, v5
	v_cvt_pk_bf16_f32 v12, v13, v12
	v_add_u32_e32 v178, 0, v155
	v_add_f32_e32 v10, v10, v8
	ds_write_b32 v178, v12 offset:34816
	v_fma_f32 v12, v11, v10, -v8
	v_sub_f32_e32 v9, v10, v9
	v_add_u32_e32 v10, s95, v138
	v_min_i32_e32 v10, 1, v10
	v_add_u32_e32 v10, 1, v10
	v_cvt_f32_i32_e32 v10, v10
	v_and_b32_e32 v5, 0xffff0000, v5
	v_cndmask_b32_e64 v4, 0, v4, s[26:27]
	v_add_f32_e32 v7, v7, v5
	v_rcp_iflag_f32_e32 v10, v10
	v_fma_f32 v11, v11, v7, -v5
	v_sub_f32_e32 v6, v7, v6
	v_lshlrev_b32_e32 v7, 16, v4
	v_cvt_pk_bf16_f32 v11, v12, v11
	v_add_u32_e32 v179, 0, v156
	v_add_f32_e32 v9, v9, v7
	ds_write_b32 v179, v11 offset:34816
	v_fma_f32 v11, v10, v9, -v7
	v_sub_f32_e32 v8, v9, v8
	v_add_u32_e32 v9, s95, v139
	v_min_i32_e32 v9, 1, v9
	v_add_u32_e32 v9, 1, v9
	v_cvt_f32_i32_e32 v9, v9
	v_and_b32_e32 v4, 0xffff0000, v4
	v_cndmask_b32_e64 v3, 0, v3, s[28:29]
	v_add_f32_e32 v6, v6, v4
	v_rcp_iflag_f32_e32 v9, v9
	v_fma_f32 v10, v10, v6, -v4
	v_sub_f32_e32 v5, v6, v5
	v_lshlrev_b32_e32 v6, 16, v3
	v_cvt_pk_bf16_f32 v10, v11, v10
	v_add_u32_e32 v180, 0, v157
	v_add_f32_e32 v8, v8, v6
	ds_write_b32 v180, v10 offset:34816
	v_fma_f32 v10, v9, v8, -v6
	v_sub_f32_e32 v7, v8, v7
	v_add_u32_e32 v8, s95, v140
	v_min_i32_e32 v8, 1, v8
	v_add_u32_e32 v8, 1, v8
	v_cvt_f32_i32_e32 v8, v8
	v_and_b32_e32 v3, 0xffff0000, v3
	v_cndmask_b32_e64 v2, 0, v2, s[38:39]
	v_add_f32_e32 v5, v5, v3
	v_rcp_iflag_f32_e32 v8, v8
	v_fma_f32 v9, v9, v5, -v3
	v_sub_f32_e32 v4, v5, v4
	v_lshlrev_b32_e32 v5, 16, v2
	v_and_b32_e32 v2, 0xffff0000, v2
	v_add_f32_e32 v7, v7, v5
	v_add_f32_e32 v4, v4, v2
	v_fma_f32 v5, v8, v7, -v5
	v_fma_f32 v2, v8, v4, -v2
	v_cvt_pk_bf16_f32 v2, v5, v2
	v_add_u32_e32 v5, s95, v141
	v_min_i32_e32 v5, 1, v5
	v_add_u32_e32 v5, 1, v5
	v_cvt_f32_i32_e32 v5, v5
	v_add_u32_e32 v181, 0, v158
	v_add_u32_e32 v182, 0, v159
	s_or_b32 s0, s94, 0x80
	v_rcp_iflag_f32_e32 v5, v5
	v_cvt_pk_bf16_f32 v9, v10, v9
	ds_write_b32 v181, v9 offset:34816
	ds_write_b32 v182, v2 offset:34816
	v_sub_f32_e32 v2, v7, v6
	v_sub_f32_e32 v3, v4, v3
	v_lshlrev_b32_e32 v4, 16, v0
	v_and_b32_e32 v0, 0xffff0000, v0
	s_xor_b32 s1, s95, 0xffffff7f
	s_mul_i32 s2, s0, 0x1e00
	v_add_f32_e32 v2, v2, v4
	v_add_f32_e32 v3, v3, v0
	s_mul_hi_i32 s3, s0, 0x1e00
	s_add_u32 s2, s91, s2
	v_fma_f32 v2, v5, v2, -v4
	v_fma_f32 v0, v5, v3, -v0
	s_addc_u32 s3, s92, s3
	v_mov_b32_e32 v105, v1
	v_cvt_pk_bf16_f32 v0, v2, v0
	v_add_u32_e32 v183, 0, v160
	v_cmp_lt_i32_e32 vcc, s1, v141
	v_lshl_add_u64 v[2:3], s[2:3], 0, v[104:105]
	s_mov_b64 s[2:3], 0x1420
	ds_write_b32 v183, v0 offset:34816
	v_lshl_add_u64 v[2:3], v[2:3], 0, s[2:3]
	v_cndmask_b32_e32 v0, 0, v141, vcc
	s_movk_i32 s6, 0x1e00
	v_mad_i64_i32 v[4:5], s[2:3], v0, s6, v[2:3]
	global_load_dword v0, v[4:5], off
	v_add_u32_e32 v186, v144, v143
	v_add_u32_e32 v185, v144, v161
	v_mov_b32_e32 v103, v1
	v_add_u32_e32 v184, v144, v163
	v_lshlrev_b32_e32 v116, 1, v98
	v_mov_b32_e32 v117, v1
	s_mov_b64 s[36:37], 0
	s_waitcnt vmcnt(0)
	v_cndmask_b32_e32 v105, 0, v0, vcc
	v_cmp_lt_i32_e32 vcc, s1, v126
	v_mov_b32_e32 v212, 0
	s_nop 0
	v_cndmask_b32_e32 v0, 0, v126, vcc
	v_mad_i64_i32 v[4:5], s[2:3], v0, s6, v[2:3]
	s_and_saveexec_b64 s[98:99], vcc
	global_load_dword v212, v[4:5], off
	s_mov_b64 exec, s[98:99]
	v_cmp_lt_i32_e32 vcc, s1, v83
	v_mov_b32_e32 v213, 0
	s_nop 0
	v_cndmask_b32_e32 v0, 0, v83, vcc
	v_mad_i64_i32 v[4:5], s[2:3], v0, s6, v[2:3]
	s_and_saveexec_b64 s[98:99], vcc
	global_load_dword v213, v[4:5], off
	s_mov_b64 exec, s[98:99]
	v_cmp_gt_i32_e32 vcc, s1, v83
	s_nop 1
	v_cndmask_b32_e64 v0, v127, 0, vcc
	v_mad_i64_i32 v[4:5], s[2:3], v0, s6, v[2:3]
	global_load_dword v0, v[4:5], off
	s_waitcnt vmcnt(0)
	v_cndmask_b32_e64 v191, v0, 0, vcc
	v_cmp_lt_i32_e32 vcc, s1, v128
	v_mov_b32_e32 v211, 0
	s_nop 0
	v_cndmask_b32_e32 v0, 0, v128, vcc
	v_mad_i64_i32 v[4:5], s[2:3], v0, s6, v[2:3]
	s_and_saveexec_b64 s[98:99], vcc
	global_load_dword v211, v[4:5], off
	s_mov_b64 exec, s[98:99]
	v_cmp_lt_i32_e32 vcc, s1, v129
	v_mov_b32_e32 v210, 0
	s_nop 0
	v_cndmask_b32_e32 v0, 0, v129, vcc
	v_mad_i64_i32 v[4:5], s[2:3], v0, s6, v[2:3]
	s_and_saveexec_b64 s[98:99], vcc
	global_load_dword v210, v[4:5], off
	s_mov_b64 exec, s[98:99]
	v_cmp_lt_i32_e32 vcc, s1, v130
	v_mov_b32_e32 v209, 0
	s_nop 0
	v_cndmask_b32_e32 v0, 0, v130, vcc
	v_mad_i64_i32 v[4:5], s[2:3], v0, s6, v[2:3]
	s_and_saveexec_b64 s[98:99], vcc
	global_load_dword v209, v[4:5], off
	s_mov_b64 exec, s[98:99]
	v_cmp_lt_i32_e32 vcc, s1, v131
	v_mov_b32_e32 v208, 0
	s_nop 0
	v_cndmask_b32_e32 v0, 0, v131, vcc
	v_mad_i64_i32 v[4:5], s[2:3], v0, s6, v[2:3]
	s_and_saveexec_b64 s[98:99], vcc
	global_load_dword v208, v[4:5], off
	s_mov_b64 exec, s[98:99]
	v_cmp_lt_i32_e32 vcc, s1, v132
	v_mov_b32_e32 v207, 0
	s_nop 0
	v_cndmask_b32_e32 v0, 0, v132, vcc
	v_mad_i64_i32 v[4:5], s[2:3], v0, s6, v[2:3]
	s_and_saveexec_b64 s[98:99], vcc
	global_load_dword v207, v[4:5], off
	s_mov_b64 exec, s[98:99]
	v_cmp_lt_i32_e32 vcc, s1, v133
	v_mov_b32_e32 v206, 0
	s_nop 0
	v_cndmask_b32_e32 v0, 0, v133, vcc
	v_mad_i64_i32 v[4:5], s[2:3], v0, s6, v[2:3]
	s_and_saveexec_b64 s[98:99], vcc
	global_load_dword v206, v[4:5], off
	s_mov_b64 exec, s[98:99]
	v_cmp_lt_i32_e32 vcc, s1, v134
	v_mov_b32_e32 v205, 0
	s_nop 0
	v_cndmask_b32_e32 v0, 0, v134, vcc
	v_mad_i64_i32 v[4:5], s[2:3], v0, s6, v[2:3]
	s_and_saveexec_b64 s[98:99], vcc
	global_load_dword v205, v[4:5], off
	s_mov_b64 exec, s[98:99]
	v_cmp_lt_i32_e32 vcc, s1, v135
	v_mov_b32_e32 v204, 0
	s_nop 0
	v_cndmask_b32_e32 v0, 0, v135, vcc
	v_mad_i64_i32 v[4:5], s[2:3], v0, s6, v[2:3]
	s_and_saveexec_b64 s[98:99], vcc
	global_load_dword v204, v[4:5], off
	s_mov_b64 exec, s[98:99]
	v_cmp_lt_i32_e32 vcc, s1, v136
	v_mov_b32_e32 v192, 0
	s_nop 0
	v_cndmask_b32_e32 v0, 0, v136, vcc
	v_mad_i64_i32 v[4:5], s[2:3], v0, s6, v[2:3]
	s_and_saveexec_b64 s[98:99], vcc
	global_load_dword v192, v[4:5], off
	s_mov_b64 exec, s[98:99]
	v_cmp_lt_i32_e32 vcc, s1, v137
	v_mov_b32_e32 v190, 0
	s_nop 0
	v_cndmask_b32_e32 v0, 0, v137, vcc
	v_mad_i64_i32 v[4:5], s[2:3], v0, s6, v[2:3]
	s_and_saveexec_b64 s[98:99], vcc
	global_load_dword v190, v[4:5], off
	s_mov_b64 exec, s[98:99]
	v_cmp_lt_i32_e32 vcc, s1, v138
	v_mov_b32_e32 v189, 0
	s_nop 0
	v_cndmask_b32_e32 v0, 0, v138, vcc
	v_mad_i64_i32 v[4:5], s[2:3], v0, s6, v[2:3]
	s_and_saveexec_b64 s[98:99], vcc
	global_load_dword v189, v[4:5], off
	s_mov_b64 exec, s[98:99]
	v_cmp_lt_i32_e32 vcc, s1, v139
	v_mov_b32_e32 v188, 0
	s_nop 0
	v_cndmask_b32_e32 v0, 0, v139, vcc
	v_mad_i64_i32 v[4:5], s[2:3], v0, s6, v[2:3]
	s_and_saveexec_b64 s[98:99], vcc
	global_load_dword v188, v[4:5], off
	s_mov_b64 exec, s[98:99]
	v_cmp_lt_i32_e32 vcc, s1, v140
	s_and_b32 s1, s0, 0xf80
	s_nop 0
	v_cndmask_b32_e32 v0, 0, v140, vcc
	v_mad_i64_i32 v[2:3], s[2:3], v0, s6, v[2:3]
	global_load_dword v0, v[2:3], off
	v_add_u32_e32 v2, s94, v142
	v_ashrrev_i32_e32 v3, 31, v2
	v_lshlrev_b64 v[2:3], 12, v[2:3]
	s_waitcnt lgkmcnt(0)
	s_barrier
	v_lshl_add_u64 v[2:3], s[70:71], 0, v[2:3]
	s_mov_b64 s[2:3], 0x26000800
	ds_read_b128 v[74:77], v186 offset:34816
	ds_read_b128 v[78:81], v186 offset:34848
	ds_read_b128 v[70:73], v186 offset:34880
	ds_read_b128 v[66:69], v186 offset:34912
	ds_read_b128 v[62:65], v186 offset:34944
	ds_read_b128 v[58:61], v186 offset:34976
	ds_read_b128 v[54:57], v186 offset:35008
	ds_read_b128 v[50:53], v186 offset:35040
	v_lshl_add_u64 v[106:107], v[2:3], 0, s[2:3]
	ds_read_b128 v[2:5], v185
	ds_read_b128 v[108:111], v185 offset:32
	ds_read_b128 v[228:231], v185 offset:64
	ds_read_b128 v[242:245], v185 offset:96
	s_waitcnt lgkmcnt(3)
	v_mfma_f32_32x32x16_bf16 v[2:17], v[2:5], v[74:77], 0
	s_waitcnt vmcnt(0)
	v_cndmask_b32_e32 v187, 0, v0, vcc
	s_waitcnt lgkmcnt(2)
	v_mfma_f32_32x32x16_bf16 v[2:17], v[108:111], v[78:81], v[2:17]
	ds_read_b128 v[108:111], v185 offset:128
	s_waitcnt lgkmcnt(2)
	v_mfma_f32_32x32x16_bf16 v[2:17], v[228:231], v[70:73], v[2:17]
	ds_read_b128 v[228:231], v185 offset:160
	s_waitcnt lgkmcnt(2)
	v_mfma_f32_32x32x16_bf16 v[2:17], v[242:245], v[66:69], v[2:17]
	ds_read_b128 v[242:245], v185 offset:192
	s_waitcnt lgkmcnt(2)
	v_mfma_f32_32x32x16_bf16 v[2:17], v[108:111], v[62:65], v[2:17]
	ds_read_b128 v[108:111], v185 offset:224
	s_waitcnt lgkmcnt(2)
	v_mfma_f32_32x32x16_bf16 v[2:17], v[228:231], v[58:61], v[2:17]
	s_waitcnt lgkmcnt(1)
	v_mfma_f32_32x32x16_bf16 v[2:17], v[242:245], v[54:57], v[2:17]
	s_waitcnt lgkmcnt(0)
	v_mfma_f32_32x32x16_bf16 v[2:17], v[108:111], v[50:53], v[2:17]
	v_lshlrev_b32_e32 v108, 1, v90
	v_mov_b32_e32 v109, v1
	v_lshlrev_b32_e32 v110, 1, v92
	v_mov_b32_e32 v111, v1
	s_nop 7
	v_mul_f32_e32 v0, v46, v2
	v_mul_f32_e32 v2, v47, v3
	v_cvt_pk_bf16_f32 v2, v0, v2
	v_mul_f32_e32 v0, v48, v4
	v_mul_f32_e32 v3, v49, v5
	v_cvt_pk_bf16_f32 v3, v0, v3
	v_lshlrev_b32_e32 v0, 1, v88
	v_lshl_add_u64 v[4:5], v[106:107], 0, v[0:1]
	global_store_dwordx2 v[4:5], v[2:3], off
	v_mul_f32_e32 v2, v42, v6
	v_mul_f32_e32 v3, v43, v7
	v_cvt_pk_bf16_f32 v2, v2, v3
	v_mul_f32_e32 v3, v44, v8
	v_mul_f32_e32 v4, v45, v9
	v_cvt_pk_bf16_f32 v3, v3, v4
	v_lshl_add_u64 v[4:5], v[106:107], 0, v[108:109]
	global_store_dwordx2 v[4:5], v[2:3], off
	v_mul_f32_e32 v2, v38, v10
	v_mul_f32_e32 v3, v39, v11
	v_cvt_pk_bf16_f32 v2, v2, v3
	v_mul_f32_e32 v3, v40, v12
	v_mul_f32_e32 v4, v41, v13
	v_cvt_pk_bf16_f32 v3, v3, v4
	v_lshl_add_u64 v[4:5], v[106:107], 0, v[110:111]
	global_store_dwordx2 v[4:5], v[2:3], off
	v_mul_f32_e32 v2, v34, v14
	v_mul_f32_e32 v3, v35, v15
	v_cvt_pk_bf16_f32 v2, v2, v3
	v_mul_f32_e32 v3, v36, v16
	v_mul_f32_e32 v4, v37, v17
	v_cvt_pk_bf16_f32 v3, v3, v4
	v_lshl_add_u64 v[4:5], v[106:107], 0, v[102:103]
	global_store_dwordx2 v[4:5], v[2:3], off
	ds_read_b128 v[228:231], v184
	ds_read_b128 v[242:245], v184 offset:32
	ds_read_b128 v[246:249], v184 offset:64
	s_waitcnt lgkmcnt(2)
	v_mfma_f32_32x32x16_bf16 v[2:17], v[228:231], v[74:77], 0
	ds_read_b128 v[228:231], v184 offset:96
	s_waitcnt lgkmcnt(2)
	v_mfma_f32_32x32x16_bf16 v[2:17], v[242:245], v[78:81], v[2:17]
	ds_read_b128 v[242:245], v184 offset:128
	v_lshlrev_b32_e32 v112, 1, v94
	v_mov_b32_e32 v113, v1
	v_lshlrev_b32_e32 v114, 1, v96
	v_mov_b32_e32 v115, v1
	s_waitcnt lgkmcnt(2)
	v_mfma_f32_32x32x16_bf16 v[2:17], v[246:249], v[70:73], v[2:17]
	ds_read_b128 v[246:249], v184 offset:160
	s_waitcnt lgkmcnt(2)
	v_mfma_f32_32x32x16_bf16 v[2:17], v[228:231], v[66:69], v[2:17]
	ds_read_b128 v[228:231], v184 offset:192
	s_waitcnt lgkmcnt(2)
	v_mfma_f32_32x32x16_bf16 v[2:17], v[242:245], v[62:65], v[2:17]
	ds_read_b128 v[242:245], v184 offset:224
	s_waitcnt lgkmcnt(2)
	v_mfma_f32_32x32x16_bf16 v[2:17], v[246:249], v[58:61], v[2:17]
	s_waitcnt lgkmcnt(1)
	v_mfma_f32_32x32x16_bf16 v[2:17], v[228:231], v[54:57], v[2:17]
	s_waitcnt lgkmcnt(0)
	v_mfma_f32_32x32x16_bf16 v[2:17], v[242:245], v[50:53], v[2:17]
	s_nop 11
	v_mul_f32_e32 v2, v30, v2
	v_mul_f32_e32 v3, v31, v3
	v_cvt_pk_bf16_f32 v2, v2, v3
	v_mul_f32_e32 v3, v32, v4
	v_mul_f32_e32 v4, v33, v5
	v_cvt_pk_bf16_f32 v3, v3, v4
	v_lshl_add_u64 v[4:5], v[106:107], 0, v[112:113]
	global_store_dwordx2 v[4:5], v[2:3], off
	v_mul_f32_e32 v2, v26, v6
	v_mul_f32_e32 v3, v27, v7
	v_cvt_pk_bf16_f32 v2, v2, v3
	v_mul_f32_e32 v3, v28, v8
	v_mul_f32_e32 v4, v29, v9
	v_cvt_pk_bf16_f32 v3, v3, v4
	v_lshl_add_u64 v[4:5], v[106:107], 0, v[114:115]
	v_add_u32_e32 v8, s1, v83
	global_store_dwordx2 v[4:5], v[2:3], off
	v_mul_f32_e32 v2, v22, v10
	v_mul_f32_e32 v3, v23, v11
	v_min_i32_e32 v8, 1, v8
	v_cvt_pk_bf16_f32 v2, v2, v3
	v_mul_f32_e32 v3, v24, v12
	v_mul_f32_e32 v4, v25, v13
	v_add_u32_e32 v8, 1, v8
	v_cvt_pk_bf16_f32 v3, v3, v4
	v_lshl_add_u64 v[4:5], v[106:107], 0, v[116:117]
	v_cvt_f32_i32_e32 v8, v8
	global_store_dwordx2 v[4:5], v[2:3], off
	v_mul_f32_e32 v2, v18, v14
	v_mul_f32_e32 v3, v19, v15
	v_cvt_pk_bf16_f32 v2, v2, v3
	v_mul_f32_e32 v3, v20, v16
	v_mul_f32_e32 v4, v21, v17
	v_cvt_pk_bf16_f32 v3, v3, v4
	v_lshlrev_b32_e32 v4, 1, v100
	v_mov_b32_e32 v5, v1
	v_lshl_add_u64 v[4:5], v[106:107], 0, v[4:5]
	v_rcp_iflag_f32_e32 v8, v8
	global_store_dwordx2 v[4:5], v[2:3], off
	v_lshlrev_b32_e32 v2, 16, v212
	v_and_b32_e32 v3, 0xffff0000, v212
	v_add_f32_e32 v4, 0, v2
	v_add_f32_e32 v5, 0, v3
	v_lshlrev_b32_e32 v6, 16, v213
	v_and_b32_e32 v7, 0xffff0000, v213
	v_add_f32_e32 v4, v4, v6
	v_add_f32_e32 v5, v5, v7
	v_fma_f32 v9, v8, v4, -v6
	v_fma_f32 v8, v8, v5, -v7
	v_cvt_pk_bf16_f32 v8, v9, v8
	s_waitcnt lgkmcnt(0)
	s_barrier
	ds_write_b32 v168, v8 offset:34816
	v_add_u32_e32 v8, s1, v127
	v_min_i32_e32 v8, 1, v8
	v_add_u32_e32 v8, 1, v8
	v_cvt_f32_i32_e32 v8, v8
	v_sub_f32_e32 v2, v4, v2
	v_sub_f32_e32 v3, v5, v3
	v_lshlrev_b32_e32 v4, 16, v191
	v_rcp_iflag_f32_e32 v8, v8
	v_and_b32_e32 v5, 0xffff0000, v191
	v_add_f32_e32 v2, v2, v4
	v_add_f32_e32 v3, v3, v5
	v_fma_f32 v9, v8, v2, -v4
	v_fma_f32 v8, v8, v3, -v5
	v_cvt_pk_bf16_f32 v8, v9, v8
	ds_write_b32 v169, v8 offset:34816
	v_add_u32_e32 v8, s1, v128
	v_min_i32_e32 v8, 1, v8
	v_add_u32_e32 v8, 1, v8
	v_cvt_f32_i32_e32 v8, v8
	v_sub_f32_e32 v2, v2, v6
	v_sub_f32_e32 v3, v3, v7
	v_lshlrev_b32_e32 v6, 16, v211
	v_rcp_iflag_f32_e32 v8, v8
	v_and_b32_e32 v7, 0xffff0000, v211
	v_add_f32_e32 v2, v2, v6
	v_add_f32_e32 v3, v3, v7
	v_fma_f32 v9, v8, v2, -v6
	v_fma_f32 v8, v8, v3, -v7
	v_cvt_pk_bf16_f32 v8, v9, v8
	ds_write_b32 v170, v8 offset:34816
	v_add_u32_e32 v8, s1, v129
	v_min_i32_e32 v8, 1, v8
	v_add_u32_e32 v8, 1, v8
	v_cvt_f32_i32_e32 v8, v8
	v_sub_f32_e32 v2, v2, v4
	v_sub_f32_e32 v3, v3, v5
	v_lshlrev_b32_e32 v4, 16, v210
	v_rcp_iflag_f32_e32 v8, v8
	v_and_b32_e32 v5, 0xffff0000, v210
	v_add_f32_e32 v2, v2, v4
	v_add_f32_e32 v3, v3, v5
	v_fma_f32 v9, v8, v2, -v4
	v_fma_f32 v8, v8, v3, -v5
	v_cvt_pk_bf16_f32 v8, v9, v8
	ds_write_b32 v171, v8 offset:34816
	v_add_u32_e32 v8, s1, v130
	v_min_i32_e32 v8, 1, v8
	v_add_u32_e32 v8, 1, v8
	v_cvt_f32_i32_e32 v8, v8
	v_sub_f32_e32 v2, v2, v6
	v_sub_f32_e32 v3, v3, v7
	v_lshlrev_b32_e32 v6, 16, v209
	v_rcp_iflag_f32_e32 v8, v8
	v_and_b32_e32 v7, 0xffff0000, v209
	v_add_f32_e32 v2, v2, v6
	v_add_f32_e32 v3, v3, v7
	v_fma_f32 v9, v8, v2, -v6
	v_fma_f32 v8, v8, v3, -v7
	v_cvt_pk_bf16_f32 v8, v9, v8
	ds_write_b32 v172, v8 offset:34816
	v_add_u32_e32 v8, s1, v131
	v_min_i32_e32 v8, 1, v8
	v_add_u32_e32 v8, 1, v8
	v_cvt_f32_i32_e32 v8, v8
	v_sub_f32_e32 v2, v2, v4
	v_sub_f32_e32 v3, v3, v5
	v_lshlrev_b32_e32 v4, 16, v208
	v_rcp_iflag_f32_e32 v8, v8
	v_and_b32_e32 v5, 0xffff0000, v208
	v_add_f32_e32 v2, v2, v4
	v_add_f32_e32 v3, v3, v5
	v_fma_f32 v9, v8, v2, -v4
	v_fma_f32 v8, v8, v3, -v5
	v_cvt_pk_bf16_f32 v8, v9, v8
	ds_write_b32 v173, v8 offset:34816
	v_add_u32_e32 v8, s1, v132
	v_min_i32_e32 v8, 1, v8
	v_add_u32_e32 v8, 1, v8
	v_cvt_f32_i32_e32 v8, v8
	v_sub_f32_e32 v2, v2, v6
	v_sub_f32_e32 v3, v3, v7
	v_lshlrev_b32_e32 v6, 16, v207
	v_rcp_iflag_f32_e32 v8, v8
	v_and_b32_e32 v7, 0xffff0000, v207
	v_add_f32_e32 v2, v2, v6
	v_add_f32_e32 v3, v3, v7
	v_fma_f32 v9, v8, v2, -v6
	v_fma_f32 v8, v8, v3, -v7
	v_cvt_pk_bf16_f32 v8, v9, v8
	ds_write_b32 v174, v8 offset:34816
	v_add_u32_e32 v8, s1, v133
	v_min_i32_e32 v8, 1, v8
	v_add_u32_e32 v8, 1, v8
	v_cvt_f32_i32_e32 v8, v8
	v_sub_f32_e32 v2, v2, v4
	v_sub_f32_e32 v3, v3, v5
	v_lshlrev_b32_e32 v4, 16, v206
	v_rcp_iflag_f32_e32 v8, v8
	v_and_b32_e32 v5, 0xffff0000, v206
	v_add_f32_e32 v2, v2, v4
	v_add_f32_e32 v3, v3, v5
	v_fma_f32 v9, v8, v2, -v4
	v_fma_f32 v8, v8, v3, -v5
	v_cvt_pk_bf16_f32 v8, v9, v8
	ds_write_b32 v175, v8 offset:34816
	v_add_u32_e32 v8, s1, v134
	v_min_i32_e32 v8, 1, v8
	v_add_u32_e32 v8, 1, v8
	v_cvt_f32_i32_e32 v8, v8
	v_sub_f32_e32 v2, v2, v6
	v_sub_f32_e32 v3, v3, v7
	v_lshlrev_b32_e32 v6, 16, v205
	v_rcp_iflag_f32_e32 v8, v8
	v_and_b32_e32 v7, 0xffff0000, v205
	v_add_f32_e32 v2, v2, v6
	v_add_f32_e32 v3, v3, v7
	v_fma_f32 v9, v8, v2, -v6
	v_fma_f32 v8, v8, v3, -v7
	v_cvt_pk_bf16_f32 v8, v9, v8
	ds_write_b32 v176, v8 offset:34816
	v_add_u32_e32 v8, s1, v135
	v_min_i32_e32 v8, 1, v8
	v_add_u32_e32 v8, 1, v8
	v_cvt_f32_i32_e32 v8, v8
	v_sub_f32_e32 v2, v2, v4
	v_sub_f32_e32 v3, v3, v5
	v_lshlrev_b32_e32 v4, 16, v204
	v_rcp_iflag_f32_e32 v8, v8
	v_and_b32_e32 v5, 0xffff0000, v204
	v_add_f32_e32 v2, v2, v4
	v_add_f32_e32 v3, v3, v5
	v_fma_f32 v9, v8, v2, -v4
	v_fma_f32 v8, v8, v3, -v5
	v_cvt_pk_bf16_f32 v8, v9, v8
	ds_write_b32 v177, v8 offset:34816
	v_add_u32_e32 v8, s1, v136
	v_min_i32_e32 v8, 1, v8
	v_add_u32_e32 v8, 1, v8
	v_cvt_f32_i32_e32 v8, v8
	v_sub_f32_e32 v2, v2, v6
	v_sub_f32_e32 v3, v3, v7
	v_lshlrev_b32_e32 v6, 16, v192
	v_rcp_iflag_f32_e32 v8, v8
	v_and_b32_e32 v7, 0xffff0000, v192
	v_add_f32_e32 v2, v2, v6
	v_add_f32_e32 v3, v3, v7
	v_fma_f32 v9, v8, v2, -v6
	v_fma_f32 v8, v8, v3, -v7
	v_cvt_pk_bf16_f32 v8, v9, v8
	ds_write_b32 v178, v8 offset:34816
	v_add_u32_e32 v8, s1, v137
	v_min_i32_e32 v8, 1, v8
	v_add_u32_e32 v8, 1, v8
	v_cvt_f32_i32_e32 v8, v8
	v_sub_f32_e32 v2, v2, v4
	v_sub_f32_e32 v3, v3, v5
	v_lshlrev_b32_e32 v4, 16, v190
	v_rcp_iflag_f32_e32 v8, v8
	v_and_b32_e32 v5, 0xffff0000, v190
	v_add_f32_e32 v2, v2, v4
	v_add_f32_e32 v3, v3, v5
	v_fma_f32 v9, v8, v2, -v4
	v_fma_f32 v8, v8, v3, -v5
	v_cvt_pk_bf16_f32 v8, v9, v8
	ds_write_b32 v179, v8 offset:34816
	v_add_u32_e32 v8, s1, v138
	v_min_i32_e32 v8, 1, v8
	v_add_u32_e32 v8, 1, v8
	v_cvt_f32_i32_e32 v8, v8
	v_sub_f32_e32 v2, v2, v6
	v_sub_f32_e32 v3, v3, v7
	v_lshlrev_b32_e32 v6, 16, v189
	v_rcp_iflag_f32_e32 v8, v8
	v_and_b32_e32 v7, 0xffff0000, v189
	v_add_f32_e32 v2, v2, v6
	v_add_f32_e32 v3, v3, v7
	v_fma_f32 v9, v8, v2, -v6
	v_fma_f32 v8, v8, v3, -v7
	v_cvt_pk_bf16_f32 v8, v9, v8
	ds_write_b32 v180, v8 offset:34816
	v_add_u32_e32 v8, s1, v139
	v_min_i32_e32 v8, 1, v8
	v_add_u32_e32 v8, 1, v8
	v_cvt_f32_i32_e32 v8, v8
	v_sub_f32_e32 v2, v2, v4
	v_sub_f32_e32 v3, v3, v5
	v_lshlrev_b32_e32 v4, 16, v188
	v_rcp_iflag_f32_e32 v8, v8
	v_and_b32_e32 v5, 0xffff0000, v188
	v_add_f32_e32 v2, v2, v4
	v_add_f32_e32 v3, v3, v5
	v_fma_f32 v9, v8, v2, -v4
	v_fma_f32 v8, v8, v3, -v5
	v_cvt_pk_bf16_f32 v8, v9, v8
	ds_write_b32 v181, v8 offset:34816
	v_add_u32_e32 v8, s1, v140
	v_min_i32_e32 v8, 1, v8
	v_add_u32_e32 v8, 1, v8
	v_cvt_f32_i32_e32 v8, v8
	v_sub_f32_e32 v2, v2, v6
	v_lshlrev_b32_e32 v6, 16, v187
	v_sub_f32_e32 v3, v3, v7
	v_rcp_iflag_f32_e32 v8, v8
	v_and_b32_e32 v7, 0xffff0000, v187
	v_add_f32_e32 v2, v2, v6
	v_add_f32_e32 v3, v3, v7
	v_fma_f32 v6, v8, v2, -v6
	v_fma_f32 v7, v8, v3, -v7
	v_cvt_pk_bf16_f32 v6, v6, v7
	ds_write_b32 v182, v6 offset:34816
	v_add_u32_e32 v6, s1, v141
	v_min_i32_e32 v6, 1, v6
	v_add_u32_e32 v6, 1, v6
	v_cvt_f32_i32_e32 v6, v6
	v_sub_f32_e32 v2, v2, v4
	v_lshlrev_b32_e32 v4, 16, v105
	v_sub_f32_e32 v3, v3, v5
	v_rcp_iflag_f32_e32 v6, v6
	v_and_b32_e32 v5, 0xffff0000, v105
	v_add_f32_e32 v2, v2, v4
	v_add_f32_e32 v3, v3, v5
	v_fma_f32 v2, v6, v2, -v4
	v_fma_f32 v3, v6, v3, -v5
	v_cvt_pk_bf16_f32 v2, v2, v3
	ds_write_b32 v183, v2 offset:34816
	v_add_u32_e32 v2, s0, v142
	v_ashrrev_i32_e32 v3, 31, v2
	v_lshlrev_b64 v[2:3], 12, v[2:3]
	s_waitcnt lgkmcnt(0)
	s_barrier
	v_lshl_add_u64 v[2:3], s[70:71], 0, v[2:3]
	ds_read_b128 v[74:77], v186 offset:34816
	ds_read_b128 v[78:81], v186 offset:34848
	ds_read_b128 v[70:73], v186 offset:34880
	ds_read_b128 v[66:69], v186 offset:34912
	ds_read_b128 v[62:65], v186 offset:34944
	ds_read_b128 v[58:61], v186 offset:34976
	ds_read_b128 v[54:57], v186 offset:35008
	ds_read_b128 v[50:53], v186 offset:35040
	v_lshl_add_u64 v[106:107], v[2:3], 0, s[2:3]
	ds_read_b128 v[2:5], v185
	ds_read_b128 v[168:171], v185 offset:32
	ds_read_b128 v[228:231], v185 offset:64
	ds_read_b128 v[242:245], v185 offset:96
	s_waitcnt lgkmcnt(3)
	v_mfma_f32_32x32x16_bf16 v[2:17], v[2:5], v[74:77], 0
	s_waitcnt lgkmcnt(2)
	v_mfma_f32_32x32x16_bf16 v[2:17], v[168:171], v[78:81], v[2:17]
	ds_read_b128 v[168:171], v185 offset:128
	s_waitcnt lgkmcnt(2)
	v_mfma_f32_32x32x16_bf16 v[2:17], v[228:231], v[70:73], v[2:17]
	ds_read_b128 v[228:231], v185 offset:160
	s_waitcnt lgkmcnt(2)
	v_mfma_f32_32x32x16_bf16 v[2:17], v[242:245], v[66:69], v[2:17]
	ds_read_b128 v[242:245], v185 offset:192
	s_waitcnt lgkmcnt(2)
	v_mfma_f32_32x32x16_bf16 v[2:17], v[168:171], v[62:65], v[2:17]
	ds_read_b128 v[168:171], v185 offset:224
	s_waitcnt lgkmcnt(2)
	v_mfma_f32_32x32x16_bf16 v[2:17], v[228:231], v[58:61], v[2:17]
	s_waitcnt lgkmcnt(1)
	v_mfma_f32_32x32x16_bf16 v[2:17], v[242:245], v[54:57], v[2:17]
	s_waitcnt lgkmcnt(0)
	v_mfma_f32_32x32x16_bf16 v[2:17], v[168:171], v[50:53], v[2:17]
	s_nop 11
	v_mul_f32_e32 v2, v46, v2
	v_mul_f32_e32 v3, v47, v3
	v_cvt_pk_bf16_f32 v2, v2, v3
	v_mul_f32_e32 v3, v48, v4
	v_mul_f32_e32 v4, v49, v5
	v_cvt_pk_bf16_f32 v3, v3, v4
	v_lshl_add_u64 v[4:5], v[106:107], 0, v[0:1]
	global_store_dwordx2 v[4:5], v[2:3], off
	v_mul_f32_e32 v0, v42, v6
	v_mul_f32_e32 v2, v43, v7
	v_mul_f32_e32 v3, v45, v9
	v_cvt_pk_bf16_f32 v2, v0, v2
	v_mul_f32_e32 v0, v44, v8
	v_cvt_pk_bf16_f32 v3, v0, v3
	v_lshl_add_u64 v[4:5], v[106:107], 0, v[108:109]
	global_store_dwordx2 v[4:5], v[2:3], off
	v_mul_f32_e32 v0, v38, v10
	v_mul_f32_e32 v2, v39, v11
	v_mul_f32_e32 v3, v41, v13
	v_cvt_pk_bf16_f32 v2, v0, v2
	v_mul_f32_e32 v0, v40, v12
	v_cvt_pk_bf16_f32 v3, v0, v3
	v_lshl_add_u64 v[4:5], v[106:107], 0, v[110:111]
	global_store_dwordx2 v[4:5], v[2:3], off
	v_mul_f32_e32 v0, v34, v14
	v_mul_f32_e32 v2, v35, v15
	v_mul_f32_e32 v3, v37, v17
	v_lshl_add_u64 v[4:5], v[106:107], 0, v[102:103]
	v_cvt_pk_bf16_f32 v2, v0, v2
	v_mul_f32_e32 v0, v36, v16
	v_cvt_pk_bf16_f32 v3, v0, v3
	global_store_dwordx2 v[4:5], v[2:3], off
	ds_read_b128 v[2:5], v184
	ds_read_b128 v[34:37], v184 offset:32
	ds_read_b128 v[228:231], v184 offset:64
	ds_read_b128 v[242:245], v184 offset:96
	s_waitcnt lgkmcnt(3)
	v_mfma_f32_32x32x16_bf16 v[2:17], v[2:5], v[74:77], 0
	s_waitcnt lgkmcnt(2)
	v_mfma_f32_32x32x16_bf16 v[2:17], v[34:37], v[78:81], v[2:17]
	ds_read_b128 v[34:37], v184 offset:128
	s_waitcnt lgkmcnt(2)
	v_mfma_f32_32x32x16_bf16 v[2:17], v[228:231], v[70:73], v[2:17]
	ds_read_b128 v[228:231], v184 offset:160
	s_waitcnt lgkmcnt(2)
	v_mfma_f32_32x32x16_bf16 v[2:17], v[242:245], v[66:69], v[2:17]
	ds_read_b128 v[242:245], v184 offset:192
	s_waitcnt lgkmcnt(2)
	v_mfma_f32_32x32x16_bf16 v[2:17], v[34:37], v[62:65], v[2:17]
	ds_read_b128 v[34:37], v184 offset:224
	s_waitcnt lgkmcnt(2)
	v_mfma_f32_32x32x16_bf16 v[2:17], v[228:231], v[58:61], v[2:17]
	s_waitcnt lgkmcnt(1)
	v_mfma_f32_32x32x16_bf16 v[2:17], v[242:245], v[54:57], v[2:17]
	s_waitcnt lgkmcnt(0)
	v_mfma_f32_32x32x16_bf16 v[2:17], v[34:37], v[50:53], v[2:17]
	s_nop 11
	v_mul_f32_e32 v0, v30, v2
	v_mul_f32_e32 v2, v31, v3
	v_mul_f32_e32 v3, v33, v5
	v_cvt_pk_bf16_f32 v2, v0, v2
	v_mul_f32_e32 v0, v32, v4
	v_cvt_pk_bf16_f32 v3, v0, v3
	v_lshl_add_u64 v[4:5], v[106:107], 0, v[112:113]
	global_store_dwordx2 v[4:5], v[2:3], off
	v_mul_f32_e32 v0, v26, v6
	v_mul_f32_e32 v2, v27, v7
	v_mul_f32_e32 v3, v29, v9
	v_cvt_pk_bf16_f32 v2, v0, v2
	v_mul_f32_e32 v0, v28, v8
	v_cvt_pk_bf16_f32 v3, v0, v3
	v_lshl_add_u64 v[4:5], v[106:107], 0, v[114:115]
	global_store_dwordx2 v[4:5], v[2:3], off
	v_mul_f32_e32 v0, v22, v10
	v_mul_f32_e32 v2, v23, v11
	v_mul_f32_e32 v3, v25, v13
	v_cvt_pk_bf16_f32 v2, v0, v2
	v_mul_f32_e32 v0, v24, v12
	v_cvt_pk_bf16_f32 v3, v0, v3
	v_lshl_add_u64 v[4:5], v[106:107], 0, v[116:117]
	global_store_dwordx2 v[4:5], v[2:3], off
	v_mul_f32_e32 v0, v18, v14
	v_mul_f32_e32 v2, v19, v15
	v_mul_f32_e32 v3, v21, v17
	v_cvt_pk_bf16_f32 v2, v0, v2
	v_mul_f32_e32 v0, v20, v16
	v_cvt_pk_bf16_f32 v3, v0, v3
